# batch epilogue loads (SwiGLU/Store/Resid/PLE): hoist serialized load-wait ladders into one wait
# speedup vs baseline: 1.0832x; 1.0832x over previous
.LBB0_42:
	v_readlane_b32 s0, v255, 6
	v_readlane_b32 s1, v255, 7
	s_add_i32 s0, s0, 4
	v_lshlrev_b32_e32 v0, 3, v153
	s_mul_hi_i32 s1, s0, 0x22000
	s_mul_i32 s0, s0, 0x22000
	v_readlane_b32 s2, v255, 0
	v_lshl_or_b32 v0, s44, 8, v0
	v_and_b32_e32 v133, 64, v177
	s_add_u32 s8, s2, s0
	v_readlane_b32 s0, v255, 1
	v_or_b32_e32 v130, s48, v0
	v_xor_b32_e32 v0, 16, v177
	v_add_u32_e32 v133, 64, v133
	s_addc_u32 s9, s0, s1
	s_lshl_b32 s0, s20, 8
	v_cmp_lt_i32_e32 vcc, v0, v133
	s_add_i32 s0, s0, s45
	v_or_b32_e32 v132, s0, v156
	v_cndmask_b32_e32 v0, v177, v0, vcc
	v_lshlrev_b32_e32 v138, 2, v0
	v_xor_b32_e32 v0, 32, v177
	v_cmp_lt_i32_e32 vcc, v0, v133
	v_ashrrev_i32_e32 v133, 31, v132
	v_readlane_b32 s0, v255, 12
	v_lshlrev_b64 v[134:135], 11, v[132:133]
	v_readlane_b32 s1, v255, 13
	v_ashrrev_i32_e32 v131, 31, v130
	s_barrier
	v_lshl_add_u64 v[136:137], s[0:1], 0, v[134:135]
	v_lshl_add_u64 v[136:137], v[130:131], 1, v[136:137]
	v_lshlrev_b32_e32 v250, 11, v132
	v_lshl_add_u32 v250, v130, 1, v250
	s_mov_b64 s[98:99], s[0:1]
	global_load_dwordx4 v[154:157], v250, s[98:99]
	global_load_dwordx4 v[192:195], v250, s[98:99] offset:256
	s_add_u32 s98, s98, 0x8000
	s_addc_u32 s99, s99, 0
	global_load_dwordx4 v[196:199], v250, s[98:99]
	global_load_dwordx4 v[200:203], v250, s[98:99] offset:256
	s_add_u32 s98, s98, 0x8000
	s_addc_u32 s99, s99, 0
	global_load_dwordx4 v[204:207], v250, s[98:99]
	global_load_dwordx4 v[208:211], v250, s[98:99] offset:256
	s_add_u32 s98, s98, 0x8000
	s_addc_u32 s99, s99, 0
	global_load_dwordx4 v[212:215], v250, s[98:99]
	global_load_dwordx4 v[218:221], v250, s[98:99] offset:256
	s_add_u32 s98, s98, 0x28000
	s_addc_u32 s99, s99, 0
	global_load_dwordx4 v[222:225], v250, s[98:99]
	global_load_dwordx4 v[226:229], v250, s[98:99] offset:256
	s_add_u32 s98, s98, 0x8000
	s_addc_u32 s99, s99, 0
	global_load_dwordx4 v[230:233], v250, s[98:99]
	global_load_dwordx4 v[234:237], v250, s[98:99] offset:256
	s_add_u32 s98, s98, 0x8000
	s_addc_u32 s99, s99, 0
	global_load_dwordx4 v[238:241], v250, s[98:99]
	global_load_dwordx4 v[242:245], v250, s[98:99] offset:256
	s_add_u32 s98, s98, 0x8000
	s_addc_u32 s99, s99, 0
	global_load_dwordx4 v[246:249], v250, s[98:99]
	global_load_dwordx4 v[180:183], v250, s[98:99] offset:256
	v_cndmask_b32_e32 v0, v177, v0, vcc
	v_lshlrev_b32_e32 v139, 2, v0
	v_mul_f32_e32 v0, 0xbfb8aa3b, v126
	v_exp_f32_e32 v0, v0
	v_cmp_eq_u32_e64 s[6:7], 0, v153
	v_mul_f32_e32 v118, 0xbfb8aa3b, v118
	v_exp_f32_e32 v118, v118
	v_add_f32_e32 v0, 1.0, v0
	v_rcp_f32_e32 v0, v0
	v_mul_f32_e32 v114, 0xbfb8aa3b, v114
	v_add_f32_e32 v118, 1.0, v118
	v_rcp_f32_e32 v118, v118
	v_exp_f32_e32 v114, v114
	s_waitcnt vmcnt(0)
	v_lshlrev_b32_e32 v126, 16, v154
	v_mul_f32_e32 v153, v0, v126
	v_mul_f32_e32 v0, 0xbfb8aa3b, v127
	v_exp_f32_e32 v0, v0
	v_and_b32_e32 v126, 0xffff0000, v154
	v_add_f32_e32 v114, 1.0, v114
	v_rcp_f32_e32 v114, v114
	v_add_f32_e32 v0, 1.0, v0
	v_rcp_f32_e32 v0, v0
	s_nop 0
	v_mul_f32_e32 v141, v0, v126
	v_mul_f32_e32 v0, 0xbfb8aa3b, v128
	v_exp_f32_e32 v0, v0
	v_lshlrev_b32_e32 v126, 16, v155
	v_mul_f32_e32 v144, v141, v141
	v_fmac_f32_e32 v144, v153, v153
	v_add_f32_e32 v0, 1.0, v0
	v_rcp_f32_e32 v0, v0
	s_nop 0
	v_mul_f32_e32 v140, v0, v126
	v_mul_f32_e32 v0, 0xbfb8aa3b, v129
	v_exp_f32_e32 v0, v0
	v_and_b32_e32 v126, 0xffff0000, v155
	v_fmac_f32_e32 v144, v140, v140
	v_add_f32_e32 v0, 1.0, v0
	v_rcp_f32_e32 v0, v0
	s_nop 0
	v_mul_f32_e32 v129, v0, v126
	v_mul_f32_e32 v0, 0xbfb8aa3b, v122
	v_exp_f32_e32 v0, v0
	v_lshlrev_b32_e32 v122, 16, v156
	v_fmac_f32_e32 v144, v129, v129
	v_add_f32_e32 v0, 1.0, v0
	v_rcp_f32_e32 v0, v0
	s_nop 0
	v_mul_f32_e32 v128, v0, v122
	v_mul_f32_e32 v0, 0xbfb8aa3b, v123
	v_exp_f32_e32 v0, v0
	v_and_b32_e32 v122, 0xffff0000, v156
	v_add_f32_e32 v0, 1.0, v0
	v_rcp_f32_e32 v0, v0
	s_nop 0
	v_mul_f32_e32 v127, v0, v122
	v_mul_f32_e32 v0, 0xbfb8aa3b, v124
	v_exp_f32_e32 v0, v0
	v_lshlrev_b32_e32 v122, 16, v157
	v_add_f32_e32 v0, 1.0, v0
	v_rcp_f32_e32 v0, v0
	s_nop 0
	v_mul_f32_e32 v126, v0, v122
	v_mul_f32_e32 v0, 0xbfb8aa3b, v125
	v_exp_f32_e32 v0, v0
	v_and_b32_e32 v122, 0xffff0000, v157
	v_add_f32_e32 v0, 1.0, v0
	v_rcp_f32_e32 v0, v0
	s_nop 0
	v_mul_f32_e32 v0, v0, v122
	v_mul_f32_e32 v122, v127, v127
	v_fmac_f32_e32 v122, v128, v128
	v_fmac_f32_e32 v122, v126, v126
	v_fmac_f32_e32 v122, v0, v0
	v_add_f32_e32 v154, v144, v122
	s_nop 1
	v_mov_b64_e32 v[122:123], v[192:193]
	v_mov_b64_e32 v[124:125], v[194:195]
	v_lshlrev_b32_e32 v136, 16, v122
	v_mul_f32_e32 v136, v118, v136
	v_mul_f32_e32 v118, 0xbfb8aa3b, v119
	v_exp_f32_e32 v118, v118
	v_and_b32_e32 v119, 0xffff0000, v122
	v_add_f32_e32 v118, 1.0, v118
	v_rcp_f32_e32 v118, v118
	s_nop 0
	v_mul_f32_e32 v122, v118, v119
	v_mul_f32_e32 v118, 0xbfb8aa3b, v120
	v_exp_f32_e32 v118, v118
	v_lshlrev_b32_e32 v119, 16, v123
	v_add_f32_e32 v118, 1.0, v118
	v_rcp_f32_e32 v118, v118
	s_nop 0
	v_mul_f32_e32 v120, v118, v119
	v_mul_f32_e32 v118, 0xbfb8aa3b, v121
	v_exp_f32_e32 v118, v118
	v_and_b32_e32 v119, 0xffff0000, v123
	v_add_f32_e32 v118, 1.0, v118
	v_rcp_f32_e32 v118, v118
	s_nop 0
	v_mul_f32_e32 v156, v118, v119
	v_lshlrev_b32_e32 v119, 16, v124
	v_mul_f32_e32 v137, v114, v119
	v_mul_f32_e32 v114, 0xbfb8aa3b, v115
	v_exp_f32_e32 v114, v114
	v_and_b32_e32 v115, 0xffff0000, v124
	v_mul_f32_e32 v118, v122, v122
	v_fmac_f32_e32 v118, v136, v136
	v_add_f32_e32 v114, 1.0, v114
	v_rcp_f32_e32 v114, v114
	v_fmac_f32_e32 v118, v120, v120
	v_fmac_f32_e32 v118, v156, v156
	v_add_f32_e32 v118, v154, v118
	v_mul_f32_e32 v155, v114, v115
	v_mul_f32_e32 v114, 0xbfb8aa3b, v116
	v_exp_f32_e32 v114, v114
	v_lshlrev_b32_e32 v115, 16, v125
	v_add_f32_e32 v114, 1.0, v114
	v_rcp_f32_e32 v114, v114
	s_nop 0
	v_mul_f32_e32 v154, v114, v115
	v_mul_f32_e32 v114, 0xbfb8aa3b, v117
	v_exp_f32_e32 v114, v114
	v_and_b32_e32 v115, 0xffff0000, v125
	v_add_f32_e32 v114, 1.0, v114
	v_rcp_f32_e32 v114, v114
	s_nop 0
	v_mul_f32_e32 v157, v114, v115
	v_mul_f32_e32 v114, v155, v155
	v_fmac_f32_e32 v114, v137, v137
	v_fmac_f32_e32 v114, v154, v154
	v_fmac_f32_e32 v114, v157, v157
	v_add_f32_e32 v114, v114, v118
	ds_bpermute_b32 v115, v138, v114
	s_waitcnt lgkmcnt(0)
	v_add_f32_e32 v116, v114, v115
	ds_bpermute_b32 v117, v139, v116
	v_lshl_add_u64 v[114:115], v[132:133], 3, s[8:9]
	s_and_saveexec_b64 s[2:3], s[6:7]
	v_readlane_b32 s58, v254, 48
	s_movk_i32 s33, 0x4000
	s_cbranch_execz .LBB0_44
	s_waitcnt lgkmcnt(0)
	v_add_f32_e32 v116, v116, v117
	v_mul_f32_e32 v116, 0x4b800000, v116
	v_trunc_f32_e32 v116, v116
	v_mul_f32_e32 v117, 0x2f800000, v116
	v_floor_f32_e32 v117, v117
	v_fmac_f32_e32 v116, 0xcf800000, v117
	v_cvt_u32_f32_e32 v116, v116
	v_cvt_u32_f32_e32 v117, v117
	global_atomic_add_x2 v[114:115], v[116:117], off
.LBB0_44:
	s_or_b64 exec, exec, s[2:3]
	v_or_b32_e32 v116, 16, v132
	s_waitcnt lgkmcnt(0)
	v_ashrrev_i32_e32 v117, 31, v116
	v_readlane_b32 s0, v255, 12
	v_lshlrev_b64 v[116:117], 11, v[116:117]
	v_readlane_b32 s1, v255, 13
	v_mul_f32_e32 v110, 0xbfb8aa3b, v110
	v_exp_f32_e32 v110, v110
	v_lshl_add_u64 v[118:119], s[0:1], 0, v[116:117]
	v_lshl_add_u64 v[118:119], v[130:131], 1, v[118:119]
	s_nop 1
	v_mov_b64_e32 v[158:159], v[196:197]
	v_mov_b64_e32 v[160:161], v[198:199]
	v_add_f32_e32 v110, 1.0, v110
	v_rcp_f32_e32 v110, v110
	v_mul_f32_e32 v106, 0xbfb8aa3b, v106
	v_exp_f32_e32 v106, v106
	v_mul_f32_e32 v103, 0xbfb8aa3b, v103
	v_exp_f32_e32 v103, v103
	v_mul_f32_e32 v104, 0xbfb8aa3b, v104
	v_add_f32_e32 v106, 1.0, v106
	v_rcp_f32_e32 v106, v106
	v_mul_f32_e32 v102, 0xbfb8aa3b, v102
	v_exp_f32_e32 v104, v104
	v_mul_f32_e32 v98, 0xbfb8aa3b, v98
	v_exp_f32_e32 v102, v102
	v_exp_f32_e32 v98, v98
	v_add_f32_e32 v103, 1.0, v103
	v_rcp_f32_e32 v103, v103
	v_add_f32_e32 v104, 1.0, v104
	v_add_f32_e32 v102, 1.0, v102
	v_rcp_f32_e32 v104, v104
	v_add_f32_e32 v98, 1.0, v98
	v_rcp_f32_e32 v102, v102
	v_rcp_f32_e32 v98, v98
	v_mul_f32_e32 v105, 0xbfb8aa3b, v105
	v_exp_f32_e32 v105, v105
	v_lshlrev_b32_e32 v121, 16, v158
	v_mul_f32_e32 v125, v110, v121
	v_mul_f32_e32 v110, 0xbfb8aa3b, v111
	v_exp_f32_e32 v110, v110
	v_and_b32_e32 v111, 0xffff0000, v158
	v_add_f32_e32 v105, 1.0, v105
	v_rcp_f32_e32 v105, v105
	v_add_f32_e32 v110, 1.0, v110
	v_rcp_f32_e32 v110, v110
	s_nop 0
	v_mul_f32_e32 v124, v110, v111
	v_mul_f32_e32 v110, 0xbfb8aa3b, v112
	v_exp_f32_e32 v110, v110
	v_lshlrev_b32_e32 v111, 16, v159
	v_mul_f32_e32 v144, v124, v124
	v_fmac_f32_e32 v144, v125, v125
	v_add_f32_e32 v110, 1.0, v110
	v_rcp_f32_e32 v110, v110
	s_nop 0
	v_mul_f32_e32 v123, v110, v111
	v_mul_f32_e32 v110, 0xbfb8aa3b, v113
	v_exp_f32_e32 v110, v110
	v_and_b32_e32 v111, 0xffff0000, v159
	v_fmac_f32_e32 v144, v123, v123
	v_add_f32_e32 v110, 1.0, v110
	v_rcp_f32_e32 v110, v110
	s_nop 0
	v_mul_f32_e32 v121, v110, v111
	v_lshlrev_b32_e32 v110, 16, v160
	v_mul_f32_e32 v113, v106, v110
	v_mul_f32_e32 v106, 0xbfb8aa3b, v107
	v_exp_f32_e32 v106, v106
	v_and_b32_e32 v107, 0xffff0000, v160
	v_fmac_f32_e32 v144, v121, v121
	v_add_f32_e32 v106, 1.0, v106
	v_rcp_f32_e32 v106, v106
	s_nop 0
	v_mul_f32_e32 v112, v106, v107
	v_mul_f32_e32 v106, 0xbfb8aa3b, v108
	v_exp_f32_e32 v106, v106
	v_lshlrev_b32_e32 v107, 16, v161
	v_add_f32_e32 v106, 1.0, v106
	v_rcp_f32_e32 v106, v106
	s_nop 0
	v_mul_f32_e32 v111, v106, v107
	v_mul_f32_e32 v106, 0xbfb8aa3b, v109
	v_exp_f32_e32 v106, v106
	v_and_b32_e32 v107, 0xffff0000, v161
	v_add_f32_e32 v106, 1.0, v106
	v_rcp_f32_e32 v106, v106
	s_nop 0
	v_mul_f32_e32 v110, v106, v107
	v_mul_f32_e32 v106, v112, v112
	v_fmac_f32_e32 v106, v113, v113
	v_fmac_f32_e32 v106, v111, v111
	v_fmac_f32_e32 v106, v110, v110
	v_add_f32_e32 v144, v144, v106
	s_nop 1
	v_mov_b64_e32 v[106:107], v[200:201]
	v_mov_b64_e32 v[108:109], v[202:203]
	v_lshlrev_b32_e32 v118, 16, v106
	v_and_b32_e32 v106, 0xffff0000, v106
	v_mul_f32_e32 v103, v103, v106
	v_lshlrev_b32_e32 v106, 16, v107
	v_mul_f32_e32 v104, v104, v106
	v_and_b32_e32 v106, 0xffff0000, v107
	v_lshlrev_b32_e32 v107, 16, v108
	v_mul_f32_e32 v102, v102, v118
	v_mul_f32_e32 v118, v98, v107
	v_mul_f32_e32 v98, 0xbfb8aa3b, v99
	v_exp_f32_e32 v98, v98
	v_and_b32_e32 v99, 0xffff0000, v108
	v_mul_f32_e32 v105, v105, v106
	v_mul_f32_e32 v106, v103, v103
	v_add_f32_e32 v98, 1.0, v98
	v_rcp_f32_e32 v98, v98
	v_fmac_f32_e32 v106, v102, v102
	v_fmac_f32_e32 v106, v104, v104
	v_fmac_f32_e32 v106, v105, v105
	v_mul_f32_e32 v158, v98, v99
	v_mul_f32_e32 v98, 0xbfb8aa3b, v100
	v_exp_f32_e32 v98, v98
	v_lshlrev_b32_e32 v99, 16, v109
	v_add_f32_e32 v106, v144, v106
	v_add_f32_e32 v98, 1.0, v98
	v_rcp_f32_e32 v98, v98
	s_nop 0
	v_mul_f32_e32 v119, v98, v99
	v_mul_f32_e32 v98, 0xbfb8aa3b, v101
	v_exp_f32_e32 v98, v98
	v_and_b32_e32 v99, 0xffff0000, v109
	v_add_f32_e32 v98, 1.0, v98
	v_rcp_f32_e32 v98, v98
	s_nop 0
	v_mul_f32_e32 v159, v98, v99
	v_mul_f32_e32 v98, v158, v158
	v_fmac_f32_e32 v98, v118, v118
	v_fmac_f32_e32 v98, v119, v119
	v_fmac_f32_e32 v98, v159, v159
	v_add_f32_e32 v98, v98, v106
	ds_bpermute_b32 v99, v138, v98
	s_waitcnt lgkmcnt(0)
	v_add_f32_e32 v98, v98, v99
	ds_bpermute_b32 v99, v139, v98
	s_and_saveexec_b64 s[2:3], s[6:7]
	s_cbranch_execz .LBB0_46
	s_waitcnt lgkmcnt(0)
	v_add_f32_e32 v98, v98, v99
	v_mul_f32_e32 v98, 0x4b800000, v98
	v_trunc_f32_e32 v98, v98
	v_mul_f32_e32 v99, 0x2f800000, v98
	v_floor_f32_e32 v99, v99
	v_fmac_f32_e32 v98, 0xcf800000, v99
	v_cvt_u32_f32_e32 v98, v98
	v_cvt_u32_f32_e32 v99, v99
	global_atomic_add_x2 v[114:115], v[98:99], off offset:128
.LBB0_46:
	s_or_b64 exec, exec, s[2:3]
	v_or_b32_e32 v98, 32, v132
	s_waitcnt lgkmcnt(0)
	v_ashrrev_i32_e32 v99, 31, v98
	v_readlane_b32 s0, v255, 12
	v_lshlrev_b64 v[98:99], 11, v[98:99]
	v_readlane_b32 s1, v255, 13
	v_mul_f32_e32 v94, 0xbfb8aa3b, v94
	v_exp_f32_e32 v94, v94
	v_lshl_add_u64 v[100:101], s[0:1], 0, v[98:99]
	v_lshl_add_u64 v[100:101], v[130:131], 1, v[100:101]
	s_nop 1
	v_mov_b64_e32 v[160:161], v[204:205]
	v_mov_b64_e32 v[162:163], v[206:207]
	v_add_f32_e32 v94, 1.0, v94
	v_rcp_f32_e32 v94, v94
	v_mul_f32_e32 v90, 0xbfb8aa3b, v90
	v_exp_f32_e32 v90, v90
	v_mul_f32_e32 v87, 0xbfb8aa3b, v87
	v_exp_f32_e32 v87, v87
	v_mul_f32_e32 v88, 0xbfb8aa3b, v88
	v_add_f32_e32 v90, 1.0, v90
	v_rcp_f32_e32 v90, v90
	v_mul_f32_e32 v86, 0xbfb8aa3b, v86
	v_exp_f32_e32 v88, v88
	v_mul_f32_e32 v82, 0xbfb8aa3b, v82
	v_exp_f32_e32 v86, v86
	v_exp_f32_e32 v82, v82
	v_add_f32_e32 v87, 1.0, v87
	v_rcp_f32_e32 v87, v87
	v_add_f32_e32 v88, 1.0, v88
	v_add_f32_e32 v86, 1.0, v86
	v_rcp_f32_e32 v88, v88
	v_add_f32_e32 v82, 1.0, v82
	v_rcp_f32_e32 v86, v86
	v_rcp_f32_e32 v82, v82
	v_mul_f32_e32 v89, 0xbfb8aa3b, v89
	v_exp_f32_e32 v89, v89
	v_lshlrev_b32_e32 v106, 16, v160
	v_mul_f32_e32 v109, v94, v106
	v_mul_f32_e32 v94, 0xbfb8aa3b, v95
	v_exp_f32_e32 v94, v94
	v_and_b32_e32 v95, 0xffff0000, v160
	v_add_f32_e32 v89, 1.0, v89
	v_rcp_f32_e32 v89, v89
	v_add_f32_e32 v94, 1.0, v94
	v_rcp_f32_e32 v94, v94
	s_nop 0
	v_mul_f32_e32 v108, v94, v95
	v_mul_f32_e32 v94, 0xbfb8aa3b, v96
	v_exp_f32_e32 v94, v94
	v_lshlrev_b32_e32 v95, 16, v161
	v_mul_f32_e32 v144, v108, v108
	v_fmac_f32_e32 v144, v109, v109
	v_add_f32_e32 v94, 1.0, v94
	v_rcp_f32_e32 v94, v94
	s_nop 0
	v_mul_f32_e32 v107, v94, v95
	v_mul_f32_e32 v94, 0xbfb8aa3b, v97
	v_exp_f32_e32 v94, v94
	v_and_b32_e32 v95, 0xffff0000, v161
	v_fmac_f32_e32 v144, v107, v107
	v_add_f32_e32 v94, 1.0, v94
	v_rcp_f32_e32 v94, v94
	s_nop 0
	v_mul_f32_e32 v106, v94, v95
	v_lshlrev_b32_e32 v94, 16, v162
	v_mul_f32_e32 v97, v90, v94
	v_mul_f32_e32 v90, 0xbfb8aa3b, v91
	v_exp_f32_e32 v90, v90
	v_and_b32_e32 v91, 0xffff0000, v162
	v_fmac_f32_e32 v144, v106, v106
	v_add_f32_e32 v90, 1.0, v90
	v_rcp_f32_e32 v90, v90
	s_nop 0
	v_mul_f32_e32 v96, v90, v91
	v_mul_f32_e32 v90, 0xbfb8aa3b, v92
	v_exp_f32_e32 v90, v90
	v_lshlrev_b32_e32 v91, 16, v163
	v_add_f32_e32 v90, 1.0, v90
	v_rcp_f32_e32 v90, v90
	s_nop 0
	v_mul_f32_e32 v95, v90, v91
	v_mul_f32_e32 v90, 0xbfb8aa3b, v93
	v_exp_f32_e32 v90, v90
	v_and_b32_e32 v91, 0xffff0000, v163
	v_add_f32_e32 v90, 1.0, v90
	v_rcp_f32_e32 v90, v90
	s_nop 0
	v_mul_f32_e32 v94, v90, v91
	v_mul_f32_e32 v90, v96, v96
	v_fmac_f32_e32 v90, v97, v97
	v_fmac_f32_e32 v90, v95, v95
	v_fmac_f32_e32 v90, v94, v94
	v_add_f32_e32 v144, v144, v90
	s_nop 1
	v_mov_b64_e32 v[90:91], v[208:209]
	v_mov_b64_e32 v[92:93], v[210:211]
	v_lshlrev_b32_e32 v100, 16, v90
	v_and_b32_e32 v90, 0xffff0000, v90
	v_mul_f32_e32 v87, v87, v90
	v_lshlrev_b32_e32 v90, 16, v91
	v_mul_f32_e32 v88, v88, v90
	v_and_b32_e32 v90, 0xffff0000, v91
	v_lshlrev_b32_e32 v91, 16, v92
	v_mul_f32_e32 v86, v86, v100
	v_mul_f32_e32 v100, v82, v91
	v_mul_f32_e32 v82, 0xbfb8aa3b, v83
	v_exp_f32_e32 v82, v82
	v_and_b32_e32 v83, 0xffff0000, v92
	v_mul_f32_e32 v89, v89, v90
	v_mul_f32_e32 v90, v87, v87
	v_add_f32_e32 v82, 1.0, v82
	v_rcp_f32_e32 v82, v82
	v_fmac_f32_e32 v90, v86, v86
	v_fmac_f32_e32 v90, v88, v88
	v_fmac_f32_e32 v90, v89, v89
	v_mul_f32_e32 v160, v82, v83
	v_mul_f32_e32 v82, 0xbfb8aa3b, v84
	v_exp_f32_e32 v82, v82
	v_lshlrev_b32_e32 v83, 16, v93
	v_add_f32_e32 v90, v144, v90
	v_add_f32_e32 v82, 1.0, v82
	v_rcp_f32_e32 v82, v82
	s_nop 0
	v_mul_f32_e32 v101, v82, v83
	v_mul_f32_e32 v82, 0xbfb8aa3b, v85
	v_exp_f32_e32 v82, v82
	v_and_b32_e32 v83, 0xffff0000, v93
	v_add_f32_e32 v82, 1.0, v82
	v_rcp_f32_e32 v82, v82
	s_nop 0
	v_mul_f32_e32 v161, v82, v83
	v_mul_f32_e32 v82, v160, v160
	v_fmac_f32_e32 v82, v100, v100
	v_fmac_f32_e32 v82, v101, v101
	v_fmac_f32_e32 v82, v161, v161
	v_add_f32_e32 v82, v82, v90
	ds_bpermute_b32 v83, v138, v82
	s_waitcnt lgkmcnt(0)
	v_add_f32_e32 v82, v82, v83
	ds_bpermute_b32 v83, v139, v82
	s_and_saveexec_b64 s[2:3], s[6:7]
	s_cbranch_execz .LBB0_48
	s_waitcnt lgkmcnt(0)
	v_add_f32_e32 v82, v82, v83
	v_mul_f32_e32 v82, 0x4b800000, v82
	v_trunc_f32_e32 v82, v82
	v_mul_f32_e32 v83, 0x2f800000, v82
	v_floor_f32_e32 v83, v83
	v_fmac_f32_e32 v82, 0xcf800000, v83
	v_cvt_u32_f32_e32 v82, v82
	v_cvt_u32_f32_e32 v83, v83
	global_atomic_add_x2 v[114:115], v[82:83], off offset:256
.LBB0_48:
	s_or_b64 exec, exec, s[2:3]
	v_or_b32_e32 v82, 48, v132
	s_waitcnt lgkmcnt(0)
	v_ashrrev_i32_e32 v83, 31, v82
	v_readlane_b32 s0, v255, 12
	v_lshlrev_b64 v[82:83], 11, v[82:83]
	v_readlane_b32 s1, v255, 13
	v_mul_f32_e32 v78, 0xbfb8aa3b, v78
	v_exp_f32_e32 v78, v78
	v_lshl_add_u64 v[84:85], s[0:1], 0, v[82:83]
	v_lshl_add_u64 v[84:85], v[130:131], 1, v[84:85]
	s_nop 1
	v_mov_b64_e32 v[162:163], v[212:213]
	v_mov_b64_e32 v[164:165], v[214:215]
	v_add_f32_e32 v78, 1.0, v78
	v_rcp_f32_e32 v78, v78
	v_mul_f32_e32 v74, 0xbfb8aa3b, v74
	v_exp_f32_e32 v74, v74
	v_mul_f32_e32 v71, 0xbfb8aa3b, v71
	v_exp_f32_e32 v71, v71
	v_mul_f32_e32 v72, 0xbfb8aa3b, v72
	v_add_f32_e32 v74, 1.0, v74
	v_rcp_f32_e32 v74, v74
	v_mul_f32_e32 v70, 0xbfb8aa3b, v70
	v_exp_f32_e32 v72, v72
	v_mul_f32_e32 v66, 0xbfb8aa3b, v66
	v_exp_f32_e32 v70, v70
	v_exp_f32_e32 v66, v66
	v_add_f32_e32 v71, 1.0, v71
	v_rcp_f32_e32 v71, v71
	v_add_f32_e32 v72, 1.0, v72
	v_add_f32_e32 v70, 1.0, v70
	v_rcp_f32_e32 v72, v72
	v_add_f32_e32 v66, 1.0, v66
	v_rcp_f32_e32 v70, v70
	v_rcp_f32_e32 v66, v66
	v_mul_f32_e32 v73, 0xbfb8aa3b, v73
	v_exp_f32_e32 v73, v73
	v_lshlrev_b32_e32 v90, 16, v162
	v_mul_f32_e32 v93, v78, v90
	v_mul_f32_e32 v78, 0xbfb8aa3b, v79
	v_exp_f32_e32 v78, v78
	v_and_b32_e32 v79, 0xffff0000, v162
	v_add_f32_e32 v73, 1.0, v73
	v_rcp_f32_e32 v73, v73
	v_add_f32_e32 v78, 1.0, v78
	v_rcp_f32_e32 v78, v78
	s_nop 0
	v_mul_f32_e32 v92, v78, v79
	v_mul_f32_e32 v78, 0xbfb8aa3b, v80
	v_exp_f32_e32 v78, v78
	v_lshlrev_b32_e32 v79, 16, v163
	v_mul_f32_e32 v144, v92, v92
	v_fmac_f32_e32 v144, v93, v93
	v_add_f32_e32 v78, 1.0, v78
	v_rcp_f32_e32 v78, v78
	s_nop 0
	v_mul_f32_e32 v91, v78, v79
	v_mul_f32_e32 v78, 0xbfb8aa3b, v81
	v_exp_f32_e32 v78, v78
	v_and_b32_e32 v79, 0xffff0000, v163
	v_fmac_f32_e32 v144, v91, v91
	v_add_f32_e32 v78, 1.0, v78
	v_rcp_f32_e32 v78, v78
	s_nop 0
	v_mul_f32_e32 v90, v78, v79
	v_lshlrev_b32_e32 v78, 16, v164
	v_mul_f32_e32 v81, v74, v78
	v_mul_f32_e32 v74, 0xbfb8aa3b, v75
	v_exp_f32_e32 v74, v74
	v_and_b32_e32 v75, 0xffff0000, v164
	v_fmac_f32_e32 v144, v90, v90
	v_add_f32_e32 v74, 1.0, v74
	v_rcp_f32_e32 v74, v74
	s_nop 0
	v_mul_f32_e32 v80, v74, v75
	v_mul_f32_e32 v74, 0xbfb8aa3b, v76
	v_exp_f32_e32 v74, v74
	v_lshlrev_b32_e32 v75, 16, v165
	v_add_f32_e32 v74, 1.0, v74
	v_rcp_f32_e32 v74, v74
	s_nop 0
	v_mul_f32_e32 v79, v74, v75
	v_mul_f32_e32 v74, 0xbfb8aa3b, v77
	v_exp_f32_e32 v74, v74
	v_and_b32_e32 v75, 0xffff0000, v165
	v_add_f32_e32 v74, 1.0, v74
	v_rcp_f32_e32 v74, v74
	s_nop 0
	v_mul_f32_e32 v78, v74, v75
	v_mul_f32_e32 v74, v80, v80
	v_fmac_f32_e32 v74, v81, v81
	v_fmac_f32_e32 v74, v79, v79
	v_fmac_f32_e32 v74, v78, v78
	v_add_f32_e32 v144, v144, v74
	s_nop 1
	v_mov_b64_e32 v[74:75], v[218:219]
	v_mov_b64_e32 v[76:77], v[220:221]
	v_lshlrev_b32_e32 v84, 16, v74
	v_and_b32_e32 v74, 0xffff0000, v74
	v_mul_f32_e32 v71, v71, v74
	v_lshlrev_b32_e32 v74, 16, v75
	v_mul_f32_e32 v72, v72, v74
	v_and_b32_e32 v74, 0xffff0000, v75
	v_lshlrev_b32_e32 v75, 16, v76
	v_mul_f32_e32 v70, v70, v84
	v_mul_f32_e32 v84, v66, v75
	v_mul_f32_e32 v66, 0xbfb8aa3b, v67
	v_exp_f32_e32 v66, v66
	v_and_b32_e32 v67, 0xffff0000, v76
	v_mul_f32_e32 v73, v73, v74
	v_mul_f32_e32 v74, v71, v71
	v_add_f32_e32 v66, 1.0, v66
	v_rcp_f32_e32 v66, v66
	v_fmac_f32_e32 v74, v70, v70
	v_fmac_f32_e32 v74, v72, v72
	v_fmac_f32_e32 v74, v73, v73
	v_mul_f32_e32 v162, v66, v67
	v_mul_f32_e32 v66, 0xbfb8aa3b, v68
	v_exp_f32_e32 v66, v66
	v_lshlrev_b32_e32 v67, 16, v77
	v_add_f32_e32 v74, v144, v74
	v_add_f32_e32 v66, 1.0, v66
	v_rcp_f32_e32 v66, v66
	s_nop 0
	v_mul_f32_e32 v85, v66, v67
	v_mul_f32_e32 v66, 0xbfb8aa3b, v69
	v_exp_f32_e32 v66, v66
	v_and_b32_e32 v67, 0xffff0000, v77
	v_add_f32_e32 v66, 1.0, v66
	v_rcp_f32_e32 v66, v66
	s_nop 0
	v_mul_f32_e32 v163, v66, v67
	v_mul_f32_e32 v66, v162, v162
	v_fmac_f32_e32 v66, v84, v84
	v_fmac_f32_e32 v66, v85, v85
	v_fmac_f32_e32 v66, v163, v163
	v_add_f32_e32 v66, v66, v74
	ds_bpermute_b32 v67, v138, v66
	s_waitcnt lgkmcnt(0)
	v_add_f32_e32 v66, v66, v67
	ds_bpermute_b32 v67, v139, v66
	s_and_saveexec_b64 s[2:3], s[6:7]
	s_cbranch_execz .LBB0_50
	s_waitcnt lgkmcnt(0)
	v_add_f32_e32 v66, v66, v67
	v_mul_f32_e32 v66, 0x4b800000, v66
	v_trunc_f32_e32 v66, v66
	v_mul_f32_e32 v67, 0x2f800000, v66
	v_floor_f32_e32 v67, v67
	v_fmac_f32_e32 v66, 0xcf800000, v67
	v_cvt_u32_f32_e32 v66, v66
	v_cvt_u32_f32_e32 v67, v67
	global_atomic_add_x2 v[114:115], v[66:67], off offset:384
.LBB0_50:
	s_or_b64 exec, exec, s[2:3]
	s_mov_b64 s[0:1], 0x40000
	s_waitcnt lgkmcnt(0)
	v_lshl_add_u64 v[66:67], v[134:135], 0, s[0:1]
	v_readlane_b32 s0, v255, 12
	v_readlane_b32 s1, v255, 13
	v_mul_f32_e32 v62, 0xbfb8aa3b, v62
	v_exp_f32_e32 v62, v62
	v_lshl_add_u64 v[68:69], s[0:1], 0, v[66:67]
	v_lshl_add_u64 v[68:69], v[130:131], 1, v[68:69]
	s_nop 1
	v_mov_b64_e32 v[164:165], v[222:223]
	v_mov_b64_e32 v[166:167], v[224:225]
	v_add_f32_e32 v62, 1.0, v62
	v_rcp_f32_e32 v62, v62
	v_mul_f32_e32 v58, 0xbfb8aa3b, v58
	v_exp_f32_e32 v58, v58
	v_mul_f32_e32 v55, 0xbfb8aa3b, v55
	v_exp_f32_e32 v55, v55
	v_mul_f32_e32 v56, 0xbfb8aa3b, v56
	v_add_f32_e32 v58, 1.0, v58
	v_rcp_f32_e32 v58, v58
	v_mul_f32_e32 v54, 0xbfb8aa3b, v54
	v_exp_f32_e32 v56, v56
	v_mul_f32_e32 v50, 0xbfb8aa3b, v50
	v_exp_f32_e32 v54, v54
	v_exp_f32_e32 v50, v50
	v_add_f32_e32 v55, 1.0, v55
	v_rcp_f32_e32 v55, v55
	v_add_f32_e32 v56, 1.0, v56
	v_add_f32_e32 v54, 1.0, v54
	v_rcp_f32_e32 v56, v56
	v_add_f32_e32 v50, 1.0, v50
	v_rcp_f32_e32 v54, v54
	v_rcp_f32_e32 v50, v50
	v_mul_f32_e32 v57, 0xbfb8aa3b, v57
	v_exp_f32_e32 v57, v57
	v_lshlrev_b32_e32 v74, 16, v164
	v_mul_f32_e32 v77, v62, v74
	v_mul_f32_e32 v62, 0xbfb8aa3b, v63
	v_exp_f32_e32 v62, v62
	v_and_b32_e32 v63, 0xffff0000, v164
	v_add_f32_e32 v57, 1.0, v57
	v_rcp_f32_e32 v57, v57
	v_add_f32_e32 v62, 1.0, v62
	v_rcp_f32_e32 v62, v62
	s_nop 0
	v_mul_f32_e32 v76, v62, v63
	v_mul_f32_e32 v62, 0xbfb8aa3b, v64
	v_exp_f32_e32 v62, v62
	v_lshlrev_b32_e32 v63, 16, v165
	v_mul_f32_e32 v144, v76, v76
	v_fmac_f32_e32 v144, v77, v77
	v_add_f32_e32 v62, 1.0, v62
	v_rcp_f32_e32 v62, v62
	s_nop 0
	v_mul_f32_e32 v75, v62, v63
	v_mul_f32_e32 v62, 0xbfb8aa3b, v65
	v_exp_f32_e32 v62, v62
	v_and_b32_e32 v63, 0xffff0000, v165
	v_fmac_f32_e32 v144, v75, v75
	v_add_f32_e32 v62, 1.0, v62
	v_rcp_f32_e32 v62, v62
	s_nop 0
	v_mul_f32_e32 v74, v62, v63
	v_lshlrev_b32_e32 v62, 16, v166
	v_mul_f32_e32 v65, v58, v62
	v_mul_f32_e32 v58, 0xbfb8aa3b, v59
	v_exp_f32_e32 v58, v58
	v_and_b32_e32 v59, 0xffff0000, v166
	v_fmac_f32_e32 v144, v74, v74
	v_add_f32_e32 v58, 1.0, v58
	v_rcp_f32_e32 v58, v58
	s_nop 0
	v_mul_f32_e32 v64, v58, v59
	v_mul_f32_e32 v58, 0xbfb8aa3b, v60
	v_exp_f32_e32 v58, v58
	v_lshlrev_b32_e32 v59, 16, v167
	v_add_f32_e32 v58, 1.0, v58
	v_rcp_f32_e32 v58, v58
	s_nop 0
	v_mul_f32_e32 v63, v58, v59
	v_mul_f32_e32 v58, 0xbfb8aa3b, v61
	v_exp_f32_e32 v58, v58
	v_and_b32_e32 v59, 0xffff0000, v167
	v_add_f32_e32 v58, 1.0, v58
	v_rcp_f32_e32 v58, v58
	s_nop 0
	v_mul_f32_e32 v62, v58, v59
	v_mul_f32_e32 v58, v64, v64
	v_fmac_f32_e32 v58, v65, v65
	v_fmac_f32_e32 v58, v63, v63
	v_fmac_f32_e32 v58, v62, v62
	v_add_f32_e32 v144, v144, v58
	s_nop 1
	v_mov_b64_e32 v[58:59], v[226:227]
	v_mov_b64_e32 v[60:61], v[228:229]
	v_lshlrev_b32_e32 v68, 16, v58
	v_and_b32_e32 v58, 0xffff0000, v58
	v_mul_f32_e32 v55, v55, v58
	v_lshlrev_b32_e32 v58, 16, v59
	v_mul_f32_e32 v56, v56, v58
	v_and_b32_e32 v58, 0xffff0000, v59
	v_lshlrev_b32_e32 v59, 16, v60
	v_mul_f32_e32 v54, v54, v68
	v_mul_f32_e32 v68, v50, v59
	v_mul_f32_e32 v50, 0xbfb8aa3b, v51
	v_exp_f32_e32 v50, v50
	v_and_b32_e32 v51, 0xffff0000, v60
	v_mul_f32_e32 v57, v57, v58
	v_mul_f32_e32 v58, v55, v55
	v_add_f32_e32 v50, 1.0, v50
	v_rcp_f32_e32 v50, v50
	v_fmac_f32_e32 v58, v54, v54
	v_fmac_f32_e32 v58, v56, v56
	v_fmac_f32_e32 v58, v57, v57
	v_mul_f32_e32 v164, v50, v51
	v_mul_f32_e32 v50, 0xbfb8aa3b, v52
	v_exp_f32_e32 v50, v50
	v_lshlrev_b32_e32 v51, 16, v61
	v_add_f32_e32 v58, v144, v58
	v_add_f32_e32 v50, 1.0, v50
	v_rcp_f32_e32 v50, v50
	s_nop 0
	v_mul_f32_e32 v69, v50, v51
	v_mul_f32_e32 v50, 0xbfb8aa3b, v53
	v_exp_f32_e32 v50, v50
	v_and_b32_e32 v51, 0xffff0000, v61
	v_add_f32_e32 v50, 1.0, v50
	v_rcp_f32_e32 v50, v50
	s_nop 0
	v_mul_f32_e32 v165, v50, v51
	v_mul_f32_e32 v50, v164, v164
	v_fmac_f32_e32 v50, v68, v68
	v_fmac_f32_e32 v50, v69, v69
	v_fmac_f32_e32 v50, v165, v165
	v_add_f32_e32 v50, v50, v58
	ds_bpermute_b32 v51, v138, v50
	s_waitcnt lgkmcnt(0)
	v_add_f32_e32 v50, v50, v51
	ds_bpermute_b32 v51, v139, v50
	s_and_saveexec_b64 s[2:3], s[6:7]
	s_cbranch_execz .LBB0_52
	s_waitcnt lgkmcnt(0)
	v_add_f32_e32 v50, v50, v51
	v_mul_f32_e32 v50, 0x4b800000, v50
	v_trunc_f32_e32 v50, v50
	v_mul_f32_e32 v51, 0x2f800000, v50
	v_floor_f32_e32 v51, v51
	v_fmac_f32_e32 v50, 0xcf800000, v51
	v_cvt_u32_f32_e32 v50, v50
	v_cvt_u32_f32_e32 v51, v51
	global_atomic_add_x2 v[114:115], v[50:51], off offset:1024
.LBB0_52:
	s_or_b64 exec, exec, s[2:3]
	s_mov_b64 s[0:1], 0x48000
	s_waitcnt lgkmcnt(0)
	v_lshl_add_u64 v[50:51], v[134:135], 0, s[0:1]
	v_readlane_b32 s0, v255, 12
	v_readlane_b32 s1, v255, 13
	v_mul_f32_e32 v46, 0xbfb8aa3b, v46
	v_exp_f32_e32 v46, v46
	v_lshl_add_u64 v[52:53], s[0:1], 0, v[50:51]
	v_lshl_add_u64 v[52:53], v[130:131], 1, v[52:53]
	s_nop 1
	v_mov_b64_e32 v[166:167], v[230:231]
	v_mov_b64_e32 v[168:169], v[232:233]
	v_add_f32_e32 v46, 1.0, v46
	v_rcp_f32_e32 v46, v46
	v_mul_f32_e32 v42, 0xbfb8aa3b, v42
	v_exp_f32_e32 v42, v42
	v_mul_f32_e32 v39, 0xbfb8aa3b, v39
	v_exp_f32_e32 v39, v39
	v_mul_f32_e32 v40, 0xbfb8aa3b, v40
	v_add_f32_e32 v42, 1.0, v42
	v_rcp_f32_e32 v42, v42
	v_mul_f32_e32 v38, 0xbfb8aa3b, v38
	v_exp_f32_e32 v40, v40
	v_mul_f32_e32 v34, 0xbfb8aa3b, v34
	v_exp_f32_e32 v38, v38
	v_exp_f32_e32 v34, v34
	v_add_f32_e32 v39, 1.0, v39
	v_rcp_f32_e32 v39, v39
	v_add_f32_e32 v40, 1.0, v40
	v_add_f32_e32 v38, 1.0, v38
	v_rcp_f32_e32 v40, v40
	v_add_f32_e32 v34, 1.0, v34
	v_rcp_f32_e32 v38, v38
	v_rcp_f32_e32 v34, v34
	v_mul_f32_e32 v41, 0xbfb8aa3b, v41
	v_exp_f32_e32 v41, v41
	v_lshlrev_b32_e32 v58, 16, v166
	v_mul_f32_e32 v61, v46, v58
	v_mul_f32_e32 v46, 0xbfb8aa3b, v47
	v_exp_f32_e32 v46, v46
	v_and_b32_e32 v47, 0xffff0000, v166
	v_add_f32_e32 v41, 1.0, v41
	v_rcp_f32_e32 v41, v41
	v_add_f32_e32 v46, 1.0, v46
	v_rcp_f32_e32 v46, v46
	s_nop 0
	v_mul_f32_e32 v60, v46, v47
	v_mul_f32_e32 v46, 0xbfb8aa3b, v48
	v_exp_f32_e32 v46, v46
	v_lshlrev_b32_e32 v47, 16, v167
	v_mul_f32_e32 v144, v60, v60
	v_fmac_f32_e32 v144, v61, v61
	v_add_f32_e32 v46, 1.0, v46
	v_rcp_f32_e32 v46, v46
	s_nop 0
	v_mul_f32_e32 v59, v46, v47
	v_mul_f32_e32 v46, 0xbfb8aa3b, v49
	v_exp_f32_e32 v46, v46
	v_and_b32_e32 v47, 0xffff0000, v167
	v_fmac_f32_e32 v144, v59, v59
	v_add_f32_e32 v46, 1.0, v46
	v_rcp_f32_e32 v46, v46
	s_nop 0
	v_mul_f32_e32 v58, v46, v47
	v_lshlrev_b32_e32 v46, 16, v168
	v_mul_f32_e32 v49, v42, v46
	v_mul_f32_e32 v42, 0xbfb8aa3b, v43
	v_exp_f32_e32 v42, v42
	v_and_b32_e32 v43, 0xffff0000, v168
	v_fmac_f32_e32 v144, v58, v58
	v_add_f32_e32 v42, 1.0, v42
	v_rcp_f32_e32 v42, v42
	s_nop 0
	v_mul_f32_e32 v48, v42, v43
	v_mul_f32_e32 v42, 0xbfb8aa3b, v44
	v_exp_f32_e32 v42, v42
	v_lshlrev_b32_e32 v43, 16, v169
	v_add_f32_e32 v42, 1.0, v42
	v_rcp_f32_e32 v42, v42
	s_nop 0
	v_mul_f32_e32 v47, v42, v43
	v_mul_f32_e32 v42, 0xbfb8aa3b, v45
	v_exp_f32_e32 v42, v42
	v_and_b32_e32 v43, 0xffff0000, v169
	v_add_f32_e32 v42, 1.0, v42
	v_rcp_f32_e32 v42, v42
	s_nop 0
	v_mul_f32_e32 v46, v42, v43
	v_mul_f32_e32 v42, v48, v48
	v_fmac_f32_e32 v42, v49, v49
	v_fmac_f32_e32 v42, v47, v47
	v_fmac_f32_e32 v42, v46, v46
	v_add_f32_e32 v144, v144, v42
	s_nop 1
	v_mov_b64_e32 v[42:43], v[234:235]
	v_mov_b64_e32 v[44:45], v[236:237]
	v_lshlrev_b32_e32 v52, 16, v42
	v_and_b32_e32 v42, 0xffff0000, v42
	v_mul_f32_e32 v39, v39, v42
	v_lshlrev_b32_e32 v42, 16, v43
	v_mul_f32_e32 v40, v40, v42
	v_and_b32_e32 v42, 0xffff0000, v43
	v_lshlrev_b32_e32 v43, 16, v44
	v_mul_f32_e32 v38, v38, v52
	v_mul_f32_e32 v52, v34, v43
	v_mul_f32_e32 v34, 0xbfb8aa3b, v35
	v_exp_f32_e32 v34, v34
	v_and_b32_e32 v35, 0xffff0000, v44
	v_mul_f32_e32 v41, v41, v42
	v_mul_f32_e32 v42, v39, v39
	v_add_f32_e32 v34, 1.0, v34
	v_rcp_f32_e32 v34, v34
	v_fmac_f32_e32 v42, v38, v38
	v_fmac_f32_e32 v42, v40, v40
	v_fmac_f32_e32 v42, v41, v41
	v_mul_f32_e32 v166, v34, v35
	v_mul_f32_e32 v34, 0xbfb8aa3b, v36
	v_exp_f32_e32 v34, v34
	v_lshlrev_b32_e32 v35, 16, v45
	v_add_f32_e32 v42, v144, v42
	v_add_f32_e32 v34, 1.0, v34
	v_rcp_f32_e32 v34, v34
	s_nop 0
	v_mul_f32_e32 v53, v34, v35
	v_mul_f32_e32 v34, 0xbfb8aa3b, v37
	v_exp_f32_e32 v34, v34
	v_and_b32_e32 v35, 0xffff0000, v45
	v_add_f32_e32 v34, 1.0, v34
	v_rcp_f32_e32 v34, v34
	s_nop 0
	v_mul_f32_e32 v167, v34, v35
	v_mul_f32_e32 v34, v166, v166
	v_fmac_f32_e32 v34, v52, v52
	v_fmac_f32_e32 v34, v53, v53
	v_fmac_f32_e32 v34, v167, v167
	v_add_f32_e32 v34, v34, v42
	ds_bpermute_b32 v35, v138, v34
	s_waitcnt lgkmcnt(0)
	v_add_f32_e32 v34, v34, v35
	ds_bpermute_b32 v35, v139, v34
	s_and_saveexec_b64 s[2:3], s[6:7]
	s_cbranch_execz .LBB0_54
	s_waitcnt lgkmcnt(0)
	v_add_f32_e32 v34, v34, v35
	v_mul_f32_e32 v34, 0x4b800000, v34
	v_trunc_f32_e32 v34, v34
	v_mul_f32_e32 v35, 0x2f800000, v34
	v_floor_f32_e32 v35, v35
	v_fmac_f32_e32 v34, 0xcf800000, v35
	v_cvt_u32_f32_e32 v34, v34
	v_cvt_u32_f32_e32 v35, v35
	global_atomic_add_x2 v[114:115], v[34:35], off offset:1152
.LBB0_54:
	s_or_b64 exec, exec, s[2:3]
	s_mov_b64 s[0:1], 0x50000
	s_waitcnt lgkmcnt(0)
	v_lshl_add_u64 v[34:35], v[134:135], 0, s[0:1]
	v_readlane_b32 s0, v255, 12
	v_readlane_b32 s1, v255, 13
	v_mul_f32_e32 v30, 0xbfb8aa3b, v30
	v_exp_f32_e32 v30, v30
	v_lshl_add_u64 v[36:37], s[0:1], 0, v[34:35]
	v_lshl_add_u64 v[36:37], v[130:131], 1, v[36:37]
	s_nop 1
	v_mov_b64_e32 v[168:169], v[238:239]
	v_mov_b64_e32 v[170:171], v[240:241]
	v_add_f32_e32 v30, 1.0, v30
	v_rcp_f32_e32 v30, v30
	v_mul_f32_e32 v26, 0xbfb8aa3b, v26
	v_exp_f32_e32 v26, v26
	v_mul_f32_e32 v23, 0xbfb8aa3b, v23
	v_exp_f32_e32 v23, v23
	v_mul_f32_e32 v24, 0xbfb8aa3b, v24
	v_add_f32_e32 v26, 1.0, v26
	v_rcp_f32_e32 v26, v26
	v_mul_f32_e32 v22, 0xbfb8aa3b, v22
	v_exp_f32_e32 v24, v24
	v_mul_f32_e32 v18, 0xbfb8aa3b, v18
	v_exp_f32_e32 v22, v22
	v_exp_f32_e32 v18, v18
	v_add_f32_e32 v23, 1.0, v23
	v_rcp_f32_e32 v23, v23
	v_add_f32_e32 v24, 1.0, v24
	v_add_f32_e32 v22, 1.0, v22
	v_rcp_f32_e32 v24, v24
	v_add_f32_e32 v18, 1.0, v18
	v_rcp_f32_e32 v22, v22
	v_rcp_f32_e32 v18, v18
	v_mul_f32_e32 v25, 0xbfb8aa3b, v25
	v_exp_f32_e32 v25, v25
	v_lshlrev_b32_e32 v42, 16, v168
	v_mul_f32_e32 v45, v30, v42
	v_mul_f32_e32 v30, 0xbfb8aa3b, v31
	v_exp_f32_e32 v30, v30
	v_and_b32_e32 v31, 0xffff0000, v168
	v_add_f32_e32 v25, 1.0, v25
	v_rcp_f32_e32 v25, v25
	v_add_f32_e32 v30, 1.0, v30
	v_rcp_f32_e32 v30, v30
	s_nop 0
	v_mul_f32_e32 v44, v30, v31
	v_mul_f32_e32 v30, 0xbfb8aa3b, v32
	v_exp_f32_e32 v30, v30
	v_lshlrev_b32_e32 v31, 16, v169
	v_mul_f32_e32 v144, v44, v44
	v_fmac_f32_e32 v144, v45, v45
	v_add_f32_e32 v30, 1.0, v30
	v_rcp_f32_e32 v30, v30
	s_nop 0
	v_mul_f32_e32 v43, v30, v31
	v_mul_f32_e32 v30, 0xbfb8aa3b, v33
	v_exp_f32_e32 v30, v30
	v_and_b32_e32 v31, 0xffff0000, v169
	v_fmac_f32_e32 v144, v43, v43
	v_add_f32_e32 v30, 1.0, v30
	v_rcp_f32_e32 v30, v30
	s_nop 0
	v_mul_f32_e32 v42, v30, v31
	v_lshlrev_b32_e32 v30, 16, v170
	v_mul_f32_e32 v33, v26, v30
	v_mul_f32_e32 v26, 0xbfb8aa3b, v27
	v_exp_f32_e32 v26, v26
	v_and_b32_e32 v27, 0xffff0000, v170
	v_fmac_f32_e32 v144, v42, v42
	v_add_f32_e32 v26, 1.0, v26
	v_rcp_f32_e32 v26, v26
	s_nop 0
	v_mul_f32_e32 v32, v26, v27
	v_mul_f32_e32 v26, 0xbfb8aa3b, v28
	v_exp_f32_e32 v26, v26
	v_lshlrev_b32_e32 v27, 16, v171
	v_add_f32_e32 v26, 1.0, v26
	v_rcp_f32_e32 v26, v26
	s_nop 0
	v_mul_f32_e32 v31, v26, v27
	v_mul_f32_e32 v26, 0xbfb8aa3b, v29
	v_exp_f32_e32 v26, v26
	v_and_b32_e32 v27, 0xffff0000, v171
	v_add_f32_e32 v26, 1.0, v26
	v_rcp_f32_e32 v26, v26
	s_nop 0
	v_mul_f32_e32 v30, v26, v27
	v_mul_f32_e32 v26, v32, v32
	v_fmac_f32_e32 v26, v33, v33
	v_fmac_f32_e32 v26, v31, v31
	v_fmac_f32_e32 v26, v30, v30
	v_add_f32_e32 v144, v144, v26
	s_nop 1
	v_mov_b64_e32 v[26:27], v[242:243]
	v_mov_b64_e32 v[28:29], v[244:245]
	v_lshlrev_b32_e32 v36, 16, v26
	v_and_b32_e32 v26, 0xffff0000, v26
	v_mul_f32_e32 v23, v23, v26
	v_lshlrev_b32_e32 v26, 16, v27
	v_mul_f32_e32 v24, v24, v26
	v_and_b32_e32 v26, 0xffff0000, v27
	v_lshlrev_b32_e32 v27, 16, v28
	v_mul_f32_e32 v22, v22, v36
	v_mul_f32_e32 v36, v18, v27
	v_mul_f32_e32 v18, 0xbfb8aa3b, v19
	v_exp_f32_e32 v18, v18
	v_and_b32_e32 v19, 0xffff0000, v28
	v_mul_f32_e32 v25, v25, v26
	v_mul_f32_e32 v26, v23, v23
	v_add_f32_e32 v18, 1.0, v18
	v_rcp_f32_e32 v18, v18
	v_fmac_f32_e32 v26, v22, v22
	v_fmac_f32_e32 v26, v24, v24
	v_fmac_f32_e32 v26, v25, v25
	v_mul_f32_e32 v168, v18, v19
	v_mul_f32_e32 v18, 0xbfb8aa3b, v20
	v_exp_f32_e32 v18, v18
	v_lshlrev_b32_e32 v19, 16, v29
	v_add_f32_e32 v26, v144, v26
	v_add_f32_e32 v18, 1.0, v18
	v_rcp_f32_e32 v18, v18
	s_nop 0
	v_mul_f32_e32 v37, v18, v19
	v_mul_f32_e32 v18, 0xbfb8aa3b, v21
	v_exp_f32_e32 v18, v18
	v_and_b32_e32 v19, 0xffff0000, v29
	v_add_f32_e32 v18, 1.0, v18
	v_rcp_f32_e32 v18, v18
	s_nop 0
	v_mul_f32_e32 v169, v18, v19
	v_mul_f32_e32 v18, v168, v168
	v_fmac_f32_e32 v18, v36, v36
	v_fmac_f32_e32 v18, v37, v37
	v_fmac_f32_e32 v18, v169, v169
	v_add_f32_e32 v18, v18, v26
	ds_bpermute_b32 v19, v138, v18
	s_waitcnt lgkmcnt(0)
	v_add_f32_e32 v18, v18, v19
	ds_bpermute_b32 v19, v139, v18
	s_and_saveexec_b64 s[2:3], s[6:7]
	s_cbranch_execz .LBB0_56
	s_waitcnt lgkmcnt(0)
	v_add_f32_e32 v18, v18, v19
	v_mul_f32_e32 v18, 0x4b800000, v18
	v_trunc_f32_e32 v18, v18
	v_mul_f32_e32 v19, 0x2f800000, v18
	v_floor_f32_e32 v19, v19
	v_fmac_f32_e32 v18, 0xcf800000, v19
	v_cvt_u32_f32_e32 v18, v18
	v_cvt_u32_f32_e32 v19, v19
	global_atomic_add_x2 v[114:115], v[18:19], off offset:1280
.LBB0_56:
	s_or_b64 exec, exec, s[2:3]
	s_mov_b64 s[0:1], 0x58000
	s_waitcnt lgkmcnt(0)
	v_lshl_add_u64 v[18:19], v[134:135], 0, s[0:1]
	v_readlane_b32 s0, v255, 12
	v_readlane_b32 s1, v255, 13
	v_mul_f32_e32 v14, 0xbfb8aa3b, v14
	v_exp_f32_e32 v14, v14
	v_lshl_add_u64 v[20:21], s[0:1], 0, v[18:19]
	v_lshl_add_u64 v[20:21], v[130:131], 1, v[20:21]
	s_nop 1
	v_mov_b64_e32 v[188:189], v[246:247]
	v_mov_b64_e32 v[190:191], v[248:249]
	v_add_f32_e32 v14, 1.0, v14
	v_rcp_f32_e32 v14, v14
	v_mul_f32_e32 v10, 0xbfb8aa3b, v10
	v_exp_f32_e32 v10, v10
	v_mul_f32_e32 v6, 0xbfb8aa3b, v6
	v_exp_f32_e32 v6, v6
	v_mul_f32_e32 v2, 0xbfb8aa3b, v2
	v_add_f32_e32 v10, 1.0, v10
	v_rcp_f32_e32 v10, v10
	v_add_f32_e32 v6, 1.0, v6
	v_rcp_f32_e32 v6, v6
	v_exp_f32_e32 v2, v2
	v_lshlrev_b32_e32 v26, 16, v188
	v_mul_f32_e32 v29, v14, v26
	v_mul_f32_e32 v14, 0xbfb8aa3b, v15
	v_exp_f32_e32 v14, v14
	v_and_b32_e32 v15, 0xffff0000, v188
	v_add_f32_e32 v2, 1.0, v2
	v_rcp_f32_e32 v2, v2
	v_add_f32_e32 v14, 1.0, v14
	v_rcp_f32_e32 v14, v14
	s_nop 0
	v_mul_f32_e32 v28, v14, v15
	v_mul_f32_e32 v14, 0xbfb8aa3b, v16
	v_exp_f32_e32 v14, v14
	v_lshlrev_b32_e32 v15, 16, v189
	v_mul_f32_e32 v144, v28, v28
	v_fmac_f32_e32 v144, v29, v29
	v_add_f32_e32 v14, 1.0, v14
	v_rcp_f32_e32 v14, v14
	s_nop 0
	v_mul_f32_e32 v27, v14, v15
	v_mul_f32_e32 v14, 0xbfb8aa3b, v17
	v_exp_f32_e32 v14, v14
	v_and_b32_e32 v15, 0xffff0000, v189
	v_fmac_f32_e32 v144, v27, v27
	v_add_f32_e32 v14, 1.0, v14
	v_rcp_f32_e32 v14, v14
	s_nop 0
	v_mul_f32_e32 v26, v14, v15
	v_lshlrev_b32_e32 v14, 16, v190
	v_mul_f32_e32 v17, v10, v14
	v_mul_f32_e32 v10, 0xbfb8aa3b, v11
	v_exp_f32_e32 v10, v10
	v_and_b32_e32 v11, 0xffff0000, v190
	v_fmac_f32_e32 v144, v26, v26
	v_add_f32_e32 v10, 1.0, v10
	v_rcp_f32_e32 v10, v10
	s_nop 0
	v_mul_f32_e32 v16, v10, v11
	v_mul_f32_e32 v10, 0xbfb8aa3b, v12
	v_exp_f32_e32 v10, v10
	v_lshlrev_b32_e32 v11, 16, v191
	v_add_f32_e32 v10, 1.0, v10
	v_rcp_f32_e32 v10, v10
	s_nop 0
	v_mul_f32_e32 v15, v10, v11
	v_mul_f32_e32 v10, 0xbfb8aa3b, v13
	v_exp_f32_e32 v10, v10
	v_and_b32_e32 v11, 0xffff0000, v191
	v_add_f32_e32 v10, 1.0, v10
	v_rcp_f32_e32 v10, v10
	s_nop 0
	v_mul_f32_e32 v14, v10, v11
	v_mul_f32_e32 v10, v16, v16
	v_fmac_f32_e32 v10, v17, v17
	v_fmac_f32_e32 v10, v15, v15
	v_fmac_f32_e32 v10, v14, v14
	v_add_f32_e32 v144, v144, v10
	s_nop 1
	v_mov_b64_e32 v[10:11], v[180:181]
	v_mov_b64_e32 v[12:13], v[182:183]
	v_lshlrev_b32_e32 v20, 16, v10
	v_mul_f32_e32 v20, v6, v20
	v_mul_f32_e32 v6, 0xbfb8aa3b, v7
	v_exp_f32_e32 v6, v6
	v_and_b32_e32 v7, 0xffff0000, v10
	v_add_f32_e32 v6, 1.0, v6
	v_rcp_f32_e32 v6, v6
	s_nop 0
	v_mul_f32_e32 v10, v6, v7
	v_mul_f32_e32 v6, 0xbfb8aa3b, v8
	v_exp_f32_e32 v6, v6
	v_lshlrev_b32_e32 v7, 16, v11
	v_add_f32_e32 v6, 1.0, v6
	v_rcp_f32_e32 v6, v6
	s_nop 0
	v_mul_f32_e32 v8, v6, v7
	v_mul_f32_e32 v6, 0xbfb8aa3b, v9
	v_exp_f32_e32 v6, v6
	v_and_b32_e32 v7, 0xffff0000, v11
	v_add_f32_e32 v6, 1.0, v6
	v_rcp_f32_e32 v6, v6
	s_nop 0
	v_mul_f32_e32 v9, v6, v7
	v_lshlrev_b32_e32 v7, 16, v12
	v_mul_f32_e32 v11, v2, v7
	v_mul_f32_e32 v2, 0xbfb8aa3b, v3
	v_exp_f32_e32 v2, v2
	v_and_b32_e32 v3, 0xffff0000, v12
	v_mul_f32_e32 v6, v10, v10
	v_fmac_f32_e32 v6, v20, v20
	v_add_f32_e32 v2, 1.0, v2
	v_rcp_f32_e32 v2, v2
	v_fmac_f32_e32 v6, v8, v8
	v_fmac_f32_e32 v6, v9, v9
	v_add_f32_e32 v6, v144, v6
	v_mul_f32_e32 v21, v2, v3
	v_mul_f32_e32 v2, 0xbfb8aa3b, v4
	v_exp_f32_e32 v2, v2
	v_lshlrev_b32_e32 v3, 16, v13
	v_add_f32_e32 v2, 1.0, v2
	v_rcp_f32_e32 v2, v2
	s_nop 0
	v_mul_f32_e32 v12, v2, v3
	v_mul_f32_e32 v2, 0xbfb8aa3b, v5
	v_exp_f32_e32 v2, v2
	v_and_b32_e32 v3, 0xffff0000, v13
	v_add_f32_e32 v2, 1.0, v2
	v_rcp_f32_e32 v2, v2
	s_nop 0
	v_mul_f32_e32 v13, v2, v3
	v_mul_f32_e32 v2, v21, v21
	v_fmac_f32_e32 v2, v11, v11
	v_fmac_f32_e32 v2, v12, v12
	v_fmac_f32_e32 v2, v13, v13
	v_add_f32_e32 v2, v2, v6
	ds_bpermute_b32 v3, v138, v2
	s_waitcnt lgkmcnt(0)
	v_add_f32_e32 v2, v2, v3
	ds_bpermute_b32 v3, v139, v2
	s_and_saveexec_b64 s[2:3], s[6:7]
	s_cbranch_execz .LBB0_58
	s_waitcnt lgkmcnt(0)
	v_add_f32_e32 v2, v2, v3
	v_mul_f32_e32 v2, 0x4b800000, v2
	v_trunc_f32_e32 v2, v2
	v_mul_f32_e32 v3, 0x2f800000, v2
	v_floor_f32_e32 v3, v3
	v_fmac_f32_e32 v2, 0xcf800000, v3
	v_cvt_u32_f32_e32 v2, v2
	v_cvt_u32_f32_e32 v3, v3
	global_atomic_add_x2 v[114:115], v[2:3], off offset:1408

.LBB0_69:
	s_or_b64 exec, exec, s[2:3]
	s_barrier
	global_load_dwordx2 v[2:3], v[114:115], off sc1
	v_readlane_b32 s2, v255, 6
	s_add_i32 s0, s2, 1
	s_mul_hi_i32 s1, s0, 0x22000
	s_mul_i32 s0, s0, 0x22000
	s_add_u32 s0, s50, s0
	s_addc_u32 s1, s51, s1
	v_readlane_b32 s3, v255, 7
	s_add_u32 s20, s0, 0x2edf1000
	s_addc_u32 s21, s1, 0
	s_lshl_b64 s[0:1], s[2:3], 12
	s_add_u32 s18, s18, s0
	s_addc_u32 s19, s19, s1
	global_load_dwordx2 v[242:243], v[114:115], off offset:128 sc1
	global_load_dwordx2 v[244:245], v[114:115], off offset:256 sc1
	global_load_dwordx2 v[246:247], v[114:115], off offset:384 sc1
	global_load_dwordx2 v[248:249], v[114:115], off offset:1024 sc1
	global_load_dwordx2 v[180:181], v[114:115], off offset:1152 sc1
	global_load_dwordx2 v[182:183], v[114:115], off offset:1280 sc1
	global_load_dwordx2 v[172:173], v[114:115], off offset:1408 sc1
	v_lshl_add_u64 v[170:171], v[130:131], 2, s[18:19]
	global_load_dwordx4 v[196:199], v[170:171], off
	global_load_dwordx4 v[200:203], v[170:171], off offset:16
	global_load_dwordx4 v[204:207], v[170:171], off offset:512
	global_load_dwordx4 v[208:211], v[170:171], off offset:528
	s_mov_b64 s[98:99], s[94:95]
	global_load_dwordx4 v[188:191], v250, s[98:99]
	global_load_dwordx4 v[212:215], v250, s[98:99] offset:256
	s_add_u32 s98, s98, 0x8000
	s_addc_u32 s99, s99, 0
	global_load_dwordx4 v[218:221], v250, s[98:99]
	global_load_dwordx4 v[222:225], v250, s[98:99] offset:256
	s_add_u32 s98, s98, 0x8000
	s_addc_u32 s99, s99, 0
	global_load_dwordx4 v[226:229], v250, s[98:99]
	global_load_dwordx4 v[230:233], v250, s[98:99] offset:256
	s_add_u32 s98, s98, 0x8000
	s_addc_u32 s99, s99, 0
	global_load_dwordx4 v[234:237], v250, s[98:99]
	global_load_dwordx4 v[238:241], v250, s[98:99] offset:256
	s_waitcnt vmcnt(0)
	v_ffbh_u32_e32 v4, v3
	v_min_u32_e32 v4, 32, v4
	v_lshlrev_b64 v[2:3], v4, v[2:3]
	v_min_u32_e32 v2, 1, v2
	v_or_b32_e32 v2, v3, v2
	v_cvt_f32_u32_e32 v2, v2
	v_sub_u32_e32 v3, 32, v4
	v_ldexp_f32 v2, v2, v3
	v_fmamk_f32 v2, v2, 0x2e800000, v143
	v_cmp_gt_f32_e32 vcc, s90, v2
	v_mul_f32_e32 v3, 0x4b800000, v2
	s_nop 0
	v_cndmask_b32_e32 v2, v2, v3, vcc
	v_rsq_f32_e32 v2, v2
	s_nop 0
	v_mul_f32_e32 v3, 0x45800000, v2
	v_cndmask_b32_e32 v6, v2, v3, vcc
	v_lshl_add_u64 v[2:3], s[94:95], 0, v[134:135]
	v_lshl_add_u64 v[4:5], v[130:131], 1, v[2:3]
	v_lshl_add_u64 v[2:3], v[130:131], 2, s[18:19]
	s_nop 1
	v_mov_b64_e32 v[192:193], v[196:197]
	v_mov_b64_e32 v[194:195], v[198:199]
	v_mul_f32_e32 v134, v153, v6
	v_mul_f32_e32 v135, v141, v6
	v_mul_f32_e32 v140, v140, v6
	v_mul_f32_e32 v129, v129, v6
	v_mul_f32_e32 v128, v128, v6
	v_mul_f32_e32 v127, v127, v6
	v_mul_f32_e32 v126, v126, v6
	v_mul_f32_e32 v0, v0, v6
	v_mul_f32_e32 v122, v122, v6
	v_mul_f32_e32 v120, v120, v6
	v_lshlrev_b32_e32 v7, 16, v188
	v_fmac_f32_e32 v7, v192, v134
	v_and_b32_e32 v134, 0xffff0000, v188
	v_fmac_f32_e32 v134, v193, v135
	v_lshlrev_b32_e32 v135, 16, v189
	v_fmac_f32_e32 v135, v194, v140
	v_and_b32_e32 v140, 0xffff0000, v189
	v_fmac_f32_e32 v140, v195, v129
	v_cvt_pk_bf16_f32 v188, v7, v134
	v_cvt_pk_bf16_f32 v189, v135, v140
	s_nop 1
	v_mov_b64_e32 v[192:193], v[200:201]
	v_mov_b64_e32 v[194:195], v[202:203]
	v_mul_f32_e32 v129, v134, v134
	v_fmac_f32_e32 v129, v7, v7
	v_lshlrev_b32_e32 v7, 16, v190
	v_fmac_f32_e32 v129, v135, v135
	v_fmac_f32_e32 v129, v140, v140
	v_mul_f32_e32 v134, v136, v6
	v_fmac_f32_e32 v7, v192, v128
	v_and_b32_e32 v128, 0xffff0000, v190
	v_fmac_f32_e32 v128, v193, v127
	v_lshlrev_b32_e32 v127, 16, v191
	v_fmac_f32_e32 v127, v194, v126
	v_and_b32_e32 v126, 0xffff0000, v191
	v_fmac_f32_e32 v126, v195, v0
	v_mul_f32_e32 v0, v128, v128
	v_fmac_f32_e32 v0, v7, v7
	v_fmac_f32_e32 v0, v127, v127
	v_fmac_f32_e32 v0, v126, v126
	v_cvt_pk_bf16_f32 v190, v7, v128
	v_cvt_pk_bf16_f32 v191, v127, v126
	global_store_dwordx4 v[4:5], v[188:191], off
	v_add_f32_e32 v0, v129, v0
	s_nop 1
	v_mov_b64_e32 v[126:127], v[212:213]
	v_mov_b64_e32 v[128:129], v[214:215]
	s_nop 1
	v_mov_b64_e32 v[188:189], v[204:205]
	v_mov_b64_e32 v[190:191], v[206:207]
	v_lshlrev_b32_e32 v7, 16, v126
	v_and_b32_e32 v126, 0xffff0000, v126
	v_fmac_f32_e32 v126, v122, v189
	v_lshlrev_b32_e32 v122, 16, v127
	v_fmac_f32_e32 v122, v120, v190
	v_and_b32_e32 v120, 0xffff0000, v127
	v_mul_f32_e32 v127, v156, v6
	v_fmac_f32_e32 v7, v134, v188
	v_fmac_f32_e32 v120, v127, v191
	v_mul_f32_e32 v127, v126, v126
	v_fmac_f32_e32 v127, v7, v7
	v_fmac_f32_e32 v127, v122, v122
	v_fmac_f32_e32 v127, v120, v120
	v_add_f32_e32 v0, v0, v127
	v_cvt_pk_bf16_f32 v126, v7, v126
	v_cvt_pk_bf16_f32 v127, v122, v120
	s_nop 1
	v_mov_b64_e32 v[188:189], v[208:209]
	v_mov_b64_e32 v[190:191], v[210:211]
	v_lshlrev_b32_e32 v7, 16, v128
	v_mul_f32_e32 v120, v137, v6
	v_mul_f32_e32 v122, v155, v6
	v_fmac_f32_e32 v7, v120, v188
	v_and_b32_e32 v120, 0xffff0000, v128
	v_fmac_f32_e32 v120, v122, v189
	v_lshlrev_b32_e32 v122, 16, v129
	v_mul_f32_e32 v128, v154, v6
	v_and_b32_e32 v129, 0xffff0000, v129
	v_mul_f32_e32 v6, v157, v6
	v_fmac_f32_e32 v129, v6, v191
	v_mul_f32_e32 v6, v120, v120
	v_fmac_f32_e32 v122, v128, v190
	v_fmac_f32_e32 v6, v7, v7
	v_fmac_f32_e32 v6, v122, v122
	v_fmac_f32_e32 v6, v129, v129
	v_add_f32_e32 v0, v0, v6
	v_cvt_pk_bf16_f32 v128, v7, v120
	v_cvt_pk_bf16_f32 v129, v122, v129
	global_store_dwordx4 v[4:5], v[126:129], off offset:256
	ds_bpermute_b32 v4, v138, v0
	s_waitcnt lgkmcnt(0)
	v_add_f32_e32 v0, v0, v4
	ds_bpermute_b32 v6, v139, v0
	v_lshl_add_u64 v[4:5], v[132:133], 3, s[20:21]
	s_and_saveexec_b64 s[2:3], s[6:7]
	s_cbranch_execz .LBB0_71
	s_waitcnt lgkmcnt(0)
	v_add_f32_e32 v0, v0, v6
	v_mul_f32_e32 v0, 0x4b800000, v0
	v_trunc_f32_e32 v0, v0
	v_mul_f32_e32 v6, 0x2f800000, v0
	v_floor_f32_e32 v7, v6
	v_fmac_f32_e32 v0, 0xcf800000, v7
	v_cvt_u32_f32_e32 v6, v0
	v_cvt_u32_f32_e32 v7, v7
	global_atomic_add_x2 v[4:5], v[6:7], off
.LBB0_71:
	s_or_b64 exec, exec, s[2:3]
	s_waitcnt lgkmcnt(0)
	s_nop 1
	v_mov_b64_e32 v[6:7], v[242:243]
	v_ffbh_u32_e32 v0, v7
	v_min_u32_e32 v0, 32, v0
	v_lshlrev_b64 v[6:7], v0, v[6:7]
	v_min_u32_e32 v6, 1, v6
	v_or_b32_e32 v6, v7, v6
	v_cvt_f32_u32_e32 v6, v6
	v_sub_u32_e32 v0, 32, v0
	v_ldexp_f32 v0, v6, v0
	v_fmamk_f32 v0, v0, 0x2e800000, v143
	v_cmp_gt_f32_e32 vcc, s90, v0
	v_mul_f32_e32 v6, 0x4b800000, v0
	s_nop 0
	v_cndmask_b32_e32 v0, v0, v6, vcc
	v_rsq_f32_e32 v0, v0
	s_nop 0
	v_mul_f32_e32 v6, 0x45800000, v0
	v_cndmask_b32_e32 v0, v0, v6, vcc
	v_lshl_add_u64 v[6:7], s[94:95], 0, v[116:117]
	v_lshl_add_u64 v[6:7], v[130:131], 1, v[6:7]
	s_nop 1
	v_mov_b64_e32 v[126:127], v[218:219]
	v_mov_b64_e32 v[128:129], v[220:221]
	s_nop 1
	v_mov_b64_e32 v[132:133], v[196:197]
	v_mov_b64_e32 v[134:135], v[198:199]
	v_mul_f32_e32 v117, v125, v0
	v_mul_f32_e32 v120, v124, v0
	v_mul_f32_e32 v113, v113, v0
	v_mul_f32_e32 v112, v112, v0
	v_mul_f32_e32 v111, v111, v0
	v_mul_f32_e32 v110, v110, v0
	v_mul_f32_e32 v102, v102, v0
	v_mul_f32_e32 v103, v103, v0
	v_mul_f32_e32 v104, v104, v0
	v_mul_f32_e32 v105, v105, v0
	v_lshlrev_b32_e32 v116, 16, v126
	v_fmac_f32_e32 v116, v132, v117
	v_and_b32_e32 v117, 0xffff0000, v126
	v_fmac_f32_e32 v117, v133, v120
	v_lshlrev_b32_e32 v122, 16, v127
	v_mul_f32_e32 v120, v123, v0
	v_mul_f32_e32 v126, v117, v117
	v_fmac_f32_e32 v122, v134, v120
	v_and_b32_e32 v123, 0xffff0000, v127
	v_mul_f32_e32 v120, v121, v0
	v_fmac_f32_e32 v126, v116, v116
	v_fmac_f32_e32 v123, v135, v120
	v_fmac_f32_e32 v126, v122, v122
	v_fmac_f32_e32 v126, v123, v123
	v_cvt_pk_bf16_f32 v120, v116, v117
	v_cvt_pk_bf16_f32 v121, v122, v123
	s_nop 1
	v_mov_b64_e32 v[122:123], v[200:201]
	v_mov_b64_e32 v[124:125], v[202:203]
	v_lshlrev_b32_e32 v116, 16, v128
	v_fmac_f32_e32 v116, v122, v113
	v_and_b32_e32 v113, 0xffff0000, v128
	v_fmac_f32_e32 v113, v123, v112
	v_lshlrev_b32_e32 v112, 16, v129
	v_fmac_f32_e32 v112, v124, v111
	v_and_b32_e32 v111, 0xffff0000, v129
	v_fmac_f32_e32 v111, v125, v110
	v_mul_f32_e32 v110, v113, v113
	v_fmac_f32_e32 v110, v116, v116
	v_fmac_f32_e32 v110, v112, v112
	v_fmac_f32_e32 v110, v111, v111
	v_cvt_pk_bf16_f32 v122, v116, v113
	v_cvt_pk_bf16_f32 v123, v112, v111
	global_store_dwordx4 v[6:7], v[120:123], off
	v_add_f32_e32 v117, v126, v110
	s_nop 1
	v_mov_b64_e32 v[110:111], v[222:223]
	v_mov_b64_e32 v[112:113], v[224:225]
	s_nop 1
	v_mov_b64_e32 v[120:121], v[204:205]
	v_mov_b64_e32 v[122:123], v[206:207]
	v_lshlrev_b32_e32 v116, 16, v110
	v_fmac_f32_e32 v116, v102, v120
	v_and_b32_e32 v102, 0xffff0000, v110
	v_fmac_f32_e32 v102, v103, v121
	v_lshlrev_b32_e32 v103, 16, v111
	v_fmac_f32_e32 v103, v104, v122
	v_and_b32_e32 v104, 0xffff0000, v111
	v_fmac_f32_e32 v104, v105, v123
	v_mul_f32_e32 v105, v102, v102
	v_fmac_f32_e32 v105, v116, v116
	v_fmac_f32_e32 v105, v103, v103
	v_cvt_pk_bf16_f32 v102, v116, v102
	v_cvt_pk_bf16_f32 v103, v103, v104
	s_nop 1
	v_mov_b64_e32 v[120:121], v[208:209]
	v_mov_b64_e32 v[122:123], v[210:211]
	v_fmac_f32_e32 v105, v104, v104
	v_lshlrev_b32_e32 v104, 16, v112
	v_mul_f32_e32 v110, v118, v0
	v_mul_f32_e32 v111, v158, v0
	v_add_f32_e32 v105, v117, v105
	v_fmac_f32_e32 v104, v110, v120
	v_and_b32_e32 v110, 0xffff0000, v112
	v_fmac_f32_e32 v110, v111, v121
	v_lshlrev_b32_e32 v111, 16, v113
	v_mul_f32_e32 v112, v119, v0
	v_fmac_f32_e32 v111, v112, v122
	v_and_b32_e32 v112, 0xffff0000, v113
	v_mul_f32_e32 v0, v159, v0
	v_fmac_f32_e32 v112, v0, v123
	v_mul_f32_e32 v0, v110, v110
	v_fmac_f32_e32 v0, v104, v104
	v_fmac_f32_e32 v0, v111, v111
	v_fmac_f32_e32 v0, v112, v112
	v_add_f32_e32 v0, v105, v0
	v_cvt_pk_bf16_f32 v104, v104, v110
	v_cvt_pk_bf16_f32 v105, v111, v112
	global_store_dwordx4 v[6:7], v[102:105], off offset:256
	ds_bpermute_b32 v6, v138, v0
	s_waitcnt lgkmcnt(0)
	v_add_f32_e32 v0, v0, v6
	ds_bpermute_b32 v6, v139, v0
	s_and_saveexec_b64 s[2:3], s[6:7]
	s_cbranch_execz .LBB0_73
	s_waitcnt lgkmcnt(0)
	v_add_f32_e32 v0, v0, v6
	v_mul_f32_e32 v0, 0x4b800000, v0
	v_trunc_f32_e32 v0, v0
	v_mul_f32_e32 v6, 0x2f800000, v0
	v_floor_f32_e32 v7, v6
	v_fmac_f32_e32 v0, 0xcf800000, v7
	v_cvt_u32_f32_e32 v6, v0
	v_cvt_u32_f32_e32 v7, v7
	global_atomic_add_x2 v[4:5], v[6:7], off offset:128
.LBB0_73:
	s_or_b64 exec, exec, s[2:3]
	s_waitcnt lgkmcnt(0)
	s_nop 1
	v_mov_b64_e32 v[6:7], v[244:245]
	v_ffbh_u32_e32 v0, v7
	v_min_u32_e32 v0, 32, v0
	v_lshlrev_b64 v[6:7], v0, v[6:7]
	v_min_u32_e32 v6, 1, v6
	v_or_b32_e32 v6, v7, v6
	v_cvt_f32_u32_e32 v6, v6
	v_sub_u32_e32 v0, 32, v0
	v_ldexp_f32 v0, v6, v0
	v_fmamk_f32 v0, v0, 0x2e800000, v143
	v_cmp_gt_f32_e32 vcc, s90, v0
	v_mul_f32_e32 v6, 0x4b800000, v0
	s_nop 0
	v_cndmask_b32_e32 v0, v0, v6, vcc
	v_rsq_f32_e32 v0, v0
	s_nop 0
	v_mul_f32_e32 v6, 0x45800000, v0
	v_cndmask_b32_e32 v0, v0, v6, vcc
	v_lshl_add_u64 v[6:7], s[94:95], 0, v[98:99]
	v_lshl_add_u64 v[6:7], v[130:131], 1, v[6:7]
	s_nop 1
	v_mov_b64_e32 v[102:103], v[226:227]
	v_mov_b64_e32 v[104:105], v[228:229]
	s_nop 1
	v_mov_b64_e32 v[110:111], v[196:197]
	v_mov_b64_e32 v[112:113], v[198:199]
	v_mul_f32_e32 v99, v109, v0
	v_mul_f32_e32 v97, v97, v0
	v_mul_f32_e32 v96, v96, v0
	v_mul_f32_e32 v95, v95, v0
	v_mul_f32_e32 v94, v94, v0
	v_mul_f32_e32 v86, v86, v0
	v_mul_f32_e32 v87, v87, v0
	v_mul_f32_e32 v88, v88, v0
	v_mul_f32_e32 v89, v89, v0
	v_lshlrev_b32_e32 v98, 16, v102
	v_fmac_f32_e32 v98, v110, v99
	v_and_b32_e32 v99, 0xffff0000, v102
	v_mul_f32_e32 v102, v108, v0
	v_fmac_f32_e32 v99, v111, v102
	v_lshlrev_b32_e32 v108, 16, v103
	v_mul_f32_e32 v102, v107, v0
	v_mul_f32_e32 v110, v99, v99
	v_fmac_f32_e32 v108, v112, v102
	v_and_b32_e32 v103, 0xffff0000, v103
	v_mul_f32_e32 v102, v106, v0
	v_fmac_f32_e32 v110, v98, v98
	v_fmac_f32_e32 v103, v113, v102
	v_fmac_f32_e32 v110, v108, v108
	v_fmac_f32_e32 v110, v103, v103
	v_cvt_pk_bf16_f32 v102, v98, v99
	v_cvt_pk_bf16_f32 v103, v108, v103
	s_nop 1
	v_mov_b64_e32 v[106:107], v[200:201]
	v_mov_b64_e32 v[108:109], v[202:203]
	v_lshlrev_b32_e32 v98, 16, v104
	v_fmac_f32_e32 v98, v106, v97
	v_and_b32_e32 v97, 0xffff0000, v104
	v_fmac_f32_e32 v97, v107, v96
	v_lshlrev_b32_e32 v96, 16, v105
	v_fmac_f32_e32 v96, v108, v95
	v_and_b32_e32 v95, 0xffff0000, v105
	v_fmac_f32_e32 v95, v109, v94
	v_mul_f32_e32 v94, v97, v97
	v_fmac_f32_e32 v94, v98, v98
	v_fmac_f32_e32 v94, v96, v96
	v_fmac_f32_e32 v94, v95, v95
	v_cvt_pk_bf16_f32 v104, v98, v97
	v_cvt_pk_bf16_f32 v105, v96, v95
	global_store_dwordx4 v[6:7], v[102:105], off
	v_add_f32_e32 v99, v110, v94
	s_nop 1
	v_mov_b64_e32 v[94:95], v[230:231]
	v_mov_b64_e32 v[96:97], v[232:233]
	s_nop 1
	v_mov_b64_e32 v[102:103], v[204:205]
	v_mov_b64_e32 v[104:105], v[206:207]
	v_lshlrev_b32_e32 v98, 16, v94
	v_fmac_f32_e32 v98, v86, v102
	v_and_b32_e32 v86, 0xffff0000, v94
	v_fmac_f32_e32 v86, v87, v103
	v_lshlrev_b32_e32 v87, 16, v95
	v_fmac_f32_e32 v87, v88, v104
	v_and_b32_e32 v88, 0xffff0000, v95
	v_fmac_f32_e32 v88, v89, v105
	v_mul_f32_e32 v89, v86, v86
	v_fmac_f32_e32 v89, v98, v98
	v_fmac_f32_e32 v89, v87, v87
	v_cvt_pk_bf16_f32 v86, v98, v86
	v_cvt_pk_bf16_f32 v87, v87, v88
	s_nop 1
	v_mov_b64_e32 v[102:103], v[208:209]
	v_mov_b64_e32 v[104:105], v[210:211]
	v_fmac_f32_e32 v89, v88, v88
	v_lshlrev_b32_e32 v88, 16, v96
	v_mul_f32_e32 v94, v100, v0
	v_mul_f32_e32 v95, v160, v0
	v_add_f32_e32 v89, v99, v89
	v_fmac_f32_e32 v88, v94, v102
	v_and_b32_e32 v94, 0xffff0000, v96
	v_fmac_f32_e32 v94, v95, v103
	v_lshlrev_b32_e32 v95, 16, v97
	v_mul_f32_e32 v96, v101, v0
	v_fmac_f32_e32 v95, v96, v104
	v_and_b32_e32 v96, 0xffff0000, v97
	v_mul_f32_e32 v0, v161, v0
	v_fmac_f32_e32 v96, v0, v105
	v_mul_f32_e32 v0, v94, v94
	v_fmac_f32_e32 v0, v88, v88
	v_fmac_f32_e32 v0, v95, v95
	v_fmac_f32_e32 v0, v96, v96
	v_add_f32_e32 v0, v89, v0
	v_cvt_pk_bf16_f32 v88, v88, v94
	v_cvt_pk_bf16_f32 v89, v95, v96
	global_store_dwordx4 v[6:7], v[86:89], off offset:256
	ds_bpermute_b32 v6, v138, v0
	s_waitcnt lgkmcnt(0)
	v_add_f32_e32 v0, v0, v6
	ds_bpermute_b32 v6, v139, v0
	s_and_saveexec_b64 s[2:3], s[6:7]
	s_cbranch_execz .LBB0_75
	s_waitcnt lgkmcnt(0)
	v_add_f32_e32 v0, v0, v6
	v_mul_f32_e32 v0, 0x4b800000, v0
	v_trunc_f32_e32 v0, v0
	v_mul_f32_e32 v6, 0x2f800000, v0
	v_floor_f32_e32 v7, v6
	v_fmac_f32_e32 v0, 0xcf800000, v7
	v_cvt_u32_f32_e32 v6, v0
	v_cvt_u32_f32_e32 v7, v7
	global_atomic_add_x2 v[4:5], v[6:7], off offset:256
.LBB0_75:
	s_or_b64 exec, exec, s[2:3]
	s_waitcnt lgkmcnt(0)
	s_nop 1
	v_mov_b64_e32 v[6:7], v[246:247]
	v_ffbh_u32_e32 v0, v7
	v_min_u32_e32 v0, 32, v0
	v_lshlrev_b64 v[6:7], v0, v[6:7]
	v_min_u32_e32 v6, 1, v6
	v_or_b32_e32 v6, v7, v6
	v_cvt_f32_u32_e32 v6, v6
	v_sub_u32_e32 v0, 32, v0
	v_ldexp_f32 v0, v6, v0
	v_fmamk_f32 v0, v0, 0x2e800000, v143
	v_cmp_gt_f32_e32 vcc, s90, v0
	v_mul_f32_e32 v6, 0x4b800000, v0
	s_nop 0
	v_cndmask_b32_e32 v0, v0, v6, vcc
	v_rsq_f32_e32 v0, v0
	s_nop 0
	v_mul_f32_e32 v6, 0x45800000, v0
	v_cndmask_b32_e32 v0, v0, v6, vcc
	v_lshl_add_u64 v[6:7], s[94:95], 0, v[82:83]
	v_lshl_add_u64 v[6:7], v[130:131], 1, v[6:7]
	s_nop 1
	v_mov_b64_e32 v[86:87], v[234:235]
	v_mov_b64_e32 v[88:89], v[236:237]
	s_nop 1
	v_mov_b64_e32 v[94:95], v[196:197]
	v_mov_b64_e32 v[96:97], v[198:199]
	v_mul_f32_e32 v83, v93, v0
	v_mul_f32_e32 v81, v81, v0
	v_mul_f32_e32 v80, v80, v0
	v_mul_f32_e32 v79, v79, v0
	v_mul_f32_e32 v78, v78, v0
	v_mul_f32_e32 v70, v70, v0
	v_mul_f32_e32 v71, v71, v0
	v_mul_f32_e32 v72, v72, v0
	v_mul_f32_e32 v73, v73, v0
	v_lshlrev_b32_e32 v82, 16, v86
	v_fmac_f32_e32 v82, v94, v83
	v_and_b32_e32 v83, 0xffff0000, v86
	v_mul_f32_e32 v86, v92, v0
	v_fmac_f32_e32 v83, v95, v86
	v_lshlrev_b32_e32 v92, 16, v87
	v_mul_f32_e32 v86, v91, v0
	v_mul_f32_e32 v94, v83, v83
	v_fmac_f32_e32 v92, v96, v86
	v_and_b32_e32 v87, 0xffff0000, v87
	v_mul_f32_e32 v86, v90, v0
	v_fmac_f32_e32 v94, v82, v82
	v_fmac_f32_e32 v87, v97, v86
	v_fmac_f32_e32 v94, v92, v92
	v_fmac_f32_e32 v94, v87, v87
	v_cvt_pk_bf16_f32 v86, v82, v83
	v_cvt_pk_bf16_f32 v87, v92, v87
	s_nop 1
	v_mov_b64_e32 v[90:91], v[200:201]
	v_mov_b64_e32 v[92:93], v[202:203]
	v_lshlrev_b32_e32 v82, 16, v88
	v_fmac_f32_e32 v82, v90, v81
	v_and_b32_e32 v81, 0xffff0000, v88
	v_fmac_f32_e32 v81, v91, v80
	v_lshlrev_b32_e32 v80, 16, v89
	v_fmac_f32_e32 v80, v92, v79
	v_and_b32_e32 v79, 0xffff0000, v89
	v_fmac_f32_e32 v79, v93, v78
	v_mul_f32_e32 v78, v81, v81
	v_fmac_f32_e32 v78, v82, v82
	v_fmac_f32_e32 v78, v80, v80
	v_fmac_f32_e32 v78, v79, v79
	v_cvt_pk_bf16_f32 v88, v82, v81
	v_cvt_pk_bf16_f32 v89, v80, v79
	global_store_dwordx4 v[6:7], v[86:89], off
	v_add_f32_e32 v83, v94, v78
	s_nop 1
	v_mov_b64_e32 v[78:79], v[238:239]
	v_mov_b64_e32 v[80:81], v[240:241]
	s_nop 1
	v_mov_b64_e32 v[86:87], v[204:205]
	v_mov_b64_e32 v[88:89], v[206:207]
	v_lshlrev_b32_e32 v82, 16, v78
	v_fmac_f32_e32 v82, v70, v86
	v_and_b32_e32 v70, 0xffff0000, v78
	v_fmac_f32_e32 v70, v71, v87
	v_lshlrev_b32_e32 v71, 16, v79
	v_fmac_f32_e32 v71, v72, v88
	v_and_b32_e32 v72, 0xffff0000, v79
	v_fmac_f32_e32 v72, v73, v89
	v_mul_f32_e32 v73, v70, v70
	v_fmac_f32_e32 v73, v82, v82
	v_fmac_f32_e32 v73, v71, v71
	v_cvt_pk_bf16_f32 v70, v82, v70
	v_cvt_pk_bf16_f32 v71, v71, v72
	s_nop 1
	v_mov_b64_e32 v[86:87], v[208:209]
	v_mov_b64_e32 v[88:89], v[210:211]
	v_fmac_f32_e32 v73, v72, v72
	v_lshlrev_b32_e32 v72, 16, v80
	v_mul_f32_e32 v78, v84, v0
	v_mul_f32_e32 v79, v162, v0
	v_add_f32_e32 v73, v83, v73
	v_fmac_f32_e32 v72, v78, v86
	v_and_b32_e32 v78, 0xffff0000, v80
	v_fmac_f32_e32 v78, v79, v87
	v_lshlrev_b32_e32 v79, 16, v81
	v_mul_f32_e32 v80, v85, v0
	v_fmac_f32_e32 v79, v80, v88
	v_and_b32_e32 v80, 0xffff0000, v81
	v_mul_f32_e32 v0, v163, v0
	v_fmac_f32_e32 v80, v0, v89
	v_mul_f32_e32 v0, v78, v78
	v_fmac_f32_e32 v0, v72, v72
	v_fmac_f32_e32 v0, v79, v79
	v_fmac_f32_e32 v0, v80, v80
	v_add_f32_e32 v0, v73, v0
	v_cvt_pk_bf16_f32 v72, v72, v78
	v_cvt_pk_bf16_f32 v73, v79, v80
	global_store_dwordx4 v[6:7], v[70:73], off offset:256
	s_mov_b64 s[98:99], s[94:95]
	s_add_u32 s98, s98, 0x40000
	s_addc_u32 s99, s99, 0
	global_load_dwordx4 v[188:191], v250, s[98:99]
	global_load_dwordx4 v[212:215], v250, s[98:99] offset:256
	s_add_u32 s98, s98, 0x8000
	s_addc_u32 s99, s99, 0
	global_load_dwordx4 v[218:221], v250, s[98:99]
	global_load_dwordx4 v[222:225], v250, s[98:99] offset:256
	s_add_u32 s98, s98, 0x8000
	s_addc_u32 s99, s99, 0
	global_load_dwordx4 v[226:229], v250, s[98:99]
	global_load_dwordx4 v[230:233], v250, s[98:99] offset:256
	s_add_u32 s98, s98, 0x8000
	s_addc_u32 s99, s99, 0
	global_load_dwordx4 v[234:237], v250, s[98:99]
	global_load_dwordx4 v[238:241], v250, s[98:99] offset:256
	s_waitcnt vmcnt(0)
	ds_bpermute_b32 v6, v138, v0
	s_waitcnt lgkmcnt(0)
	v_add_f32_e32 v0, v0, v6
	ds_bpermute_b32 v6, v139, v0
	s_and_saveexec_b64 s[2:3], s[6:7]
	s_cbranch_execz .LBB0_77
	s_waitcnt lgkmcnt(0)
	v_add_f32_e32 v0, v0, v6
	v_mul_f32_e32 v0, 0x4b800000, v0
	v_trunc_f32_e32 v0, v0
	v_mul_f32_e32 v6, 0x2f800000, v0
	v_floor_f32_e32 v7, v6
	v_fmac_f32_e32 v0, 0xcf800000, v7
	v_cvt_u32_f32_e32 v6, v0
	v_cvt_u32_f32_e32 v7, v7
	global_atomic_add_x2 v[4:5], v[6:7], off offset:384
.LBB0_77:
	s_or_b64 exec, exec, s[2:3]
	s_waitcnt lgkmcnt(0)
	s_nop 1
	v_mov_b64_e32 v[6:7], v[248:249]
	v_ffbh_u32_e32 v0, v7
	v_min_u32_e32 v0, 32, v0
	v_lshlrev_b64 v[6:7], v0, v[6:7]
	v_min_u32_e32 v6, 1, v6
	v_or_b32_e32 v6, v7, v6
	v_cvt_f32_u32_e32 v6, v6
	v_sub_u32_e32 v0, 32, v0
	v_ldexp_f32 v0, v6, v0
	v_fmamk_f32 v0, v0, 0x2e800000, v143
	v_cmp_gt_f32_e32 vcc, s90, v0
	v_mul_f32_e32 v6, 0x4b800000, v0
	s_nop 0
	v_cndmask_b32_e32 v0, v0, v6, vcc
	v_rsq_f32_e32 v0, v0
	s_nop 0
	v_mul_f32_e32 v6, 0x45800000, v0
	v_cndmask_b32_e32 v0, v0, v6, vcc
	v_lshl_add_u64 v[6:7], s[94:95], 0, v[66:67]
	v_lshl_add_u64 v[6:7], v[130:131], 1, v[6:7]
	s_nop 1
	v_mov_b64_e32 v[70:71], v[188:189]
	v_mov_b64_e32 v[72:73], v[190:191]
	s_nop 1
	v_mov_b64_e32 v[78:79], v[196:197]
	v_mov_b64_e32 v[80:81], v[198:199]
	v_mul_f32_e32 v67, v77, v0
	v_mul_f32_e32 v65, v65, v0
	v_mul_f32_e32 v64, v64, v0
	v_mul_f32_e32 v63, v63, v0
	v_mul_f32_e32 v62, v62, v0
	v_mul_f32_e32 v54, v54, v0
	v_mul_f32_e32 v55, v55, v0
	v_mul_f32_e32 v56, v56, v0
	v_mul_f32_e32 v57, v57, v0
	v_lshlrev_b32_e32 v66, 16, v70
	v_fmac_f32_e32 v66, v78, v67
	v_and_b32_e32 v67, 0xffff0000, v70
	v_mul_f32_e32 v70, v76, v0
	v_fmac_f32_e32 v67, v79, v70
	v_lshlrev_b32_e32 v76, 16, v71
	v_mul_f32_e32 v70, v75, v0
	v_mul_f32_e32 v78, v67, v67
	v_fmac_f32_e32 v76, v80, v70
	v_and_b32_e32 v71, 0xffff0000, v71
	v_mul_f32_e32 v70, v74, v0
	v_fmac_f32_e32 v78, v66, v66
	v_fmac_f32_e32 v71, v81, v70
	v_fmac_f32_e32 v78, v76, v76
	v_fmac_f32_e32 v78, v71, v71
	v_cvt_pk_bf16_f32 v70, v66, v67
	v_cvt_pk_bf16_f32 v71, v76, v71
	s_nop 1
	v_mov_b64_e32 v[74:75], v[200:201]
	v_mov_b64_e32 v[76:77], v[202:203]
	v_lshlrev_b32_e32 v66, 16, v72
	v_fmac_f32_e32 v66, v74, v65
	v_and_b32_e32 v65, 0xffff0000, v72
	v_fmac_f32_e32 v65, v75, v64
	v_lshlrev_b32_e32 v64, 16, v73
	v_fmac_f32_e32 v64, v76, v63
	v_and_b32_e32 v63, 0xffff0000, v73
	v_fmac_f32_e32 v63, v77, v62
	v_mul_f32_e32 v62, v65, v65
	v_fmac_f32_e32 v62, v66, v66
	v_fmac_f32_e32 v62, v64, v64
	v_fmac_f32_e32 v62, v63, v63
	v_cvt_pk_bf16_f32 v72, v66, v65
	v_cvt_pk_bf16_f32 v73, v64, v63
	global_store_dwordx4 v[6:7], v[70:73], off
	v_add_f32_e32 v67, v78, v62
	s_nop 1
	v_mov_b64_e32 v[62:63], v[212:213]
	v_mov_b64_e32 v[64:65], v[214:215]
	s_nop 1
	v_mov_b64_e32 v[70:71], v[204:205]
	v_mov_b64_e32 v[72:73], v[206:207]
	v_lshlrev_b32_e32 v66, 16, v62
	v_fmac_f32_e32 v66, v54, v70
	v_and_b32_e32 v54, 0xffff0000, v62
	v_fmac_f32_e32 v54, v55, v71
	v_lshlrev_b32_e32 v55, 16, v63
	v_fmac_f32_e32 v55, v56, v72
	v_and_b32_e32 v56, 0xffff0000, v63
	v_fmac_f32_e32 v56, v57, v73
	v_mul_f32_e32 v57, v54, v54
	v_fmac_f32_e32 v57, v66, v66
	v_fmac_f32_e32 v57, v55, v55
	v_cvt_pk_bf16_f32 v54, v66, v54
	v_cvt_pk_bf16_f32 v55, v55, v56
	s_nop 1
	v_mov_b64_e32 v[70:71], v[208:209]
	v_mov_b64_e32 v[72:73], v[210:211]
	v_fmac_f32_e32 v57, v56, v56
	v_lshlrev_b32_e32 v56, 16, v64
	v_mul_f32_e32 v62, v68, v0
	v_mul_f32_e32 v63, v164, v0
	v_add_f32_e32 v57, v67, v57
	v_fmac_f32_e32 v56, v62, v70
	v_and_b32_e32 v62, 0xffff0000, v64
	v_fmac_f32_e32 v62, v63, v71
	v_lshlrev_b32_e32 v63, 16, v65
	v_mul_f32_e32 v64, v69, v0
	v_fmac_f32_e32 v63, v64, v72
	v_and_b32_e32 v64, 0xffff0000, v65
	v_mul_f32_e32 v0, v165, v0
	v_fmac_f32_e32 v64, v0, v73
	v_mul_f32_e32 v0, v62, v62
	v_fmac_f32_e32 v0, v56, v56
	v_fmac_f32_e32 v0, v63, v63
	v_fmac_f32_e32 v0, v64, v64
	v_add_f32_e32 v0, v57, v0
	v_cvt_pk_bf16_f32 v56, v56, v62
	v_cvt_pk_bf16_f32 v57, v63, v64
	global_store_dwordx4 v[6:7], v[54:57], off offset:256
	ds_bpermute_b32 v6, v138, v0
	s_waitcnt lgkmcnt(0)
	v_add_f32_e32 v0, v0, v6
	ds_bpermute_b32 v6, v139, v0
	s_and_saveexec_b64 s[2:3], s[6:7]
	s_cbranch_execz .LBB0_79
	s_waitcnt lgkmcnt(0)
	v_add_f32_e32 v0, v0, v6
	v_mul_f32_e32 v0, 0x4b800000, v0
	v_trunc_f32_e32 v0, v0
	v_mul_f32_e32 v6, 0x2f800000, v0
	v_floor_f32_e32 v7, v6
	v_fmac_f32_e32 v0, 0xcf800000, v7
	v_cvt_u32_f32_e32 v6, v0
	v_cvt_u32_f32_e32 v7, v7
	global_atomic_add_x2 v[4:5], v[6:7], off offset:1024
.LBB0_79:
	s_or_b64 exec, exec, s[2:3]
	s_waitcnt lgkmcnt(0)
	s_nop 1
	v_mov_b64_e32 v[6:7], v[180:181]
	v_ffbh_u32_e32 v0, v7
	v_min_u32_e32 v0, 32, v0
	v_lshlrev_b64 v[6:7], v0, v[6:7]
	v_min_u32_e32 v6, 1, v6
	v_or_b32_e32 v6, v7, v6
	v_cvt_f32_u32_e32 v6, v6
	v_sub_u32_e32 v0, 32, v0
	v_ldexp_f32 v0, v6, v0
	v_fmamk_f32 v0, v0, 0x2e800000, v143
	v_cmp_gt_f32_e32 vcc, s90, v0
	v_mul_f32_e32 v6, 0x4b800000, v0
	s_nop 0
	v_cndmask_b32_e32 v0, v0, v6, vcc
	v_rsq_f32_e32 v0, v0
	s_nop 0
	v_mul_f32_e32 v6, 0x45800000, v0
	v_cndmask_b32_e32 v0, v0, v6, vcc
	v_lshl_add_u64 v[6:7], s[94:95], 0, v[50:51]
	v_lshl_add_u64 v[6:7], v[130:131], 1, v[6:7]
	s_nop 1
	v_mov_b64_e32 v[54:55], v[218:219]
	v_mov_b64_e32 v[56:57], v[220:221]
	s_nop 1
	v_mov_b64_e32 v[62:63], v[196:197]
	v_mov_b64_e32 v[64:65], v[198:199]
	v_mul_f32_e32 v51, v61, v0
	v_mul_f32_e32 v49, v49, v0
	v_mul_f32_e32 v48, v48, v0
	v_mul_f32_e32 v47, v47, v0
	v_mul_f32_e32 v46, v46, v0
	v_mul_f32_e32 v38, v38, v0
	v_mul_f32_e32 v39, v39, v0
	v_mul_f32_e32 v40, v40, v0
	v_mul_f32_e32 v41, v41, v0
	v_lshlrev_b32_e32 v50, 16, v54
	v_fmac_f32_e32 v50, v62, v51
	v_and_b32_e32 v51, 0xffff0000, v54
	v_mul_f32_e32 v54, v60, v0
	v_fmac_f32_e32 v51, v63, v54
	v_lshlrev_b32_e32 v60, 16, v55
	v_mul_f32_e32 v54, v59, v0
	v_mul_f32_e32 v62, v51, v51
	v_fmac_f32_e32 v60, v64, v54
	v_and_b32_e32 v55, 0xffff0000, v55
	v_mul_f32_e32 v54, v58, v0
	v_fmac_f32_e32 v62, v50, v50
	v_fmac_f32_e32 v55, v65, v54
	v_fmac_f32_e32 v62, v60, v60
	v_fmac_f32_e32 v62, v55, v55
	v_cvt_pk_bf16_f32 v54, v50, v51
	v_cvt_pk_bf16_f32 v55, v60, v55
	s_nop 1
	v_mov_b64_e32 v[58:59], v[200:201]
	v_mov_b64_e32 v[60:61], v[202:203]
	v_lshlrev_b32_e32 v50, 16, v56
	v_fmac_f32_e32 v50, v58, v49
	v_and_b32_e32 v49, 0xffff0000, v56
	v_fmac_f32_e32 v49, v59, v48
	v_lshlrev_b32_e32 v48, 16, v57
	v_fmac_f32_e32 v48, v60, v47
	v_and_b32_e32 v47, 0xffff0000, v57
	v_fmac_f32_e32 v47, v61, v46
	v_mul_f32_e32 v46, v49, v49
	v_fmac_f32_e32 v46, v50, v50
	v_fmac_f32_e32 v46, v48, v48
	v_fmac_f32_e32 v46, v47, v47
	v_cvt_pk_bf16_f32 v56, v50, v49
	v_cvt_pk_bf16_f32 v57, v48, v47
	global_store_dwordx4 v[6:7], v[54:57], off
	v_add_f32_e32 v51, v62, v46
	s_nop 1
	v_mov_b64_e32 v[46:47], v[222:223]
	v_mov_b64_e32 v[48:49], v[224:225]
	s_nop 1
	v_mov_b64_e32 v[54:55], v[204:205]
	v_mov_b64_e32 v[56:57], v[206:207]
	v_lshlrev_b32_e32 v50, 16, v46
	v_fmac_f32_e32 v50, v38, v54
	v_and_b32_e32 v38, 0xffff0000, v46
	v_fmac_f32_e32 v38, v39, v55
	v_lshlrev_b32_e32 v39, 16, v47
	v_fmac_f32_e32 v39, v40, v56
	v_and_b32_e32 v40, 0xffff0000, v47
	v_fmac_f32_e32 v40, v41, v57
	v_mul_f32_e32 v41, v38, v38
	v_fmac_f32_e32 v41, v50, v50
	v_fmac_f32_e32 v41, v39, v39
	v_cvt_pk_bf16_f32 v38, v50, v38
	v_cvt_pk_bf16_f32 v39, v39, v40
	s_nop 1
	v_mov_b64_e32 v[54:55], v[208:209]
	v_mov_b64_e32 v[56:57], v[210:211]
	v_fmac_f32_e32 v41, v40, v40
	v_lshlrev_b32_e32 v40, 16, v48
	v_mul_f32_e32 v46, v52, v0
	v_mul_f32_e32 v47, v166, v0
	v_add_f32_e32 v41, v51, v41
	v_fmac_f32_e32 v40, v46, v54
	v_and_b32_e32 v46, 0xffff0000, v48
	v_fmac_f32_e32 v46, v47, v55
	v_lshlrev_b32_e32 v47, 16, v49
	v_mul_f32_e32 v48, v53, v0
	v_fmac_f32_e32 v47, v48, v56
	v_and_b32_e32 v48, 0xffff0000, v49
	v_mul_f32_e32 v0, v167, v0
	v_fmac_f32_e32 v48, v0, v57
	v_mul_f32_e32 v0, v46, v46
	v_fmac_f32_e32 v0, v40, v40
	v_fmac_f32_e32 v0, v47, v47
	v_fmac_f32_e32 v0, v48, v48
	v_add_f32_e32 v0, v41, v0
	v_cvt_pk_bf16_f32 v40, v40, v46
	v_cvt_pk_bf16_f32 v41, v47, v48
	global_store_dwordx4 v[6:7], v[38:41], off offset:256
	ds_bpermute_b32 v6, v138, v0
	s_waitcnt lgkmcnt(0)
	v_add_f32_e32 v0, v0, v6
	ds_bpermute_b32 v6, v139, v0
	s_and_saveexec_b64 s[2:3], s[6:7]
	s_cbranch_execz .LBB0_81
	s_waitcnt lgkmcnt(0)
	v_add_f32_e32 v0, v0, v6
	v_mul_f32_e32 v0, 0x4b800000, v0
	v_trunc_f32_e32 v0, v0
	v_mul_f32_e32 v6, 0x2f800000, v0
	v_floor_f32_e32 v7, v6
	v_fmac_f32_e32 v0, 0xcf800000, v7
	v_cvt_u32_f32_e32 v6, v0
	v_cvt_u32_f32_e32 v7, v7
	global_atomic_add_x2 v[4:5], v[6:7], off offset:1152
.LBB0_81:
	s_or_b64 exec, exec, s[2:3]
	s_waitcnt lgkmcnt(0)
	s_nop 1
	v_mov_b64_e32 v[6:7], v[182:183]
	v_ffbh_u32_e32 v0, v7
	v_min_u32_e32 v0, 32, v0
	v_lshlrev_b64 v[6:7], v0, v[6:7]
	v_min_u32_e32 v6, 1, v6
	v_or_b32_e32 v6, v7, v6
	v_cvt_f32_u32_e32 v6, v6
	v_sub_u32_e32 v0, 32, v0
	v_ldexp_f32 v0, v6, v0
	v_fmamk_f32 v0, v0, 0x2e800000, v143
	v_cmp_gt_f32_e32 vcc, s90, v0
	v_mul_f32_e32 v6, 0x4b800000, v0
	s_nop 0
	v_cndmask_b32_e32 v0, v0, v6, vcc
	v_rsq_f32_e32 v0, v0
	s_nop 0
	v_mul_f32_e32 v6, 0x45800000, v0
	v_cndmask_b32_e32 v0, v0, v6, vcc
	v_lshl_add_u64 v[6:7], s[94:95], 0, v[34:35]
	v_lshl_add_u64 v[6:7], v[130:131], 1, v[6:7]
	s_nop 1
	v_mov_b64_e32 v[38:39], v[226:227]
	v_mov_b64_e32 v[40:41], v[228:229]
	s_nop 1
	v_mov_b64_e32 v[46:47], v[196:197]
	v_mov_b64_e32 v[48:49], v[198:199]
	v_mul_f32_e32 v35, v45, v0
	v_mul_f32_e32 v33, v33, v0
	v_mul_f32_e32 v32, v32, v0
	v_mul_f32_e32 v31, v31, v0
	v_mul_f32_e32 v30, v30, v0
	v_mul_f32_e32 v22, v22, v0
	v_mul_f32_e32 v23, v23, v0
	v_mul_f32_e32 v24, v24, v0
	v_mul_f32_e32 v25, v25, v0
	v_lshlrev_b32_e32 v34, 16, v38
	v_fmac_f32_e32 v34, v46, v35
	v_and_b32_e32 v35, 0xffff0000, v38
	v_mul_f32_e32 v38, v44, v0
	v_fmac_f32_e32 v35, v47, v38
	v_lshlrev_b32_e32 v44, 16, v39
	v_mul_f32_e32 v38, v43, v0
	v_mul_f32_e32 v46, v35, v35
	v_fmac_f32_e32 v44, v48, v38
	v_and_b32_e32 v39, 0xffff0000, v39
	v_mul_f32_e32 v38, v42, v0
	v_fmac_f32_e32 v46, v34, v34
	v_fmac_f32_e32 v39, v49, v38
	v_fmac_f32_e32 v46, v44, v44
	v_fmac_f32_e32 v46, v39, v39
	v_cvt_pk_bf16_f32 v38, v34, v35
	v_cvt_pk_bf16_f32 v39, v44, v39
	s_nop 1
	v_mov_b64_e32 v[42:43], v[200:201]
	v_mov_b64_e32 v[44:45], v[202:203]
	v_lshlrev_b32_e32 v34, 16, v40
	v_fmac_f32_e32 v34, v42, v33
	v_and_b32_e32 v33, 0xffff0000, v40
	v_fmac_f32_e32 v33, v43, v32
	v_lshlrev_b32_e32 v32, 16, v41
	v_fmac_f32_e32 v32, v44, v31
	v_and_b32_e32 v31, 0xffff0000, v41
	v_fmac_f32_e32 v31, v45, v30
	v_mul_f32_e32 v30, v33, v33
	v_fmac_f32_e32 v30, v34, v34
	v_fmac_f32_e32 v30, v32, v32
	v_fmac_f32_e32 v30, v31, v31
	v_cvt_pk_bf16_f32 v40, v34, v33
	v_cvt_pk_bf16_f32 v41, v32, v31
	global_store_dwordx4 v[6:7], v[38:41], off
	v_add_f32_e32 v35, v46, v30
	s_nop 1
	v_mov_b64_e32 v[30:31], v[230:231]
	v_mov_b64_e32 v[32:33], v[232:233]
	s_nop 1
	v_mov_b64_e32 v[38:39], v[204:205]
	v_mov_b64_e32 v[40:41], v[206:207]
	v_lshlrev_b32_e32 v34, 16, v30
	v_fmac_f32_e32 v34, v22, v38
	v_and_b32_e32 v22, 0xffff0000, v30
	v_fmac_f32_e32 v22, v23, v39
	v_lshlrev_b32_e32 v23, 16, v31
	v_fmac_f32_e32 v23, v24, v40
	v_and_b32_e32 v24, 0xffff0000, v31
	v_fmac_f32_e32 v24, v25, v41
	v_mul_f32_e32 v25, v22, v22
	v_fmac_f32_e32 v25, v34, v34
	v_fmac_f32_e32 v25, v23, v23
	v_cvt_pk_bf16_f32 v22, v34, v22
	v_cvt_pk_bf16_f32 v23, v23, v24
	s_nop 1
	v_mov_b64_e32 v[38:39], v[208:209]
	v_mov_b64_e32 v[40:41], v[210:211]
	v_fmac_f32_e32 v25, v24, v24
	v_lshlrev_b32_e32 v24, 16, v32
	v_mul_f32_e32 v30, v36, v0
	v_mul_f32_e32 v31, v168, v0
	v_add_f32_e32 v25, v35, v25
	v_fmac_f32_e32 v24, v30, v38
	v_and_b32_e32 v30, 0xffff0000, v32
	v_fmac_f32_e32 v30, v31, v39
	v_lshlrev_b32_e32 v31, 16, v33
	v_mul_f32_e32 v32, v37, v0
	v_fmac_f32_e32 v31, v32, v40
	v_and_b32_e32 v32, 0xffff0000, v33
	v_mul_f32_e32 v0, v169, v0
	v_fmac_f32_e32 v32, v0, v41
	v_mul_f32_e32 v0, v30, v30
	v_fmac_f32_e32 v0, v24, v24
	v_fmac_f32_e32 v0, v31, v31
	v_fmac_f32_e32 v0, v32, v32
	v_add_f32_e32 v0, v25, v0
	v_cvt_pk_bf16_f32 v24, v24, v30
	v_cvt_pk_bf16_f32 v25, v31, v32
	global_store_dwordx4 v[6:7], v[22:25], off offset:256
	ds_bpermute_b32 v6, v138, v0
	s_waitcnt lgkmcnt(0)
	v_add_f32_e32 v0, v0, v6
	ds_bpermute_b32 v6, v139, v0
	s_and_saveexec_b64 s[2:3], s[6:7]
	s_cbranch_execz .LBB0_83
	s_waitcnt lgkmcnt(0)
	v_add_f32_e32 v0, v0, v6
	v_mul_f32_e32 v0, 0x4b800000, v0
	v_trunc_f32_e32 v0, v0
	v_mul_f32_e32 v6, 0x2f800000, v0
	v_floor_f32_e32 v7, v6
	v_fmac_f32_e32 v0, 0xcf800000, v7
	v_cvt_u32_f32_e32 v6, v0
	v_cvt_u32_f32_e32 v7, v7
	global_atomic_add_x2 v[4:5], v[6:7], off offset:1280
.LBB0_83:
	s_or_b64 exec, exec, s[2:3]
	s_waitcnt lgkmcnt(0)
	s_nop 1
	v_mov_b64_e32 v[6:7], v[172:173]
	v_ffbh_u32_e32 v0, v7
	v_min_u32_e32 v0, 32, v0
	v_lshlrev_b64 v[6:7], v0, v[6:7]
	v_min_u32_e32 v6, 1, v6
	v_or_b32_e32 v6, v7, v6
	v_cvt_f32_u32_e32 v6, v6
	v_sub_u32_e32 v0, 32, v0
	v_ldexp_f32 v0, v6, v0
	v_fmamk_f32 v0, v0, 0x2e800000, v143
	v_cmp_gt_f32_e32 vcc, s90, v0
	v_mul_f32_e32 v6, 0x4b800000, v0
	s_nop 0
	v_cndmask_b32_e32 v0, v0, v6, vcc
	v_rsq_f32_e32 v0, v0
	s_nop 0
	v_mul_f32_e32 v6, 0x45800000, v0
	v_cndmask_b32_e32 v0, v0, v6, vcc
	v_lshl_add_u64 v[6:7], s[94:95], 0, v[18:19]
	v_lshl_add_u64 v[6:7], v[130:131], 1, v[6:7]
	s_nop 1
	v_mov_b64_e32 v[22:23], v[234:235]
	v_mov_b64_e32 v[24:25], v[236:237]
	s_nop 1
	v_mov_b64_e32 v[30:31], v[196:197]
	v_mov_b64_e32 v[32:33], v[198:199]
	v_mul_f32_e32 v19, v29, v0
	v_mul_f32_e32 v17, v17, v0
	v_mul_f32_e32 v16, v16, v0
	v_mul_f32_e32 v15, v15, v0
	v_mul_f32_e32 v14, v14, v0
	v_mul_f32_e32 v10, v10, v0
	v_mul_f32_e32 v8, v8, v0
	v_mul_f32_e32 v20, v20, v0
	v_lshlrev_b32_e32 v18, 16, v22
	v_fmac_f32_e32 v18, v30, v19
	v_and_b32_e32 v19, 0xffff0000, v22
	v_mul_f32_e32 v22, v28, v0
	v_fmac_f32_e32 v19, v31, v22
	v_lshlrev_b32_e32 v28, 16, v23
	v_mul_f32_e32 v22, v27, v0
	v_mul_f32_e32 v30, v19, v19
	v_fmac_f32_e32 v28, v32, v22
	v_and_b32_e32 v23, 0xffff0000, v23
	v_mul_f32_e32 v22, v26, v0
	v_fmac_f32_e32 v30, v18, v18
	v_fmac_f32_e32 v23, v33, v22
	v_fmac_f32_e32 v30, v28, v28
	v_fmac_f32_e32 v30, v23, v23
	v_cvt_pk_bf16_f32 v22, v18, v19
	v_cvt_pk_bf16_f32 v23, v28, v23
	s_nop 1
	v_mov_b64_e32 v[26:27], v[200:201]
	v_mov_b64_e32 v[28:29], v[202:203]
	v_lshlrev_b32_e32 v18, 16, v24
	v_fmac_f32_e32 v18, v26, v17
	v_and_b32_e32 v17, 0xffff0000, v24
	v_fmac_f32_e32 v17, v27, v16
	v_lshlrev_b32_e32 v16, 16, v25
	v_fmac_f32_e32 v16, v28, v15
	v_and_b32_e32 v15, 0xffff0000, v25
	v_fmac_f32_e32 v15, v29, v14
	v_mul_f32_e32 v14, v17, v17
	v_fmac_f32_e32 v14, v18, v18
	v_fmac_f32_e32 v14, v16, v16
	v_fmac_f32_e32 v14, v15, v15
	v_cvt_pk_bf16_f32 v24, v18, v17
	v_cvt_pk_bf16_f32 v25, v16, v15
	global_store_dwordx4 v[6:7], v[22:25], off
	v_add_f32_e32 v19, v30, v14
	s_nop 1
	v_mov_b64_e32 v[14:15], v[238:239]
	v_mov_b64_e32 v[16:17], v[240:241]
	s_nop 1
	v_mov_b64_e32 v[22:23], v[204:205]
	v_mov_b64_e32 v[24:25], v[206:207]
	v_lshlrev_b32_e32 v18, 16, v14
	v_and_b32_e32 v14, 0xffff0000, v14
	v_fmac_f32_e32 v14, v10, v23
	v_lshlrev_b32_e32 v10, 16, v15
	v_fmac_f32_e32 v10, v8, v24
	v_and_b32_e32 v15, 0xffff0000, v15
	v_mul_f32_e32 v8, v9, v0
	v_fmac_f32_e32 v18, v20, v22
	v_fmac_f32_e32 v15, v8, v25
	v_mul_f32_e32 v8, v14, v14
	v_fmac_f32_e32 v8, v18, v18
	v_fmac_f32_e32 v8, v10, v10
	v_fmac_f32_e32 v8, v15, v15
	v_add_f32_e32 v19, v19, v8
	v_cvt_pk_bf16_f32 v8, v18, v14
	v_cvt_pk_bf16_f32 v9, v10, v15
	s_nop 1
	v_mov_b64_e32 v[22:23], v[208:209]
	v_mov_b64_e32 v[24:25], v[210:211]
	v_lshlrev_b32_e32 v2, 16, v16
	v_mul_f32_e32 v3, v11, v0
	v_mul_f32_e32 v10, v21, v0
	v_lshlrev_b32_e32 v11, 16, v17
	v_fmac_f32_e32 v2, v3, v22
	v_and_b32_e32 v3, 0xffff0000, v16
	v_fmac_f32_e32 v3, v10, v23
	v_mul_f32_e32 v10, v12, v0
	v_and_b32_e32 v12, 0xffff0000, v17
	v_mul_f32_e32 v0, v13, v0
	v_fmac_f32_e32 v12, v0, v25
	v_mul_f32_e32 v0, v3, v3
	v_fmac_f32_e32 v11, v10, v24
	v_fmac_f32_e32 v0, v2, v2
	v_fmac_f32_e32 v0, v11, v11
	v_fmac_f32_e32 v0, v12, v12
	v_add_f32_e32 v0, v19, v0
	v_cvt_pk_bf16_f32 v10, v2, v3
	ds_bpermute_b32 v2, v138, v0
	v_cvt_pk_bf16_f32 v11, v11, v12
	global_store_dwordx4 v[6:7], v[8:11], off offset:256
	s_waitcnt lgkmcnt(0)
	v_add_f32_e32 v0, v0, v2
	ds_bpermute_b32 v2, v139, v0
	s_and_saveexec_b64 s[2:3], s[6:7]
	s_cbranch_execz .LBB0_85
	s_waitcnt lgkmcnt(0)
	v_add_f32_e32 v0, v0, v2
	v_mul_f32_e32 v0, 0x4b800000, v0
	v_trunc_f32_e32 v0, v0
	v_mul_f32_e32 v2, 0x2f800000, v0
	v_floor_f32_e32 v3, v2
	v_fmac_f32_e32 v0, 0xcf800000, v3
	v_cvt_u32_f32_e32 v2, v0
	v_cvt_u32_f32_e32 v3, v3
	global_atomic_add_x2 v[4:5], v[2:3], off offset:1408

.LBB0_125:
	v_add_u32_e32 v140, s3, v158
	ds_read_b128 v[154:157], v140
	ds_read_b128 v[162:165], v140 offset:1024
	ds_read_b128 v[166:169], v140 offset:2048
	ds_read_b128 v[188:191], v140 offset:3072
	s_add_u32 s22, s20, 0xfffc0080
	s_addc_u32 s23, s21, -1
	s_cmp_eq_u32 s55, 12
	s_cselect_b32 s25, s5, s23
	s_cselect_b32 s24, s13, s22
	s_cselect_b32 s23, s9, s33
	s_cselect_b32 s22, s14, s15
	v_lshl_add_u64 v[140:141], s[20:21], 0, v[136:137]
	s_add_i32 m0, s34, 0xc000
	ds_read_b128 v[192:195], v160
	ds_read_b128 v[196:199], v160 offset:1024
	ds_read_b128 v[200:203], v160 offset:2048
	ds_read_b128 v[204:207], v160 offset:3072
	ds_read_b128 v[208:211], v160 offset:4096
	ds_read_b128 v[212:215], v160 offset:5120
	ds_read_b128 v[218:221], v160 offset:6144
	ds_read_b128 v[222:225], v160 offset:7168
	global_load_lds_dwordx4 v[140:141], off
	v_lshl_add_u64 v[140:141], s[20:21], 0, v[138:139]
	s_add_i32 m0, s34, 0xe000
	s_nop 0
	global_load_lds_dwordx4 v[140:141], off
	s_waitcnt lgkmcnt(8)
	s_barrier
	s_waitcnt lgkmcnt(0)
	s_setprio 1
	s_waitcnt lgkmcnt(0)
	v_mfma_f32_16x16x32_bf16 v[126:129], v[154:157], v[192:195], v[126:129]
	v_mfma_f32_16x16x32_bf16 v[122:125], v[166:169], v[192:195], v[122:125]
	v_mfma_f32_16x16x32_bf16 v[110:113], v[154:157], v[200:203], v[110:113]
	v_mfma_f32_16x16x32_bf16 v[106:109], v[166:169], v[200:203], v[106:109]
	v_mfma_f32_16x16x32_bf16 v[94:97], v[154:157], v[208:211], v[94:97]
	v_mfma_f32_16x16x32_bf16 v[90:93], v[166:169], v[208:211], v[90:93]
	v_mfma_f32_16x16x32_bf16 v[78:81], v[154:157], v[218:221], v[78:81]
	v_mfma_f32_16x16x32_bf16 v[74:77], v[166:169], v[218:221], v[74:77]
	v_mfma_f32_16x16x32_bf16 v[126:129], v[162:165], v[196:199], v[126:129]
	v_mfma_f32_16x16x32_bf16 v[122:125], v[188:191], v[196:199], v[122:125]
	v_mfma_f32_16x16x32_bf16 v[110:113], v[162:165], v[204:207], v[110:113]
	v_mfma_f32_16x16x32_bf16 v[106:109], v[188:191], v[204:207], v[106:109]
	v_mfma_f32_16x16x32_bf16 v[94:97], v[162:165], v[212:215], v[94:97]
	v_mfma_f32_16x16x32_bf16 v[90:93], v[188:191], v[212:215], v[90:93]
	v_mfma_f32_16x16x32_bf16 v[78:81], v[162:165], v[222:225], v[78:81]
	v_mfma_f32_16x16x32_bf16 v[74:77], v[188:191], v[222:225], v[74:77]
	s_setprio 0
	s_barrier
	v_add_u32_e32 v140, s36, v158
	s_mov_b32 m0, s30
	ds_read_b128 v[226:229], v140
	ds_read_b128 v[230:233], v140 offset:1024
	ds_read_b128 v[234:237], v140 offset:2048
	ds_read_b128 v[238:241], v140 offset:3072
	v_lshl_add_u64 v[140:141], s[22:23], 0, v[0:1]
	global_load_lds_dwordx4 v[140:141], off
	v_lshl_add_u64 v[144:145], s[22:23], 0, v[130:131]
	s_mov_b32 m0, s31
	s_nop 0
	global_load_lds_dwordx4 v[144:145], off
	s_barrier
	s_waitcnt lgkmcnt(0)
	s_setprio 1
	s_waitcnt lgkmcnt(0)
	v_mfma_f32_16x16x32_bf16 v[118:121], v[226:229], v[192:195], v[118:121]
	v_mfma_f32_16x16x32_bf16 v[114:117], v[234:237], v[192:195], v[114:117]
	v_mfma_f32_16x16x32_bf16 v[102:105], v[226:229], v[200:203], v[102:105]
	v_mfma_f32_16x16x32_bf16 v[98:101], v[234:237], v[200:203], v[98:101]
	v_mfma_f32_16x16x32_bf16 v[86:89], v[226:229], v[208:211], v[86:89]
	v_mfma_f32_16x16x32_bf16 v[82:85], v[234:237], v[208:211], v[82:85]
	v_mfma_f32_16x16x32_bf16 v[70:73], v[226:229], v[218:221], v[70:73]
	v_mfma_f32_16x16x32_bf16 v[66:69], v[234:237], v[218:221], v[66:69]
	v_mfma_f32_16x16x32_bf16 v[118:121], v[230:233], v[196:199], v[118:121]
	v_mfma_f32_16x16x32_bf16 v[114:117], v[238:241], v[196:199], v[114:117]
	v_mfma_f32_16x16x32_bf16 v[102:105], v[230:233], v[204:207], v[102:105]
	v_mfma_f32_16x16x32_bf16 v[98:101], v[238:241], v[204:207], v[98:101]
	v_mfma_f32_16x16x32_bf16 v[86:89], v[230:233], v[212:215], v[86:89]
	v_mfma_f32_16x16x32_bf16 v[82:85], v[238:241], v[212:215], v[82:85]
	v_mfma_f32_16x16x32_bf16 v[70:73], v[230:233], v[222:225], v[70:73]
	v_mfma_f32_16x16x32_bf16 v[66:69], v[238:241], v[222:225], v[66:69]
	s_setprio 0
	s_mov_b32 m0, s34
	v_lshl_add_u64 v[146:147], s[24:25], 0, v[134:135]
	s_barrier
	ds_read_b128 v[192:195], v160 offset:16384
	ds_read_b128 v[196:199], v160 offset:17408
	ds_read_b128 v[200:203], v160 offset:18432
	ds_read_b128 v[204:207], v160 offset:19456
	ds_read_b128 v[208:211], v160 offset:20480
	ds_read_b128 v[212:215], v160 offset:21504
	ds_read_b128 v[218:221], v160 offset:22528
	ds_read_b128 v[222:225], v160 offset:23552
	global_load_lds_dwordx4 v[146:147], off
	v_lshl_add_u64 v[170:171], s[24:25], 0, v[132:133]
	s_mov_b32 m0, s35
	s_nop 0
	global_load_lds_dwordx4 v[170:171], off
	s_barrier
	s_waitcnt lgkmcnt(0)
	s_setprio 1
	s_waitcnt lgkmcnt(0)
	v_mfma_f32_16x16x32_bf16 v[62:65], v[154:157], v[192:195], v[62:65]
	v_mfma_f32_16x16x32_bf16 v[58:61], v[166:169], v[192:195], v[58:61]
	v_mfma_f32_16x16x32_bf16 v[46:49], v[154:157], v[200:203], v[46:49]
	v_mfma_f32_16x16x32_bf16 v[42:45], v[166:169], v[200:203], v[42:45]
	v_mfma_f32_16x16x32_bf16 v[30:33], v[154:157], v[208:211], v[30:33]
	v_mfma_f32_16x16x32_bf16 v[26:29], v[166:169], v[208:211], v[26:29]
	v_mfma_f32_16x16x32_bf16 v[14:17], v[154:157], v[218:221], v[14:17]
	v_mfma_f32_16x16x32_bf16 v[10:13], v[166:169], v[218:221], v[10:13]
	v_mfma_f32_16x16x32_bf16 v[62:65], v[162:165], v[196:199], v[62:65]
	v_mfma_f32_16x16x32_bf16 v[58:61], v[188:191], v[196:199], v[58:61]
	v_mfma_f32_16x16x32_bf16 v[46:49], v[162:165], v[204:207], v[46:49]
	v_mfma_f32_16x16x32_bf16 v[42:45], v[188:191], v[204:207], v[42:45]
	v_mfma_f32_16x16x32_bf16 v[30:33], v[162:165], v[212:215], v[30:33]
	v_mfma_f32_16x16x32_bf16 v[26:29], v[188:191], v[212:215], v[26:29]
	v_mfma_f32_16x16x32_bf16 v[14:17], v[162:165], v[222:225], v[14:17]
	v_mfma_f32_16x16x32_bf16 v[10:13], v[188:191], v[222:225], v[10:13]
	s_setprio 0
	s_barrier
	s_add_u32 s56, s22, 0x40000
	s_addc_u32 s57, s23, 0
	s_mov_b32 m0, s37
	v_lshl_add_u64 v[154:155], s[56:57], 0, v[0:1]
	global_load_lds_dwordx4 v[154:155], off
	v_lshl_add_u64 v[154:155], s[56:57], 0, v[130:131]
	s_mov_b32 m0, s38
	s_nop 0
	global_load_lds_dwordx4 v[154:155], off
	s_waitcnt vmcnt(6)
	s_barrier
	s_setprio 1
	v_mfma_f32_16x16x32_bf16 v[54:57], v[226:229], v[192:195], v[54:57]
	v_mfma_f32_16x16x32_bf16 v[50:53], v[234:237], v[192:195], v[50:53]
	v_mfma_f32_16x16x32_bf16 v[38:41], v[226:229], v[200:203], v[38:41]
	v_mfma_f32_16x16x32_bf16 v[34:37], v[234:237], v[200:203], v[34:37]
	v_mfma_f32_16x16x32_bf16 v[22:25], v[226:229], v[208:211], v[22:25]
	v_mfma_f32_16x16x32_bf16 v[18:21], v[234:237], v[208:211], v[18:21]
	v_mfma_f32_16x16x32_bf16 v[6:9], v[226:229], v[218:221], v[6:9]
	v_mfma_f32_16x16x32_bf16 v[2:5], v[234:237], v[218:221], v[2:5]
	v_mfma_f32_16x16x32_bf16 v[54:57], v[230:233], v[196:199], v[54:57]
	v_mfma_f32_16x16x32_bf16 v[50:53], v[238:241], v[196:199], v[50:53]
	v_mfma_f32_16x16x32_bf16 v[38:41], v[230:233], v[204:207], v[38:41]
	v_mfma_f32_16x16x32_bf16 v[34:37], v[238:241], v[204:207], v[34:37]
	v_mfma_f32_16x16x32_bf16 v[22:25], v[230:233], v[212:215], v[22:25]
	v_mfma_f32_16x16x32_bf16 v[18:21], v[238:241], v[212:215], v[18:21]
	v_mfma_f32_16x16x32_bf16 v[6:9], v[230:233], v[222:225], v[6:9]
	v_mfma_f32_16x16x32_bf16 v[2:5], v[238:241], v[222:225], v[2:5]
	s_setprio 0
	v_add_u32_e32 v161, s41, v158
	s_barrier
	ds_read_b128 v[154:157], v161
	ds_read_b128 v[162:165], v161 offset:1024
	ds_read_b128 v[166:169], v161 offset:2048
	ds_read_b128 v[188:191], v161 offset:3072
	s_add_u32 s24, s24, 0x40000
	s_addc_u32 s25, s25, 0
	s_mov_b32 m0, s39
	v_lshl_add_u64 v[172:173], s[24:25], 0, v[134:135]
	ds_read_b128 v[192:195], v160 offset:32768
	ds_read_b128 v[196:199], v160 offset:33792
	ds_read_b128 v[200:203], v160 offset:34816
	ds_read_b128 v[204:207], v160 offset:35840
	ds_read_b128 v[208:211], v160 offset:36864
	ds_read_b128 v[212:215], v160 offset:37888
	ds_read_b128 v[218:221], v160 offset:38912
	ds_read_b128 v[222:225], v160 offset:39936
	global_load_lds_dwordx4 v[172:173], off
	v_lshl_add_u64 v[172:173], s[24:25], 0, v[132:133]
	s_mov_b32 m0, s40
	s_nop 0
	global_load_lds_dwordx4 v[172:173], off
	s_waitcnt lgkmcnt(8)
	s_barrier
	s_waitcnt lgkmcnt(0)
	s_setprio 1
	s_waitcnt lgkmcnt(0)
	v_mfma_f32_16x16x32_bf16 v[126:129], v[154:157], v[192:195], v[126:129]
	v_mfma_f32_16x16x32_bf16 v[122:125], v[166:169], v[192:195], v[122:125]
	v_mfma_f32_16x16x32_bf16 v[110:113], v[154:157], v[200:203], v[110:113]
	v_mfma_f32_16x16x32_bf16 v[106:109], v[166:169], v[200:203], v[106:109]
	v_mfma_f32_16x16x32_bf16 v[94:97], v[154:157], v[208:211], v[94:97]
	v_mfma_f32_16x16x32_bf16 v[90:93], v[166:169], v[208:211], v[90:93]
	v_mfma_f32_16x16x32_bf16 v[78:81], v[154:157], v[218:221], v[78:81]
	v_mfma_f32_16x16x32_bf16 v[74:77], v[166:169], v[218:221], v[74:77]
	v_mfma_f32_16x16x32_bf16 v[126:129], v[162:165], v[196:199], v[126:129]
	v_mfma_f32_16x16x32_bf16 v[122:125], v[188:191], v[196:199], v[122:125]
	v_mfma_f32_16x16x32_bf16 v[110:113], v[162:165], v[204:207], v[110:113]
	v_mfma_f32_16x16x32_bf16 v[106:109], v[188:191], v[204:207], v[106:109]
	v_mfma_f32_16x16x32_bf16 v[94:97], v[162:165], v[212:215], v[94:97]
	v_mfma_f32_16x16x32_bf16 v[90:93], v[188:191], v[212:215], v[90:93]
	v_mfma_f32_16x16x32_bf16 v[78:81], v[162:165], v[222:225], v[78:81]
	v_mfma_f32_16x16x32_bf16 v[74:77], v[188:191], v[222:225], v[74:77]
	s_setprio 0
	s_barrier
	s_mov_b32 m0, s42
	v_add_u32_e32 v161, s48, v158
	v_lshl_add_u64 v[140:141], v[140:141], 0, s[66:67]
	ds_read_b128 v[226:229], v161
	ds_read_b128 v[230:233], v161 offset:1024
	ds_read_b128 v[234:237], v161 offset:2048
	ds_read_b128 v[238:241], v161 offset:3072
	global_load_lds_dwordx4 v[140:141], off
	v_lshl_add_u64 v[140:141], v[144:145], 0, s[66:67]
	s_mov_b32 m0, s43
	s_nop 0
	global_load_lds_dwordx4 v[140:141], off
	s_barrier
	s_waitcnt lgkmcnt(0)
	s_setprio 1
	s_waitcnt lgkmcnt(0)
	v_mfma_f32_16x16x32_bf16 v[118:121], v[226:229], v[192:195], v[118:121]
	v_mfma_f32_16x16x32_bf16 v[114:117], v[234:237], v[192:195], v[114:117]
	v_mfma_f32_16x16x32_bf16 v[102:105], v[226:229], v[200:203], v[102:105]
	v_mfma_f32_16x16x32_bf16 v[98:101], v[234:237], v[200:203], v[98:101]
	v_mfma_f32_16x16x32_bf16 v[86:89], v[226:229], v[208:211], v[86:89]
	v_mfma_f32_16x16x32_bf16 v[82:85], v[234:237], v[208:211], v[82:85]
	v_mfma_f32_16x16x32_bf16 v[70:73], v[226:229], v[218:221], v[70:73]
	v_mfma_f32_16x16x32_bf16 v[66:69], v[234:237], v[218:221], v[66:69]
	v_mfma_f32_16x16x32_bf16 v[118:121], v[230:233], v[196:199], v[118:121]
	v_mfma_f32_16x16x32_bf16 v[114:117], v[238:241], v[196:199], v[114:117]
	v_mfma_f32_16x16x32_bf16 v[102:105], v[230:233], v[204:207], v[102:105]
	v_mfma_f32_16x16x32_bf16 v[98:101], v[238:241], v[204:207], v[98:101]
	v_mfma_f32_16x16x32_bf16 v[86:89], v[230:233], v[212:215], v[86:89]
	v_mfma_f32_16x16x32_bf16 v[82:85], v[238:241], v[212:215], v[82:85]
	v_mfma_f32_16x16x32_bf16 v[70:73], v[230:233], v[222:225], v[70:73]
	v_mfma_f32_16x16x32_bf16 v[66:69], v[238:241], v[222:225], v[66:69]
	s_setprio 0
	s_mov_b32 m0, s44
	v_lshl_add_u64 v[140:141], v[146:147], 0, s[66:67]
	s_barrier
	ds_read_b128 v[192:195], v160 offset:49152
	ds_read_b128 v[196:199], v160 offset:50176
	ds_read_b128 v[200:203], v160 offset:51200
	ds_read_b128 v[204:207], v160 offset:52224
	ds_read_b128 v[208:211], v160 offset:53248
	ds_read_b128 v[212:215], v160 offset:54272
	ds_read_b128 v[218:221], v160 offset:55296
	ds_read_b128 v[222:225], v160 offset:56320
	global_load_lds_dwordx4 v[140:141], off
	v_lshl_add_u64 v[140:141], v[170:171], 0, s[66:67]
	s_mov_b32 m0, s45
	s_nop 0
	global_load_lds_dwordx4 v[140:141], off
	s_barrier
	s_waitcnt lgkmcnt(0)
	s_setprio 1
	s_waitcnt lgkmcnt(0)
	v_mfma_f32_16x16x32_bf16 v[62:65], v[154:157], v[192:195], v[62:65]
	v_mfma_f32_16x16x32_bf16 v[58:61], v[166:169], v[192:195], v[58:61]
	v_mfma_f32_16x16x32_bf16 v[46:49], v[154:157], v[200:203], v[46:49]
	v_mfma_f32_16x16x32_bf16 v[42:45], v[166:169], v[200:203], v[42:45]
	v_mfma_f32_16x16x32_bf16 v[30:33], v[154:157], v[208:211], v[30:33]
	v_mfma_f32_16x16x32_bf16 v[26:29], v[166:169], v[208:211], v[26:29]
	v_mfma_f32_16x16x32_bf16 v[14:17], v[154:157], v[218:221], v[14:17]
	v_mfma_f32_16x16x32_bf16 v[10:13], v[166:169], v[218:221], v[10:13]
	v_mfma_f32_16x16x32_bf16 v[62:65], v[162:165], v[196:199], v[62:65]
	v_mfma_f32_16x16x32_bf16 v[58:61], v[188:191], v[196:199], v[58:61]
	v_mfma_f32_16x16x32_bf16 v[46:49], v[162:165], v[204:207], v[46:49]
	v_mfma_f32_16x16x32_bf16 v[42:45], v[188:191], v[204:207], v[42:45]
	v_mfma_f32_16x16x32_bf16 v[30:33], v[162:165], v[212:215], v[30:33]
	v_mfma_f32_16x16x32_bf16 v[26:29], v[188:191], v[212:215], v[26:29]
	v_mfma_f32_16x16x32_bf16 v[14:17], v[162:165], v[222:225], v[14:17]
	v_mfma_f32_16x16x32_bf16 v[10:13], v[188:191], v[222:225], v[10:13]
	s_setprio 0
	s_barrier
	s_add_u32 s22, s22, 0x40080
	s_addc_u32 s23, s23, 0
	s_mov_b32 m0, s52
	v_lshl_add_u64 v[140:141], s[22:23], 0, v[0:1]
	global_load_lds_dwordx4 v[140:141], off
	v_lshl_add_u64 v[140:141], s[22:23], 0, v[130:131]
	s_mov_b32 m0, s53
	s_nop 0
	global_load_lds_dwordx4 v[140:141], off
	s_waitcnt vmcnt(6)
	s_barrier
	s_setprio 1
	v_mfma_f32_16x16x32_bf16 v[54:57], v[226:229], v[192:195], v[54:57]
	v_mfma_f32_16x16x32_bf16 v[50:53], v[234:237], v[192:195], v[50:53]
	v_mfma_f32_16x16x32_bf16 v[38:41], v[226:229], v[200:203], v[38:41]
	v_mfma_f32_16x16x32_bf16 v[34:37], v[234:237], v[200:203], v[34:37]
	v_mfma_f32_16x16x32_bf16 v[22:25], v[226:229], v[208:211], v[22:25]
	v_mfma_f32_16x16x32_bf16 v[18:21], v[234:237], v[208:211], v[18:21]
	v_mfma_f32_16x16x32_bf16 v[6:9], v[226:229], v[218:221], v[6:9]
	v_mfma_f32_16x16x32_bf16 v[2:5], v[234:237], v[218:221], v[2:5]
	v_mfma_f32_16x16x32_bf16 v[54:57], v[230:233], v[196:199], v[54:57]
	v_mfma_f32_16x16x32_bf16 v[50:53], v[238:241], v[196:199], v[50:53]
	v_mfma_f32_16x16x32_bf16 v[38:41], v[230:233], v[204:207], v[38:41]
	v_mfma_f32_16x16x32_bf16 v[34:37], v[238:241], v[204:207], v[34:37]
	v_mfma_f32_16x16x32_bf16 v[22:25], v[230:233], v[212:215], v[22:25]
	v_mfma_f32_16x16x32_bf16 v[18:21], v[238:241], v[212:215], v[18:21]
	v_mfma_f32_16x16x32_bf16 v[6:9], v[230:233], v[222:225], v[6:9]
	v_mfma_f32_16x16x32_bf16 v[2:5], v[238:241], v[222:225], v[2:5]
	s_setprio 0
	s_add_i32 s55, s55, 2
	s_add_u32 s20, s20, 0x100
	s_addc_u32 s21, s21, 0
	s_add_u32 s15, s15, 0x100
	s_addc_u32 s33, s33, 0
	s_cmp_gt_u32 s55, 13
	s_barrier
	s_cbranch_scc0 .LBB0_125
	v_lshl_add_u32 v140, s2, 8, v153
	v_ashrrev_i32_e32 v141, 31, v140
	v_lshl_add_u64 v[154:155], v[140:141], 3, s[0:1]
	global_load_dwordx2 v[144:145], v[154:155], off
	global_load_dwordx2 v[192:193], v[154:155], off offset:128
	global_load_dwordx2 v[194:195], v[154:155], off offset:256
	global_load_dwordx2 v[196:197], v[154:155], off offset:384
	global_load_dwordx2 v[198:199], v[154:155], off offset:1024
	global_load_dwordx2 v[200:201], v[154:155], off offset:1152
	global_load_dwordx2 v[202:203], v[154:155], off offset:1280
	global_load_dwordx2 v[204:205], v[154:155], off offset:1408
	v_lshl_or_b32 v156, s4, 7, v159
	v_ashrrev_i32_e32 v157, 31, v156
	s_movk_i32 s2, 0x1600
	s_mov_b64 s[22:23], s[18:19]
	s_mov_b64 s[20:21], s[16:17]
	s_waitcnt vmcnt(0)
	v_ffbh_u32_e32 v141, v145
	v_min_u32_e32 v141, 32, v141
	v_lshlrev_b64 v[144:145], v141, v[144:145]
	v_min_u32_e32 v144, 1, v144
	v_or_b32_e32 v144, v145, v144
	v_cvt_f32_u32_e32 v144, v144
	v_sub_u32_e32 v141, 32, v141
	v_ldexp_f32 v141, v144, v141
	v_fmamk_f32 v141, v141, 0x2e800000, v143
	v_cmp_gt_f32_e32 vcc, s90, v141
	v_mul_f32_e32 v144, 0x4b800000, v141
	s_nop 0
	v_cndmask_b32_e32 v141, v141, v144, vcc
	v_rsq_f32_e32 v141, v141
	s_nop 0
	v_mul_f32_e32 v144, 0x45800000, v141
	v_cndmask_b32_e32 v144, v141, v144, vcc
	v_pk_mul_f32 v[126:127], v[126:127], v[144:145] op_sel_hi:[1,0]
	v_pk_mul_f32 v[118:119], v[118:119], v[144:145] op_sel_hi:[1,0]
	v_mul_f32_e32 v141, 0xbfb8aa3b, v126
	v_exp_f32_e32 v141, v141
	v_pk_mul_f32 v[128:129], v[128:129], v[144:145] op_sel_hi:[1,0]
	v_pk_mul_f32 v[120:121], v[120:121], v[144:145] op_sel_hi:[1,0]
	v_pk_mul_f32 v[114:115], v[114:115], v[144:145] op_sel_hi:[1,0]
	v_add_f32_e32 v141, 1.0, v141
	v_rcp_f32_e32 v141, v141
	v_pk_mul_f32 v[124:125], v[124:125], v[144:145] op_sel_hi:[1,0]
	v_pk_mul_f32 v[116:117], v[116:117], v[144:145] op_sel_hi:[1,0]
	v_mul_f32_e32 v126, v126, v141
	v_mul_f32_e32 v118, v118, v126
	v_mul_f32_e32 v126, 0xbfb8aa3b, v127
	v_exp_f32_e32 v126, v126
	s_nop 0
	v_add_f32_e32 v126, 1.0, v126
	v_rcp_f32_e32 v126, v126
	s_nop 0
	v_mul_f32_e32 v126, v127, v126
	v_mul_f32_e32 v119, v119, v126
	v_cvt_pk_bf16_f32 v118, v118, v119
	v_mul_f32_e32 v119, 0xbfb8aa3b, v128
	v_exp_f32_e32 v119, v119
	s_nop 0
	v_add_f32_e32 v119, 1.0, v119
	v_rcp_f32_e32 v119, v119
	s_nop 0
	v_mul_f32_e32 v119, v128, v119
	v_mul_f32_e32 v119, v120, v119
	v_mul_f32_e32 v120, 0xbfb8aa3b, v129
	v_exp_f32_e32 v120, v120
	s_nop 0
	v_add_f32_e32 v120, 1.0, v120
	v_rcp_f32_e32 v120, v120
	s_nop 0
	v_mul_f32_e32 v120, v129, v120
	v_mul_f32_e32 v120, v121, v120
	v_cvt_pk_bf16_f32 v119, v119, v120
	v_pk_mul_f32 v[120:121], v[122:123], v[144:145] op_sel_hi:[1,0]
	s_nop 0
	v_mul_f32_e32 v122, 0xbfb8aa3b, v120
	v_exp_f32_e32 v122, v122
	s_nop 0
	v_add_f32_e32 v122, 1.0, v122
	v_rcp_f32_e32 v122, v122
	s_nop 0
	v_mul_f32_e32 v120, v120, v122
	v_mul_f32_e32 v114, v114, v120
	v_mul_f32_e32 v120, 0xbfb8aa3b, v121
	v_exp_f32_e32 v120, v120
	s_nop 0
	v_add_f32_e32 v120, 1.0, v120
	v_rcp_f32_e32 v120, v120
	s_nop 0
	v_mul_f32_e32 v120, v121, v120
	v_mul_f32_e32 v115, v115, v120
	v_cvt_pk_bf16_f32 v120, v114, v115
	v_mul_f32_e32 v114, 0xbfb8aa3b, v124
	v_mul_f32_e32 v115, 0xbfb8aa3b, v125
	v_exp_f32_e32 v114, v114
	v_exp_f32_e32 v115, v115
	v_add_f32_e32 v114, 1.0, v114
	v_add_f32_e32 v115, 1.0, v115
	v_rcp_f32_e32 v114, v114
	v_rcp_f32_e32 v115, v115
	v_mul_f32_e32 v114, v124, v114
	v_mul_f32_e32 v115, v125, v115
	v_mul_f32_e32 v114, v116, v114
	v_mul_f32_e32 v115, v117, v115
	v_cvt_pk_bf16_f32 v121, v114, v115
	v_mov_b64_e32 v[114:115], s[72:73]
	v_mad_i64_i32 v[122:123], s[4:5], v140, s2, v[114:115]
	v_lshlrev_b64 v[116:117], 1, v[156:157]
	v_lshl_add_u64 v[122:123], v[122:123], 0, v[116:117]
	global_store_dwordx4 v[122:123], v[118:121], off
	s_nop 1
	v_mov_b64_e32 v[118:119], v[192:193]
	s_nop 0
	v_or_b32_e32 v120, 16, v140
	v_ffbh_u32_e32 v121, v119
	v_min_u32_e32 v121, 32, v121
	v_lshlrev_b64 v[118:119], v121, v[118:119]
	v_min_u32_e32 v118, 1, v118
	v_or_b32_e32 v118, v119, v118
	v_cvt_f32_u32_e32 v118, v118
	v_sub_u32_e32 v119, 32, v121
	v_ldexp_f32 v118, v118, v119
	v_fmamk_f32 v118, v118, 0x2e800000, v143
	v_cmp_gt_f32_e32 vcc, s90, v118
	v_mul_f32_e32 v119, 0x4b800000, v118
	s_nop 0
	v_cndmask_b32_e32 v118, v118, v119, vcc
	v_rsq_f32_e32 v118, v118
	s_nop 0
	v_mul_f32_e32 v119, 0x45800000, v118
	v_cndmask_b32_e32 v118, v118, v119, vcc
	v_pk_mul_f32 v[110:111], v[110:111], v[118:119] op_sel_hi:[1,0]
	v_pk_mul_f32 v[112:113], v[112:113], v[118:119] op_sel_hi:[1,0]
	v_pk_mul_f32 v[104:105], v[104:105], v[118:119] op_sel_hi:[1,0]
	v_pk_mul_f32 v[102:103], v[102:103], v[118:119] op_sel_hi:[1,0]
	v_mul_f32_e32 v119, 0xbfb8aa3b, v110
	v_exp_f32_e32 v119, v119
	s_nop 0
	v_add_f32_e32 v119, 1.0, v119
	v_rcp_f32_e32 v119, v119
	s_nop 0
	v_mul_f32_e32 v110, v110, v119
	v_mul_f32_e32 v102, v102, v110
	v_mul_f32_e32 v110, 0xbfb8aa3b, v111
	v_exp_f32_e32 v110, v110
	v_pk_mul_f32 v[98:99], v[98:99], v[118:119] op_sel_hi:[1,0]
	v_pk_mul_f32 v[108:109], v[108:109], v[118:119] op_sel_hi:[1,0]
	v_pk_mul_f32 v[100:101], v[100:101], v[118:119] op_sel_hi:[1,0]
	v_add_f32_e32 v110, 1.0, v110
	v_rcp_f32_e32 v110, v110
	s_nop 0
	v_mul_f32_e32 v110, v111, v110
	v_mul_f32_e32 v103, v103, v110
	v_cvt_pk_bf16_f32 v102, v102, v103
	v_mul_f32_e32 v103, 0xbfb8aa3b, v112
	v_exp_f32_e32 v103, v103
	s_nop 0
	v_add_f32_e32 v103, 1.0, v103
	v_rcp_f32_e32 v103, v103
	s_nop 0
	v_mul_f32_e32 v103, v112, v103
	v_mul_f32_e32 v103, v104, v103
	v_mul_f32_e32 v104, 0xbfb8aa3b, v113
	v_exp_f32_e32 v104, v104
	s_nop 0
	v_add_f32_e32 v104, 1.0, v104
	v_rcp_f32_e32 v104, v104
	s_nop 0
	v_mul_f32_e32 v104, v113, v104
	v_mul_f32_e32 v104, v105, v104
	v_cvt_pk_bf16_f32 v103, v103, v104
	v_pk_mul_f32 v[104:105], v[106:107], v[118:119] op_sel_hi:[1,0]
	s_nop 0
	v_mul_f32_e32 v106, 0xbfb8aa3b, v104
	v_exp_f32_e32 v106, v106
	s_nop 0
	v_add_f32_e32 v106, 1.0, v106
	v_rcp_f32_e32 v106, v106
	s_nop 0
	v_mul_f32_e32 v104, v104, v106
	v_mul_f32_e32 v98, v98, v104
	v_mul_f32_e32 v104, 0xbfb8aa3b, v105
	v_exp_f32_e32 v104, v104
	s_nop 0
	v_add_f32_e32 v104, 1.0, v104
	v_rcp_f32_e32 v104, v104
	s_nop 0
	v_mul_f32_e32 v104, v105, v104
	v_mul_f32_e32 v99, v99, v104
	v_cvt_pk_bf16_f32 v104, v98, v99
	v_mul_f32_e32 v98, 0xbfb8aa3b, v108
	v_mul_f32_e32 v99, 0xbfb8aa3b, v109
	v_exp_f32_e32 v98, v98
	v_exp_f32_e32 v99, v99
	v_add_f32_e32 v98, 1.0, v98
	v_add_f32_e32 v99, 1.0, v99
	v_rcp_f32_e32 v98, v98
	v_rcp_f32_e32 v99, v99
	v_mul_f32_e32 v98, v108, v98
	v_mul_f32_e32 v99, v109, v99
	v_mul_f32_e32 v98, v100, v98
	v_mul_f32_e32 v99, v101, v99
	v_cvt_pk_bf16_f32 v105, v98, v99
	v_mad_i64_i32 v[98:99], s[4:5], v120, s2, v[114:115]
	v_lshl_add_u64 v[98:99], v[98:99], 0, v[116:117]
	global_store_dwordx4 v[98:99], v[102:105], off
	s_nop 1
	v_mov_b64_e32 v[98:99], v[194:195]
	v_or_b32_e32 v100, 32, v140
	v_ffbh_u32_e32 v101, v99
	v_min_u32_e32 v101, 32, v101
	v_lshlrev_b64 v[98:99], v101, v[98:99]
	v_min_u32_e32 v98, 1, v98
	v_or_b32_e32 v98, v99, v98
	v_cvt_f32_u32_e32 v98, v98
	v_sub_u32_e32 v99, 32, v101
	v_ldexp_f32 v98, v98, v99
	v_fmamk_f32 v98, v98, 0x2e800000, v143
	v_cmp_gt_f32_e32 vcc, s90, v98
	v_mul_f32_e32 v99, 0x4b800000, v98
	s_nop 0
	v_cndmask_b32_e32 v98, v98, v99, vcc
	v_rsq_f32_e32 v98, v98
	s_nop 0
	v_mul_f32_e32 v99, 0x45800000, v98
	v_cndmask_b32_e32 v98, v98, v99, vcc
	v_pk_mul_f32 v[94:95], v[94:95], v[98:99] op_sel_hi:[1,0]
	v_pk_mul_f32 v[96:97], v[96:97], v[98:99] op_sel_hi:[1,0]
	v_pk_mul_f32 v[88:89], v[88:89], v[98:99] op_sel_hi:[1,0]
	v_pk_mul_f32 v[86:87], v[86:87], v[98:99] op_sel_hi:[1,0]
	v_mul_f32_e32 v99, 0xbfb8aa3b, v94
	v_exp_f32_e32 v99, v99
	s_nop 0
	v_add_f32_e32 v99, 1.0, v99
	v_rcp_f32_e32 v99, v99
	s_nop 0
	v_mul_f32_e32 v94, v94, v99
	v_mul_f32_e32 v86, v86, v94
	v_mul_f32_e32 v94, 0xbfb8aa3b, v95
	v_exp_f32_e32 v94, v94
	v_pk_mul_f32 v[82:83], v[82:83], v[98:99] op_sel_hi:[1,0]
	v_pk_mul_f32 v[92:93], v[92:93], v[98:99] op_sel_hi:[1,0]
	v_pk_mul_f32 v[84:85], v[84:85], v[98:99] op_sel_hi:[1,0]
	v_add_f32_e32 v94, 1.0, v94
	v_rcp_f32_e32 v94, v94
	s_nop 0
	v_mul_f32_e32 v94, v95, v94
	v_mul_f32_e32 v87, v87, v94
	v_cvt_pk_bf16_f32 v86, v86, v87
	v_mul_f32_e32 v87, 0xbfb8aa3b, v96
	v_exp_f32_e32 v87, v87
	s_nop 0
	v_add_f32_e32 v87, 1.0, v87
	v_rcp_f32_e32 v87, v87
	s_nop 0
	v_mul_f32_e32 v87, v96, v87
	v_mul_f32_e32 v87, v88, v87
	v_mul_f32_e32 v88, 0xbfb8aa3b, v97
	v_exp_f32_e32 v88, v88
	s_nop 0
	v_add_f32_e32 v88, 1.0, v88
	v_rcp_f32_e32 v88, v88
	s_nop 0
	v_mul_f32_e32 v88, v97, v88
	v_mul_f32_e32 v88, v89, v88
	v_cvt_pk_bf16_f32 v87, v87, v88
	v_pk_mul_f32 v[88:89], v[90:91], v[98:99] op_sel_hi:[1,0]
	s_nop 0
	v_mul_f32_e32 v90, 0xbfb8aa3b, v88
	v_exp_f32_e32 v90, v90
	s_nop 0
	v_add_f32_e32 v90, 1.0, v90
	v_rcp_f32_e32 v90, v90
	s_nop 0
	v_mul_f32_e32 v88, v88, v90
	v_mul_f32_e32 v82, v82, v88
	v_mul_f32_e32 v88, 0xbfb8aa3b, v89
	v_exp_f32_e32 v88, v88
	s_nop 0
	v_add_f32_e32 v88, 1.0, v88
	v_rcp_f32_e32 v88, v88
	s_nop 0
	v_mul_f32_e32 v88, v89, v88
	v_mul_f32_e32 v83, v83, v88
	v_cvt_pk_bf16_f32 v88, v82, v83
	v_mul_f32_e32 v82, 0xbfb8aa3b, v92
	v_mul_f32_e32 v83, 0xbfb8aa3b, v93
	v_exp_f32_e32 v82, v82
	v_exp_f32_e32 v83, v83
	v_add_f32_e32 v82, 1.0, v82
	v_add_f32_e32 v83, 1.0, v83
	v_rcp_f32_e32 v82, v82
	v_rcp_f32_e32 v83, v83
	v_mul_f32_e32 v82, v92, v82
	v_mul_f32_e32 v83, v93, v83
	v_mul_f32_e32 v82, v84, v82
	v_mul_f32_e32 v83, v85, v83
	v_cvt_pk_bf16_f32 v89, v82, v83
	v_mad_i64_i32 v[82:83], s[4:5], v100, s2, v[114:115]
	v_lshl_add_u64 v[82:83], v[82:83], 0, v[116:117]
	global_store_dwordx4 v[82:83], v[86:89], off
	s_nop 1
	v_mov_b64_e32 v[82:83], v[196:197]
	v_or_b32_e32 v84, 48, v140
	v_ffbh_u32_e32 v85, v83
	v_min_u32_e32 v85, 32, v85
	v_lshlrev_b64 v[82:83], v85, v[82:83]
	v_min_u32_e32 v82, 1, v82
	v_or_b32_e32 v82, v83, v82
	v_cvt_f32_u32_e32 v82, v82
	v_sub_u32_e32 v83, 32, v85
	v_ldexp_f32 v82, v82, v83
	v_fmamk_f32 v82, v82, 0x2e800000, v143
	v_cmp_gt_f32_e32 vcc, s90, v82
	v_mul_f32_e32 v83, 0x4b800000, v82
	s_nop 0
	v_cndmask_b32_e32 v82, v82, v83, vcc
	v_rsq_f32_e32 v82, v82
	s_nop 0
	v_mul_f32_e32 v83, 0x45800000, v82
	v_cndmask_b32_e32 v82, v82, v83, vcc
	v_pk_mul_f32 v[78:79], v[78:79], v[82:83] op_sel_hi:[1,0]
	v_pk_mul_f32 v[80:81], v[80:81], v[82:83] op_sel_hi:[1,0]
	v_pk_mul_f32 v[72:73], v[72:73], v[82:83] op_sel_hi:[1,0]
	v_pk_mul_f32 v[70:71], v[70:71], v[82:83] op_sel_hi:[1,0]
	v_mul_f32_e32 v83, 0xbfb8aa3b, v78
	v_exp_f32_e32 v83, v83
	s_nop 0
	v_add_f32_e32 v83, 1.0, v83
	v_rcp_f32_e32 v83, v83
	s_nop 0
	v_mul_f32_e32 v78, v78, v83
	v_mul_f32_e32 v70, v70, v78
	v_mul_f32_e32 v78, 0xbfb8aa3b, v79
	v_exp_f32_e32 v78, v78
	v_pk_mul_f32 v[66:67], v[66:67], v[82:83] op_sel_hi:[1,0]
	v_pk_mul_f32 v[76:77], v[76:77], v[82:83] op_sel_hi:[1,0]
	v_pk_mul_f32 v[68:69], v[68:69], v[82:83] op_sel_hi:[1,0]
	v_add_f32_e32 v78, 1.0, v78
	v_rcp_f32_e32 v78, v78
	s_nop 0
	v_mul_f32_e32 v78, v79, v78
	v_mul_f32_e32 v71, v71, v78
	v_cvt_pk_bf16_f32 v70, v70, v71
	v_mul_f32_e32 v71, 0xbfb8aa3b, v80
	v_exp_f32_e32 v71, v71
	s_nop 0
	v_add_f32_e32 v71, 1.0, v71
	v_rcp_f32_e32 v71, v71
	s_nop 0
	v_mul_f32_e32 v71, v80, v71
	v_mul_f32_e32 v71, v72, v71
	v_mul_f32_e32 v72, 0xbfb8aa3b, v81
	v_exp_f32_e32 v72, v72
	s_nop 0
	v_add_f32_e32 v72, 1.0, v72
	v_rcp_f32_e32 v72, v72
	s_nop 0
	v_mul_f32_e32 v72, v81, v72
	v_mul_f32_e32 v72, v73, v72
	v_cvt_pk_bf16_f32 v71, v71, v72
	v_pk_mul_f32 v[72:73], v[74:75], v[82:83] op_sel_hi:[1,0]
	s_nop 0
	v_mul_f32_e32 v74, 0xbfb8aa3b, v72
	v_exp_f32_e32 v74, v74
	s_nop 0
	v_add_f32_e32 v74, 1.0, v74
	v_rcp_f32_e32 v74, v74
	s_nop 0
	v_mul_f32_e32 v72, v72, v74
	v_mul_f32_e32 v66, v66, v72
	v_mul_f32_e32 v72, 0xbfb8aa3b, v73
	v_exp_f32_e32 v72, v72
	s_nop 0
	v_add_f32_e32 v72, 1.0, v72
	v_rcp_f32_e32 v72, v72
	s_nop 0
	v_mul_f32_e32 v72, v73, v72
	v_mul_f32_e32 v67, v67, v72
	v_cvt_pk_bf16_f32 v72, v66, v67
	v_mul_f32_e32 v66, 0xbfb8aa3b, v76
	v_mul_f32_e32 v67, 0xbfb8aa3b, v77
	v_exp_f32_e32 v66, v66
	v_exp_f32_e32 v67, v67
	v_add_f32_e32 v66, 1.0, v66
	v_add_f32_e32 v67, 1.0, v67
	v_rcp_f32_e32 v66, v66
	v_rcp_f32_e32 v67, v67
	v_mul_f32_e32 v66, v76, v66
	v_mul_f32_e32 v67, v77, v67
	v_mul_f32_e32 v66, v68, v66
	v_mul_f32_e32 v67, v69, v67
	v_cvt_pk_bf16_f32 v73, v66, v67
	v_mad_i64_i32 v[66:67], s[4:5], v84, s2, v[114:115]
	v_lshl_add_u64 v[66:67], v[66:67], 0, v[116:117]
	global_store_dwordx4 v[66:67], v[70:73], off
	s_nop 1
	v_mov_b64_e32 v[66:67], v[198:199]
	v_add_u32_e32 v68, 0x80, v140
	v_ffbh_u32_e32 v69, v67
	v_min_u32_e32 v69, 32, v69
	v_lshlrev_b64 v[66:67], v69, v[66:67]
	v_min_u32_e32 v66, 1, v66
	v_or_b32_e32 v66, v67, v66
	v_cvt_f32_u32_e32 v66, v66
	v_sub_u32_e32 v67, 32, v69
	v_ldexp_f32 v66, v66, v67
	v_fmamk_f32 v66, v66, 0x2e800000, v143
	v_cmp_gt_f32_e32 vcc, s90, v66
	v_mul_f32_e32 v67, 0x4b800000, v66
	s_nop 0
	v_cndmask_b32_e32 v66, v66, v67, vcc
	v_rsq_f32_e32 v66, v66
	s_nop 0
	v_mul_f32_e32 v67, 0x45800000, v66
	v_cndmask_b32_e32 v66, v66, v67, vcc
	v_pk_mul_f32 v[62:63], v[62:63], v[66:67] op_sel_hi:[1,0]
	v_pk_mul_f32 v[64:65], v[64:65], v[66:67] op_sel_hi:[1,0]
	v_pk_mul_f32 v[56:57], v[56:57], v[66:67] op_sel_hi:[1,0]
	v_pk_mul_f32 v[54:55], v[54:55], v[66:67] op_sel_hi:[1,0]
	v_mul_f32_e32 v67, 0xbfb8aa3b, v62
	v_exp_f32_e32 v67, v67
	s_nop 0
	v_add_f32_e32 v67, 1.0, v67
	v_rcp_f32_e32 v67, v67
	s_nop 0
	v_mul_f32_e32 v62, v62, v67
	v_mul_f32_e32 v54, v54, v62
	v_mul_f32_e32 v62, 0xbfb8aa3b, v63
	v_exp_f32_e32 v62, v62
	v_pk_mul_f32 v[50:51], v[50:51], v[66:67] op_sel_hi:[1,0]
	v_pk_mul_f32 v[60:61], v[60:61], v[66:67] op_sel_hi:[1,0]
	v_pk_mul_f32 v[52:53], v[52:53], v[66:67] op_sel_hi:[1,0]
	v_add_f32_e32 v62, 1.0, v62
	v_rcp_f32_e32 v62, v62
	s_nop 0
	v_mul_f32_e32 v62, v63, v62
	v_mul_f32_e32 v55, v55, v62
	v_cvt_pk_bf16_f32 v54, v54, v55
	v_mul_f32_e32 v55, 0xbfb8aa3b, v64
	v_exp_f32_e32 v55, v55
	s_nop 0
	v_add_f32_e32 v55, 1.0, v55
	v_rcp_f32_e32 v55, v55
	s_nop 0
	v_mul_f32_e32 v55, v64, v55
	v_mul_f32_e32 v55, v56, v55
	v_mul_f32_e32 v56, 0xbfb8aa3b, v65
	v_exp_f32_e32 v56, v56
	s_nop 0
	v_add_f32_e32 v56, 1.0, v56
	v_rcp_f32_e32 v56, v56
	s_nop 0
	v_mul_f32_e32 v56, v65, v56
	v_mul_f32_e32 v56, v57, v56
	v_cvt_pk_bf16_f32 v55, v55, v56
	v_pk_mul_f32 v[56:57], v[58:59], v[66:67] op_sel_hi:[1,0]
	s_nop 0
	v_mul_f32_e32 v58, 0xbfb8aa3b, v56
	v_exp_f32_e32 v58, v58
	s_nop 0
	v_add_f32_e32 v58, 1.0, v58
	v_rcp_f32_e32 v58, v58
	s_nop 0
	v_mul_f32_e32 v56, v56, v58
	v_mul_f32_e32 v50, v50, v56
	v_mul_f32_e32 v56, 0xbfb8aa3b, v57
	v_exp_f32_e32 v56, v56
	s_nop 0
	v_add_f32_e32 v56, 1.0, v56
	v_rcp_f32_e32 v56, v56
	s_nop 0
	v_mul_f32_e32 v56, v57, v56
	v_mul_f32_e32 v51, v51, v56
	v_cvt_pk_bf16_f32 v56, v50, v51
	v_mul_f32_e32 v50, 0xbfb8aa3b, v60
	v_mul_f32_e32 v51, 0xbfb8aa3b, v61
	v_exp_f32_e32 v50, v50
	v_exp_f32_e32 v51, v51
	v_add_f32_e32 v50, 1.0, v50
	v_add_f32_e32 v51, 1.0, v51
	v_rcp_f32_e32 v50, v50
	v_rcp_f32_e32 v51, v51
	v_mul_f32_e32 v50, v60, v50
	v_mul_f32_e32 v51, v61, v51
	v_mul_f32_e32 v50, v52, v50
	v_mul_f32_e32 v51, v53, v51
	v_cvt_pk_bf16_f32 v57, v50, v51
	v_mad_i64_i32 v[50:51], s[4:5], v68, s2, v[114:115]
	v_lshl_add_u64 v[50:51], v[50:51], 0, v[116:117]
	global_store_dwordx4 v[50:51], v[54:57], off
	s_nop 1
	v_mov_b64_e32 v[50:51], v[200:201]
	v_add_u32_e32 v52, 0x90, v140
	v_ffbh_u32_e32 v53, v51
	v_min_u32_e32 v53, 32, v53
	v_lshlrev_b64 v[50:51], v53, v[50:51]
	v_min_u32_e32 v50, 1, v50
	v_or_b32_e32 v50, v51, v50
	v_cvt_f32_u32_e32 v50, v50
	v_sub_u32_e32 v51, 32, v53
	v_ldexp_f32 v50, v50, v51
	v_fmamk_f32 v50, v50, 0x2e800000, v143
	v_cmp_gt_f32_e32 vcc, s90, v50
	v_mul_f32_e32 v51, 0x4b800000, v50
	s_nop 0
	v_cndmask_b32_e32 v50, v50, v51, vcc
	v_rsq_f32_e32 v50, v50
	s_nop 0
	v_mul_f32_e32 v51, 0x45800000, v50
	v_cndmask_b32_e32 v50, v50, v51, vcc
	v_pk_mul_f32 v[46:47], v[46:47], v[50:51] op_sel_hi:[1,0]
	v_pk_mul_f32 v[48:49], v[48:49], v[50:51] op_sel_hi:[1,0]
	v_pk_mul_f32 v[40:41], v[40:41], v[50:51] op_sel_hi:[1,0]
	v_pk_mul_f32 v[38:39], v[38:39], v[50:51] op_sel_hi:[1,0]
	v_mul_f32_e32 v51, 0xbfb8aa3b, v46
	v_exp_f32_e32 v51, v51
	s_nop 0
	v_add_f32_e32 v51, 1.0, v51
	v_rcp_f32_e32 v51, v51
	s_nop 0
	v_mul_f32_e32 v46, v46, v51
	v_mul_f32_e32 v38, v38, v46
	v_mul_f32_e32 v46, 0xbfb8aa3b, v47
	v_exp_f32_e32 v46, v46
	v_pk_mul_f32 v[34:35], v[34:35], v[50:51] op_sel_hi:[1,0]
	v_pk_mul_f32 v[44:45], v[44:45], v[50:51] op_sel_hi:[1,0]
	v_pk_mul_f32 v[36:37], v[36:37], v[50:51] op_sel_hi:[1,0]
	v_add_f32_e32 v46, 1.0, v46
	v_rcp_f32_e32 v46, v46
	s_nop 0
	v_mul_f32_e32 v46, v47, v46
	v_mul_f32_e32 v39, v39, v46
	v_cvt_pk_bf16_f32 v38, v38, v39
	v_mul_f32_e32 v39, 0xbfb8aa3b, v48
	v_exp_f32_e32 v39, v39
	s_nop 0
	v_add_f32_e32 v39, 1.0, v39
	v_rcp_f32_e32 v39, v39
	s_nop 0
	v_mul_f32_e32 v39, v48, v39
	v_mul_f32_e32 v39, v40, v39
	v_mul_f32_e32 v40, 0xbfb8aa3b, v49
	v_exp_f32_e32 v40, v40
	s_nop 0
	v_add_f32_e32 v40, 1.0, v40
	v_rcp_f32_e32 v40, v40
	s_nop 0
	v_mul_f32_e32 v40, v49, v40
	v_mul_f32_e32 v40, v41, v40
	v_cvt_pk_bf16_f32 v39, v39, v40
	v_pk_mul_f32 v[40:41], v[42:43], v[50:51] op_sel_hi:[1,0]
	s_nop 0
	v_mul_f32_e32 v42, 0xbfb8aa3b, v40
	v_exp_f32_e32 v42, v42
	s_nop 0
	v_add_f32_e32 v42, 1.0, v42
	v_rcp_f32_e32 v42, v42
	s_nop 0
	v_mul_f32_e32 v40, v40, v42
	v_mul_f32_e32 v34, v34, v40
	v_mul_f32_e32 v40, 0xbfb8aa3b, v41
	v_exp_f32_e32 v40, v40
	s_nop 0
	v_add_f32_e32 v40, 1.0, v40
	v_rcp_f32_e32 v40, v40
	s_nop 0
	v_mul_f32_e32 v40, v41, v40
	v_mul_f32_e32 v35, v35, v40
	v_cvt_pk_bf16_f32 v40, v34, v35
	v_mul_f32_e32 v34, 0xbfb8aa3b, v44
	v_mul_f32_e32 v35, 0xbfb8aa3b, v45
	v_exp_f32_e32 v34, v34
	v_exp_f32_e32 v35, v35
	v_add_f32_e32 v34, 1.0, v34
	v_add_f32_e32 v35, 1.0, v35
	v_rcp_f32_e32 v34, v34
	v_rcp_f32_e32 v35, v35
	v_mul_f32_e32 v34, v44, v34
	v_mul_f32_e32 v35, v45, v35
	v_mul_f32_e32 v34, v36, v34
	v_mul_f32_e32 v35, v37, v35
	v_cvt_pk_bf16_f32 v41, v34, v35
	v_mad_i64_i32 v[34:35], s[4:5], v52, s2, v[114:115]
	v_lshl_add_u64 v[34:35], v[34:35], 0, v[116:117]
	global_store_dwordx4 v[34:35], v[38:41], off
	s_nop 1
	v_mov_b64_e32 v[34:35], v[202:203]
	v_add_u32_e32 v36, 0xa0, v140
	v_ffbh_u32_e32 v37, v35
	v_min_u32_e32 v37, 32, v37
	v_lshlrev_b64 v[34:35], v37, v[34:35]
	v_min_u32_e32 v34, 1, v34
	v_or_b32_e32 v34, v35, v34
	v_cvt_f32_u32_e32 v34, v34
	v_sub_u32_e32 v35, 32, v37
	v_ldexp_f32 v34, v34, v35
	v_fmamk_f32 v34, v34, 0x2e800000, v143
	v_cmp_gt_f32_e32 vcc, s90, v34
	v_mul_f32_e32 v35, 0x4b800000, v34
	s_nop 0
	v_cndmask_b32_e32 v34, v34, v35, vcc
	v_rsq_f32_e32 v34, v34
	s_nop 0
	v_mul_f32_e32 v35, 0x45800000, v34
	v_cndmask_b32_e32 v34, v34, v35, vcc
	v_pk_mul_f32 v[30:31], v[30:31], v[34:35] op_sel_hi:[1,0]
	v_pk_mul_f32 v[32:33], v[32:33], v[34:35] op_sel_hi:[1,0]
	v_pk_mul_f32 v[24:25], v[24:25], v[34:35] op_sel_hi:[1,0]
	v_pk_mul_f32 v[22:23], v[22:23], v[34:35] op_sel_hi:[1,0]
	v_mul_f32_e32 v35, 0xbfb8aa3b, v30
	v_exp_f32_e32 v35, v35
	s_nop 0
	v_add_f32_e32 v35, 1.0, v35
	v_rcp_f32_e32 v35, v35
	s_nop 0
	v_mul_f32_e32 v30, v30, v35
	v_mul_f32_e32 v22, v22, v30
	v_mul_f32_e32 v30, 0xbfb8aa3b, v31
	v_exp_f32_e32 v30, v30
	v_pk_mul_f32 v[18:19], v[18:19], v[34:35] op_sel_hi:[1,0]
	v_pk_mul_f32 v[28:29], v[28:29], v[34:35] op_sel_hi:[1,0]
	v_pk_mul_f32 v[20:21], v[20:21], v[34:35] op_sel_hi:[1,0]
	v_add_f32_e32 v30, 1.0, v30
	v_rcp_f32_e32 v30, v30
	s_nop 0
	v_mul_f32_e32 v30, v31, v30
	v_mul_f32_e32 v23, v23, v30
	v_cvt_pk_bf16_f32 v22, v22, v23
	v_mul_f32_e32 v23, 0xbfb8aa3b, v32
	v_exp_f32_e32 v23, v23
	s_nop 0
	v_add_f32_e32 v23, 1.0, v23
	v_rcp_f32_e32 v23, v23
	s_nop 0
	v_mul_f32_e32 v23, v32, v23
	v_mul_f32_e32 v23, v24, v23
	v_mul_f32_e32 v24, 0xbfb8aa3b, v33
	v_exp_f32_e32 v24, v24
	s_nop 0
	v_add_f32_e32 v24, 1.0, v24
	v_rcp_f32_e32 v24, v24
	s_nop 0
	v_mul_f32_e32 v24, v33, v24
	v_mul_f32_e32 v24, v25, v24
	v_cvt_pk_bf16_f32 v23, v23, v24
	v_pk_mul_f32 v[24:25], v[26:27], v[34:35] op_sel_hi:[1,0]
	s_nop 0
	v_mul_f32_e32 v26, 0xbfb8aa3b, v24
	v_exp_f32_e32 v26, v26
	s_nop 0
	v_add_f32_e32 v26, 1.0, v26
	v_rcp_f32_e32 v26, v26
	s_nop 0
	v_mul_f32_e32 v24, v24, v26
	v_mul_f32_e32 v18, v18, v24
	v_mul_f32_e32 v24, 0xbfb8aa3b, v25
	v_exp_f32_e32 v24, v24
	s_nop 0
	v_add_f32_e32 v24, 1.0, v24
	v_rcp_f32_e32 v24, v24
	s_nop 0
	v_mul_f32_e32 v24, v25, v24
	v_mul_f32_e32 v19, v19, v24
	v_cvt_pk_bf16_f32 v24, v18, v19
	v_mul_f32_e32 v18, 0xbfb8aa3b, v28
	v_mul_f32_e32 v19, 0xbfb8aa3b, v29
	v_exp_f32_e32 v18, v18
	v_exp_f32_e32 v19, v19
	v_add_f32_e32 v18, 1.0, v18
	v_add_f32_e32 v19, 1.0, v19
	v_rcp_f32_e32 v18, v18
	v_rcp_f32_e32 v19, v19
	v_mul_f32_e32 v18, v28, v18
	v_mul_f32_e32 v19, v29, v19
	v_mul_f32_e32 v18, v20, v18
	v_mul_f32_e32 v19, v21, v19
	v_cvt_pk_bf16_f32 v25, v18, v19
	v_mad_i64_i32 v[18:19], s[4:5], v36, s2, v[114:115]
	v_lshl_add_u64 v[18:19], v[18:19], 0, v[116:117]
	global_store_dwordx4 v[18:19], v[22:25], off
	s_nop 1
	v_mov_b64_e32 v[18:19], v[204:205]
	v_add_u32_e32 v20, 0xb0, v140
	v_ffbh_u32_e32 v21, v19
	v_min_u32_e32 v21, 32, v21
	v_lshlrev_b64 v[18:19], v21, v[18:19]
	v_min_u32_e32 v18, 1, v18
	v_or_b32_e32 v18, v19, v18
	v_cvt_f32_u32_e32 v18, v18
	v_sub_u32_e32 v19, 32, v21
	v_ldexp_f32 v18, v18, v19
	v_fmamk_f32 v18, v18, 0x2e800000, v143
	v_cmp_gt_f32_e32 vcc, s90, v18
	v_mul_f32_e32 v19, 0x4b800000, v18
	s_nop 0
	v_cndmask_b32_e32 v18, v18, v19, vcc
	v_rsq_f32_e32 v18, v18
	s_nop 0
	v_mul_f32_e32 v19, 0x45800000, v18
	v_cndmask_b32_e32 v18, v18, v19, vcc
	v_pk_mul_f32 v[14:15], v[14:15], v[18:19] op_sel_hi:[1,0]
	v_pk_mul_f32 v[16:17], v[16:17], v[18:19] op_sel_hi:[1,0]
	v_pk_mul_f32 v[8:9], v[8:9], v[18:19] op_sel_hi:[1,0]
	v_pk_mul_f32 v[6:7], v[6:7], v[18:19] op_sel_hi:[1,0]
	v_mul_f32_e32 v19, 0xbfb8aa3b, v14
	v_exp_f32_e32 v19, v19
	s_and_b64 vcc, exec, s[6:7]
	v_add_f32_e32 v19, 1.0, v19
	v_rcp_f32_e32 v19, v19
	s_nop 0
	v_mul_f32_e32 v14, v14, v19
	v_mul_f32_e32 v6, v6, v14
	v_mul_f32_e32 v14, 0xbfb8aa3b, v15
	v_exp_f32_e32 v14, v14
	v_pk_mul_f32 v[2:3], v[2:3], v[18:19] op_sel_hi:[1,0]
	v_pk_mul_f32 v[12:13], v[12:13], v[18:19] op_sel_hi:[1,0]
	v_pk_mul_f32 v[4:5], v[4:5], v[18:19] op_sel_hi:[1,0]
	v_add_f32_e32 v14, 1.0, v14
	v_rcp_f32_e32 v14, v14
	s_nop 0
	v_mul_f32_e32 v14, v15, v14
	v_mul_f32_e32 v7, v7, v14
	v_cvt_pk_bf16_f32 v6, v6, v7
	v_mul_f32_e32 v7, 0xbfb8aa3b, v16
	v_exp_f32_e32 v7, v7
	s_nop 0
	v_add_f32_e32 v7, 1.0, v7
	v_rcp_f32_e32 v7, v7
	s_nop 0
	v_mul_f32_e32 v7, v16, v7
	v_mul_f32_e32 v7, v8, v7
	v_mul_f32_e32 v8, 0xbfb8aa3b, v17
	v_exp_f32_e32 v8, v8
	s_nop 0
	v_add_f32_e32 v8, 1.0, v8
	v_rcp_f32_e32 v8, v8
	s_nop 0
	v_mul_f32_e32 v8, v17, v8
	v_mul_f32_e32 v8, v9, v8
	v_cvt_pk_bf16_f32 v7, v7, v8
	v_pk_mul_f32 v[8:9], v[10:11], v[18:19] op_sel_hi:[1,0]
	s_nop 0
	v_mul_f32_e32 v10, 0xbfb8aa3b, v8
	v_exp_f32_e32 v10, v10
	s_nop 0
	v_add_f32_e32 v10, 1.0, v10
	v_rcp_f32_e32 v10, v10
	s_nop 0
	v_mul_f32_e32 v8, v8, v10
	v_mul_f32_e32 v2, v2, v8
	v_mul_f32_e32 v8, 0xbfb8aa3b, v9
	v_exp_f32_e32 v8, v8
	s_nop 0
	v_add_f32_e32 v8, 1.0, v8
	v_rcp_f32_e32 v8, v8
	s_nop 0
	v_mul_f32_e32 v8, v9, v8
	v_mul_f32_e32 v3, v3, v8
	v_cvt_pk_bf16_f32 v8, v2, v3
	v_mul_f32_e32 v2, 0xbfb8aa3b, v12
	v_mul_f32_e32 v3, 0xbfb8aa3b, v13
	v_exp_f32_e32 v2, v2
	v_exp_f32_e32 v3, v3
	v_add_f32_e32 v2, 1.0, v2
	v_add_f32_e32 v3, 1.0, v3
	v_rcp_f32_e32 v2, v2
	v_rcp_f32_e32 v3, v3
	v_mul_f32_e32 v2, v12, v2
	v_mul_f32_e32 v3, v13, v3
	v_mul_f32_e32 v2, v4, v2
	v_mul_f32_e32 v3, v5, v3
	v_cvt_pk_bf16_f32 v9, v2, v3
	v_mad_i64_i32 v[2:3], s[4:5], v20, s2, v[114:115]
	v_lshl_add_u64 v[2:3], v[2:3], 0, v[116:117]
	s_mov_b32 s4, s8
	s_mov_b32 s2, s12
	global_store_dwordx4 v[2:3], v[6:9], off
	s_cbranch_vccz .LBB0_122
	s_waitcnt vmcnt(0)
	s_cmpk_gt_u32 s26, 0xff
	s_cbranch_scc1 .LBB0_129
	s_barrier

.LBB0_177:
	v_lshl_add_u32 v2, s81, 8, v153
	v_ashrrev_i32_e32 v3, 31, v2
	v_lshl_or_b32 v156, s0, 8, v165
	v_lshlrev_b64 v[160:161], 11, v[2:3]
	v_ashrrev_i32_e32 v157, 31, v156
	v_lshl_add_u64 v[160:161], s[94:95], 0, v[160:161]
	v_lshl_add_u64 v[160:161], v[156:157], 1, v[160:161]
	v_lshlrev_b32_e32 v250, 11, v2
	v_lshl_add_u32 v250, v156, 1, v250
	s_mov_b64 s[98:99], s[94:95]
	global_load_dwordx4 v[168:171], v250, s[98:99]
	global_load_dwordx4 v[180:183], v250, s[98:99] offset:256
	s_add_u32 s98, s98, 0x8000
	s_addc_u32 s99, s99, 0
	global_load_dwordx4 v[192:195], v250, s[98:99]
	global_load_dwordx4 v[196:199], v250, s[98:99] offset:256
	s_add_u32 s98, s98, 0x8000
	s_addc_u32 s99, s99, 0
	global_load_dwordx4 v[200:203], v250, s[98:99]
	global_load_dwordx4 v[204:207], v250, s[98:99] offset:256
	s_add_u32 s98, s98, 0x8000
	s_addc_u32 s99, s99, 0
	global_load_dwordx4 v[208:211], v250, s[98:99]
	global_load_dwordx4 v[212:215], v250, s[98:99] offset:256
	s_add_u32 s98, s98, 0x28000
	s_addc_u32 s99, s99, 0
	global_load_dwordx4 v[218:221], v250, s[98:99]
	global_load_dwordx4 v[222:225], v250, s[98:99] offset:256
	s_add_u32 s98, s98, 0x8000
	s_addc_u32 s99, s99, 0
	global_load_dwordx4 v[226:229], v250, s[98:99]
	global_load_dwordx4 v[230:233], v250, s[98:99] offset:256
	s_add_u32 s98, s98, 0x8000
	s_addc_u32 s99, s99, 0
	global_load_dwordx4 v[234:237], v250, s[98:99]
	global_load_dwordx4 v[238:241], v250, s[98:99] offset:256
	s_add_u32 s98, s98, 0x8000
	s_addc_u32 s99, s99, 0
	global_load_dwordx4 v[242:245], v250, s[98:99]
	global_load_dwordx4 v[246:249], v250, s[98:99] offset:256
	s_waitcnt lgkmcnt(0)
	v_pk_mul_f32 v[124:125], v[124:125], v[0:1] op_sel_hi:[1,0]
	v_pk_mul_f32 v[188:189], v[130:131], v[0:1] op_sel_hi:[1,0]
	v_pk_mul_f32 v[128:129], v[128:129], v[0:1] op_sel_hi:[1,0]
	v_pk_mul_f32 v[126:127], v[126:127], v[0:1] op_sel_hi:[1,0]
	v_pk_mul_f32 v[120:121], v[120:121], v[0:1] op_sel_hi:[1,0]
	v_pk_mul_f32 v[116:117], v[116:117], v[0:1] op_sel_hi:[1,0]
	s_andn2_b64 vcc, exec, s[34:35]
	s_waitcnt vmcnt(0)
	v_lshlrev_b32_e32 v144, 16, v170
	v_lshlrev_b32_e32 v130, 16, v168
	v_add_f32_e32 v124, v124, v144
	v_and_b32_e32 v144, 0xffff0000, v170
	v_add_f32_e32 v128, v128, v130
	v_and_b32_e32 v130, 0xffff0000, v168
	v_add_f32_e32 v125, v125, v144
	v_lshlrev_b32_e32 v144, 16, v171
	v_add_f32_e32 v131, v129, v130
	v_lshlrev_b32_e32 v129, 16, v169
	v_and_b32_e32 v130, 0xffff0000, v169
	v_add_f32_e32 v126, v126, v144
	v_and_b32_e32 v144, 0xffff0000, v171
	v_add_f32_e32 v129, v188, v129
	v_add_f32_e32 v130, v189, v130
	v_cvt_pk_bf16_f32 v168, v128, v131
	v_cvt_pk_bf16_f32 v169, v129, v130
	v_add_f32_e32 v127, v127, v144
	v_cvt_pk_bf16_f32 v170, v124, v125
	v_cvt_pk_bf16_f32 v171, v126, v127
	global_store_dwordx4 v[160:161], v[168:171], off
	s_nop 1
	v_mov_b64_e32 v[168:169], v[180:181]
	v_mov_b64_e32 v[170:171], v[182:183]
	v_pk_mul_f32 v[188:189], v[122:123], v[0:1] op_sel_hi:[1,0]
	v_lshlrev_b32_e32 v122, 16, v168
	v_add_f32_e32 v120, v120, v122
	v_and_b32_e32 v122, 0xffff0000, v168
	v_add_f32_e32 v123, v121, v122
	v_lshlrev_b32_e32 v121, 16, v169
	v_and_b32_e32 v122, 0xffff0000, v169
	v_add_f32_e32 v121, v188, v121
	v_add_f32_e32 v122, v189, v122
	v_pk_mul_f32 v[188:189], v[118:119], v[0:1] op_sel_hi:[1,0]
	v_lshlrev_b32_e32 v0, 16, v170
	v_add_f32_e32 v0, v116, v0
	v_and_b32_e32 v116, 0xffff0000, v170
	v_add_f32_e32 v118, v117, v116
	v_lshlrev_b32_e32 v116, 16, v171
	v_and_b32_e32 v117, 0xffff0000, v171
	v_cndmask_b32_e64 v119, 0, 1, s[34:35]
	v_add_f32_e32 v116, v188, v116
	v_add_f32_e32 v117, v189, v117
	v_cmp_ne_u32_e64 s[6:7], 1, v119
	v_cvt_pk_bf16_f32 v168, v120, v123
	v_cvt_pk_bf16_f32 v169, v121, v122
	v_cvt_pk_bf16_f32 v170, v0, v118
	v_cvt_pk_bf16_f32 v171, v116, v117
	global_store_dwordx4 v[160:161], v[168:171], off offset:256
	s_cbranch_vccnz .LBB0_181
	v_mul_f32_e32 v118, v118, v118
	v_mul_f32_e32 v119, v131, v131
	v_mul_f32_e32 v125, v125, v125
	v_fmac_f32_e32 v118, v0, v0
	v_fmac_f32_e32 v119, v128, v128
	v_fmac_f32_e32 v125, v124, v124
	v_mul_f32_e32 v123, v123, v123
	v_fmac_f32_e32 v118, v116, v116
	v_fmac_f32_e32 v119, v129, v129
	v_fmac_f32_e32 v125, v126, v126
	v_fmac_f32_e32 v123, v120, v120
	v_fmac_f32_e32 v118, v117, v117
	v_and_b32_e32 v117, 64, v177
	v_fmac_f32_e32 v119, v130, v130
	v_fmac_f32_e32 v125, v127, v127
	v_fmac_f32_e32 v123, v121, v121
	v_xor_b32_e32 v116, 16, v177
	v_add_u32_e32 v117, 64, v117
	v_add_f32_e32 v119, v119, v125
	v_fmac_f32_e32 v123, v122, v122
	v_cmp_lt_i32_e32 vcc, v116, v117
	v_add_f32_e32 v119, v119, v123
	v_add_f32_e32 v0, v118, v119
	v_cndmask_b32_e32 v116, v177, v116, vcc
	v_lshlrev_b32_e32 v116, 2, v116
	ds_bpermute_b32 v116, v116, v0
	s_waitcnt lgkmcnt(0)
	v_add_f32_e32 v0, v0, v116
	v_xor_b32_e32 v116, 32, v177
	v_cmp_lt_i32_e32 vcc, v116, v117
	s_nop 1
	v_cndmask_b32_e32 v116, v177, v116, vcc
	v_lshlrev_b32_e32 v116, 2, v116
	ds_bpermute_b32 v116, v116, v0
	s_and_saveexec_b64 s[2:3], s[8:9]
	s_cbranch_execz .LBB0_180
	s_waitcnt lgkmcnt(0)
	v_add_f32_e32 v0, v0, v116
	v_mul_f32_e32 v0, 0x4b800000, v0
	v_trunc_f32_e32 v0, v0
	v_mul_f32_e32 v116, 0x2f800000, v0
	v_floor_f32_e32 v117, v116
	v_fmac_f32_e32 v0, 0xcf800000, v117
	v_cvt_u32_f32_e32 v116, v0
	v_cvt_u32_f32_e32 v117, v117
	v_readlane_b32 s0, v255, 17
	v_readlane_b32 s1, v255, 18
	s_nop 1
	v_lshl_add_u64 v[118:119], v[2:3], 3, s[0:1]
	global_atomic_add_x2 v[118:119], v[116:117], off

.LBB0_183:
	s_waitcnt lgkmcnt(0)
	v_or_b32_e32 v116, 16, v2
	v_ashrrev_i32_e32 v117, 31, v116
	v_lshlrev_b64 v[116:117], 11, v[116:117]
	v_lshl_add_u64 v[116:117], s[94:95], 0, v[116:117]
	v_lshl_add_u64 v[116:117], v[156:157], 1, v[116:117]
	s_nop 1
	v_mov_b64_e32 v[118:119], v[192:193]
	v_mov_b64_e32 v[120:121], v[194:195]
	v_pk_mul_f32 v[122:123], v[114:115], v[0:1] op_sel_hi:[1,0]
	v_pk_mul_f32 v[112:113], v[112:113], v[0:1] op_sel_hi:[1,0]
	v_pk_mul_f32 v[108:109], v[108:109], v[0:1] op_sel_hi:[1,0]
	v_pk_mul_f32 v[110:111], v[110:111], v[0:1] op_sel_hi:[1,0]
	v_pk_mul_f32 v[104:105], v[104:105], v[0:1] op_sel_hi:[1,0]
	v_pk_mul_f32 v[102:103], v[102:103], v[0:1] op_sel_hi:[1,0]
	v_pk_mul_f32 v[100:101], v[100:101], v[0:1] op_sel_hi:[1,0]
	s_and_b64 vcc, exec, s[6:7]
	v_lshlrev_b32_e32 v114, 16, v118
	v_add_f32_e32 v112, v112, v114
	v_and_b32_e32 v114, 0xffff0000, v118
	v_add_f32_e32 v115, v113, v114
	v_lshlrev_b32_e32 v113, 16, v119
	v_add_f32_e32 v113, v122, v113
	v_lshlrev_b32_e32 v122, 16, v120
	v_and_b32_e32 v120, 0xffff0000, v120
	v_add_f32_e32 v109, v109, v120
	v_lshlrev_b32_e32 v120, 16, v121
	v_and_b32_e32 v114, 0xffff0000, v119
	v_add_f32_e32 v110, v110, v120
	v_and_b32_e32 v120, 0xffff0000, v121
	v_add_f32_e32 v114, v123, v114
	v_cvt_pk_bf16_f32 v118, v112, v115
	v_cvt_pk_bf16_f32 v119, v113, v114
	v_add_f32_e32 v108, v108, v122
	v_add_f32_e32 v111, v111, v120
	v_cvt_pk_bf16_f32 v120, v108, v109
	v_cvt_pk_bf16_f32 v121, v110, v111
	global_store_dwordx4 v[116:117], v[118:121], off
	s_nop 1
	v_mov_b64_e32 v[118:119], v[196:197]
	v_mov_b64_e32 v[120:121], v[198:199]
	v_pk_mul_f32 v[122:123], v[106:107], v[0:1] op_sel_hi:[1,0]
	v_lshlrev_b32_e32 v0, 16, v120
	v_lshlrev_b32_e32 v106, 16, v118
	v_add_f32_e32 v0, v100, v0
	v_and_b32_e32 v100, 0xffff0000, v120
	v_add_f32_e32 v104, v104, v106
	v_and_b32_e32 v106, 0xffff0000, v118
	v_add_f32_e32 v100, v101, v100
	v_lshlrev_b32_e32 v101, 16, v121
	v_add_f32_e32 v107, v105, v106
	v_lshlrev_b32_e32 v105, 16, v119
	v_and_b32_e32 v106, 0xffff0000, v119
	v_add_f32_e32 v101, v102, v101
	v_and_b32_e32 v102, 0xffff0000, v121
	v_add_f32_e32 v105, v122, v105
	v_add_f32_e32 v106, v123, v106
	v_add_f32_e32 v102, v103, v102
	v_cvt_pk_bf16_f32 v118, v104, v107
	v_cvt_pk_bf16_f32 v119, v105, v106
	v_cvt_pk_bf16_f32 v120, v0, v100
	v_cvt_pk_bf16_f32 v121, v101, v102
	global_store_dwordx4 v[116:117], v[118:121], off offset:256
	s_cbranch_vccnz .LBB0_187
	v_mul_f32_e32 v103, v115, v115
	v_mul_f32_e32 v109, v109, v109
	v_fmac_f32_e32 v103, v112, v112
	v_fmac_f32_e32 v109, v108, v108
	v_mul_f32_e32 v107, v107, v107
	v_fmac_f32_e32 v103, v113, v113
	v_fmac_f32_e32 v109, v110, v110
	v_fmac_f32_e32 v107, v104, v104
	v_mul_f32_e32 v100, v100, v100
	v_fmac_f32_e32 v103, v114, v114
	v_fmac_f32_e32 v109, v111, v111
	v_fmac_f32_e32 v107, v105, v105
	v_fmac_f32_e32 v100, v0, v0
	v_add_f32_e32 v103, v103, v109
	v_fmac_f32_e32 v107, v106, v106
	v_fmac_f32_e32 v100, v101, v101
	v_add_f32_e32 v103, v103, v107
	v_fmac_f32_e32 v100, v102, v102
	v_and_b32_e32 v101, 64, v177
	v_add_f32_e32 v0, v100, v103
	v_xor_b32_e32 v100, 16, v177
	v_add_u32_e32 v101, 64, v101
	v_cmp_lt_i32_e32 vcc, v100, v101
	s_nop 1
	v_cndmask_b32_e32 v100, v177, v100, vcc
	v_lshlrev_b32_e32 v100, 2, v100
	ds_bpermute_b32 v100, v100, v0
	s_waitcnt lgkmcnt(0)
	v_add_f32_e32 v0, v0, v100
	v_xor_b32_e32 v100, 32, v177
	v_cmp_lt_i32_e32 vcc, v100, v101
	s_nop 1
	v_cndmask_b32_e32 v100, v177, v100, vcc
	v_lshlrev_b32_e32 v100, 2, v100
	ds_bpermute_b32 v100, v100, v0
	s_and_saveexec_b64 s[2:3], s[8:9]
	s_cbranch_execz .LBB0_186
	s_waitcnt lgkmcnt(0)
	v_add_f32_e32 v0, v0, v100
	v_mul_f32_e32 v0, 0x4b800000, v0
	v_trunc_f32_e32 v0, v0
	v_mul_f32_e32 v100, 0x2f800000, v0
	v_floor_f32_e32 v101, v100
	v_fmac_f32_e32 v0, 0xcf800000, v101
	v_cvt_u32_f32_e32 v100, v0
	v_cvt_u32_f32_e32 v101, v101
	v_readlane_b32 s0, v255, 17
	v_readlane_b32 s1, v255, 18
	s_nop 1
	v_lshl_add_u64 v[102:103], v[2:3], 3, s[0:1]
	global_atomic_add_x2 v[102:103], v[100:101], off offset:128

.LBB0_189:
	s_waitcnt lgkmcnt(0)
	v_or_b32_e32 v100, 32, v2
	v_ashrrev_i32_e32 v101, 31, v100
	v_lshlrev_b64 v[100:101], 11, v[100:101]
	v_lshl_add_u64 v[100:101], s[94:95], 0, v[100:101]
	v_lshl_add_u64 v[100:101], v[156:157], 1, v[100:101]
	s_nop 1
	v_mov_b64_e32 v[102:103], v[200:201]
	v_mov_b64_e32 v[104:105], v[202:203]
	v_pk_mul_f32 v[106:107], v[98:99], v[0:1] op_sel_hi:[1,0]
	v_pk_mul_f32 v[96:97], v[96:97], v[0:1] op_sel_hi:[1,0]
	v_pk_mul_f32 v[92:93], v[92:93], v[0:1] op_sel_hi:[1,0]
	v_pk_mul_f32 v[94:95], v[94:95], v[0:1] op_sel_hi:[1,0]
	v_pk_mul_f32 v[88:89], v[88:89], v[0:1] op_sel_hi:[1,0]
	v_pk_mul_f32 v[86:87], v[86:87], v[0:1] op_sel_hi:[1,0]
	v_pk_mul_f32 v[84:85], v[84:85], v[0:1] op_sel_hi:[1,0]
	s_and_b64 vcc, exec, s[6:7]
	v_lshlrev_b32_e32 v98, 16, v102
	v_add_f32_e32 v96, v96, v98
	v_and_b32_e32 v98, 0xffff0000, v102
	v_add_f32_e32 v99, v97, v98
	v_lshlrev_b32_e32 v97, 16, v103
	v_add_f32_e32 v97, v106, v97
	v_lshlrev_b32_e32 v106, 16, v104
	v_and_b32_e32 v104, 0xffff0000, v104
	v_add_f32_e32 v93, v93, v104
	v_lshlrev_b32_e32 v104, 16, v105
	v_and_b32_e32 v98, 0xffff0000, v103
	v_add_f32_e32 v94, v94, v104
	v_and_b32_e32 v104, 0xffff0000, v105
	v_add_f32_e32 v98, v107, v98
	v_cvt_pk_bf16_f32 v102, v96, v99
	v_cvt_pk_bf16_f32 v103, v97, v98
	v_add_f32_e32 v92, v92, v106
	v_add_f32_e32 v95, v95, v104
	v_cvt_pk_bf16_f32 v104, v92, v93
	v_cvt_pk_bf16_f32 v105, v94, v95
	global_store_dwordx4 v[100:101], v[102:105], off
	s_nop 1
	v_mov_b64_e32 v[102:103], v[204:205]
	v_mov_b64_e32 v[104:105], v[206:207]
	v_pk_mul_f32 v[106:107], v[90:91], v[0:1] op_sel_hi:[1,0]
	v_lshlrev_b32_e32 v0, 16, v104
	v_lshlrev_b32_e32 v90, 16, v102
	v_add_f32_e32 v0, v84, v0
	v_and_b32_e32 v84, 0xffff0000, v104
	v_add_f32_e32 v88, v88, v90
	v_and_b32_e32 v90, 0xffff0000, v102
	v_add_f32_e32 v84, v85, v84
	v_lshlrev_b32_e32 v85, 16, v105
	v_add_f32_e32 v91, v89, v90
	v_lshlrev_b32_e32 v89, 16, v103
	v_and_b32_e32 v90, 0xffff0000, v103
	v_add_f32_e32 v85, v86, v85
	v_and_b32_e32 v86, 0xffff0000, v105
	v_add_f32_e32 v89, v106, v89
	v_add_f32_e32 v90, v107, v90
	v_add_f32_e32 v86, v87, v86
	v_cvt_pk_bf16_f32 v102, v88, v91
	v_cvt_pk_bf16_f32 v103, v89, v90
	v_cvt_pk_bf16_f32 v104, v0, v84
	v_cvt_pk_bf16_f32 v105, v85, v86
	global_store_dwordx4 v[100:101], v[102:105], off offset:256
	s_cbranch_vccnz .LBB0_193
	v_mul_f32_e32 v87, v99, v99
	v_mul_f32_e32 v93, v93, v93
	v_fmac_f32_e32 v87, v96, v96
	v_fmac_f32_e32 v93, v92, v92
	v_mul_f32_e32 v91, v91, v91
	v_fmac_f32_e32 v87, v97, v97
	v_fmac_f32_e32 v93, v94, v94
	v_fmac_f32_e32 v91, v88, v88
	v_mul_f32_e32 v84, v84, v84
	v_fmac_f32_e32 v87, v98, v98
	v_fmac_f32_e32 v93, v95, v95
	v_fmac_f32_e32 v91, v89, v89
	v_fmac_f32_e32 v84, v0, v0
	v_add_f32_e32 v87, v87, v93
	v_fmac_f32_e32 v91, v90, v90
	v_fmac_f32_e32 v84, v85, v85
	v_add_f32_e32 v87, v87, v91
	v_fmac_f32_e32 v84, v86, v86
	v_and_b32_e32 v85, 64, v177
	v_add_f32_e32 v0, v84, v87
	v_xor_b32_e32 v84, 16, v177
	v_add_u32_e32 v85, 64, v85
	v_cmp_lt_i32_e32 vcc, v84, v85
	s_nop 1
	v_cndmask_b32_e32 v84, v177, v84, vcc
	v_lshlrev_b32_e32 v84, 2, v84
	ds_bpermute_b32 v84, v84, v0
	s_waitcnt lgkmcnt(0)
	v_add_f32_e32 v0, v0, v84
	v_xor_b32_e32 v84, 32, v177
	v_cmp_lt_i32_e32 vcc, v84, v85
	s_nop 1
	v_cndmask_b32_e32 v84, v177, v84, vcc
	v_lshlrev_b32_e32 v84, 2, v84
	ds_bpermute_b32 v84, v84, v0
	s_and_saveexec_b64 s[2:3], s[8:9]
	s_cbranch_execz .LBB0_192
	s_waitcnt lgkmcnt(0)
	v_add_f32_e32 v0, v0, v84
	v_mul_f32_e32 v0, 0x4b800000, v0
	v_trunc_f32_e32 v0, v0
	v_mul_f32_e32 v84, 0x2f800000, v0
	v_floor_f32_e32 v85, v84
	v_fmac_f32_e32 v0, 0xcf800000, v85
	v_cvt_u32_f32_e32 v84, v0
	v_cvt_u32_f32_e32 v85, v85
	v_readlane_b32 s0, v255, 17
	v_readlane_b32 s1, v255, 18
	s_nop 1
	v_lshl_add_u64 v[86:87], v[2:3], 3, s[0:1]
	global_atomic_add_x2 v[86:87], v[84:85], off offset:256

.LBB0_195:
	s_waitcnt lgkmcnt(0)
	v_or_b32_e32 v84, 48, v2
	v_ashrrev_i32_e32 v85, 31, v84
	v_lshlrev_b64 v[84:85], 11, v[84:85]
	v_lshl_add_u64 v[84:85], s[94:95], 0, v[84:85]
	v_lshl_add_u64 v[84:85], v[156:157], 1, v[84:85]
	s_nop 1
	v_mov_b64_e32 v[86:87], v[208:209]
	v_mov_b64_e32 v[88:89], v[210:211]
	v_pk_mul_f32 v[90:91], v[82:83], v[0:1] op_sel_hi:[1,0]
	v_pk_mul_f32 v[80:81], v[80:81], v[0:1] op_sel_hi:[1,0]
	v_pk_mul_f32 v[76:77], v[76:77], v[0:1] op_sel_hi:[1,0]
	v_pk_mul_f32 v[78:79], v[78:79], v[0:1] op_sel_hi:[1,0]
	v_pk_mul_f32 v[72:73], v[72:73], v[0:1] op_sel_hi:[1,0]
	v_pk_mul_f32 v[70:71], v[70:71], v[0:1] op_sel_hi:[1,0]
	v_pk_mul_f32 v[68:69], v[68:69], v[0:1] op_sel_hi:[1,0]
	s_and_b64 vcc, exec, s[6:7]
	v_lshlrev_b32_e32 v82, 16, v86
	v_add_f32_e32 v80, v80, v82
	v_and_b32_e32 v82, 0xffff0000, v86
	v_add_f32_e32 v83, v81, v82
	v_lshlrev_b32_e32 v81, 16, v87
	v_add_f32_e32 v81, v90, v81
	v_lshlrev_b32_e32 v90, 16, v88
	v_and_b32_e32 v88, 0xffff0000, v88
	v_add_f32_e32 v77, v77, v88
	v_lshlrev_b32_e32 v88, 16, v89
	v_and_b32_e32 v82, 0xffff0000, v87
	v_add_f32_e32 v78, v78, v88
	v_and_b32_e32 v88, 0xffff0000, v89
	v_add_f32_e32 v82, v91, v82
	v_cvt_pk_bf16_f32 v86, v80, v83
	v_cvt_pk_bf16_f32 v87, v81, v82
	v_add_f32_e32 v76, v76, v90
	v_add_f32_e32 v79, v79, v88
	v_cvt_pk_bf16_f32 v88, v76, v77
	v_cvt_pk_bf16_f32 v89, v78, v79
	global_store_dwordx4 v[84:85], v[86:89], off
	s_nop 1
	v_mov_b64_e32 v[86:87], v[212:213]
	v_mov_b64_e32 v[88:89], v[214:215]
	v_pk_mul_f32 v[90:91], v[74:75], v[0:1] op_sel_hi:[1,0]
	v_lshlrev_b32_e32 v0, 16, v88
	v_lshlrev_b32_e32 v74, 16, v86
	v_add_f32_e32 v0, v68, v0
	v_and_b32_e32 v68, 0xffff0000, v88
	v_add_f32_e32 v72, v72, v74
	v_and_b32_e32 v74, 0xffff0000, v86
	v_add_f32_e32 v68, v69, v68
	v_lshlrev_b32_e32 v69, 16, v89
	v_add_f32_e32 v75, v73, v74
	v_lshlrev_b32_e32 v73, 16, v87
	v_and_b32_e32 v74, 0xffff0000, v87
	v_add_f32_e32 v69, v70, v69
	v_and_b32_e32 v70, 0xffff0000, v89
	v_add_f32_e32 v73, v90, v73
	v_add_f32_e32 v74, v91, v74
	v_add_f32_e32 v70, v71, v70
	v_cvt_pk_bf16_f32 v86, v72, v75
	v_cvt_pk_bf16_f32 v87, v73, v74
	v_cvt_pk_bf16_f32 v88, v0, v68
	v_cvt_pk_bf16_f32 v89, v69, v70
	global_store_dwordx4 v[84:85], v[86:89], off offset:256
	s_cbranch_vccnz .LBB0_199
	v_mul_f32_e32 v71, v83, v83
	v_mul_f32_e32 v77, v77, v77
	v_fmac_f32_e32 v71, v80, v80
	v_fmac_f32_e32 v77, v76, v76
	v_mul_f32_e32 v75, v75, v75
	v_fmac_f32_e32 v71, v81, v81
	v_fmac_f32_e32 v77, v78, v78
	v_fmac_f32_e32 v75, v72, v72
	v_mul_f32_e32 v68, v68, v68
	v_fmac_f32_e32 v71, v82, v82
	v_fmac_f32_e32 v77, v79, v79
	v_fmac_f32_e32 v75, v73, v73
	v_fmac_f32_e32 v68, v0, v0
	v_add_f32_e32 v71, v71, v77
	v_fmac_f32_e32 v75, v74, v74
	v_fmac_f32_e32 v68, v69, v69
	v_add_f32_e32 v71, v71, v75
	v_fmac_f32_e32 v68, v70, v70
	v_and_b32_e32 v69, 64, v177
	v_add_f32_e32 v0, v68, v71
	v_xor_b32_e32 v68, 16, v177
	v_add_u32_e32 v69, 64, v69
	v_cmp_lt_i32_e32 vcc, v68, v69
	s_nop 1
	v_cndmask_b32_e32 v68, v177, v68, vcc
	v_lshlrev_b32_e32 v68, 2, v68
	ds_bpermute_b32 v68, v68, v0
	s_waitcnt lgkmcnt(0)
	v_add_f32_e32 v0, v0, v68
	v_xor_b32_e32 v68, 32, v177
	v_cmp_lt_i32_e32 vcc, v68, v69
	s_nop 1
	v_cndmask_b32_e32 v68, v177, v68, vcc
	v_lshlrev_b32_e32 v68, 2, v68
	ds_bpermute_b32 v68, v68, v0
	s_and_saveexec_b64 s[2:3], s[8:9]
	s_cbranch_execz .LBB0_198
	s_waitcnt lgkmcnt(0)
	v_add_f32_e32 v0, v0, v68
	v_mul_f32_e32 v0, 0x4b800000, v0
	v_trunc_f32_e32 v0, v0
	v_mul_f32_e32 v68, 0x2f800000, v0
	v_floor_f32_e32 v69, v68
	v_fmac_f32_e32 v0, 0xcf800000, v69
	v_cvt_u32_f32_e32 v68, v0
	v_cvt_u32_f32_e32 v69, v69
	v_readlane_b32 s0, v255, 17
	v_readlane_b32 s1, v255, 18
	s_nop 1
	v_lshl_add_u64 v[70:71], v[2:3], 3, s[0:1]
	global_atomic_add_x2 v[70:71], v[68:69], off offset:384

.LBB0_201:
	s_waitcnt lgkmcnt(0)
	v_lshlrev_b64 v[68:69], 11, v[2:3]
	v_lshl_add_u64 v[68:69], s[94:95], 0, v[68:69]
	v_lshl_add_u64 v[70:71], v[156:157], 1, v[68:69]
	v_add_co_u32_e32 v74, vcc, 0x40000, v70
	s_mov_b64 s[0:1], 0x40000
	s_nop 0
	v_addc_co_u32_e32 v75, vcc, 0, v71, vcc
	v_lshl_add_u64 v[68:69], v[70:71], 0, s[0:1]
	s_nop 1
	v_mov_b64_e32 v[70:71], v[218:219]
	v_mov_b64_e32 v[72:73], v[220:221]
	v_pk_mul_f32 v[76:77], v[66:67], v[0:1] op_sel_hi:[1,0]
	v_pk_mul_f32 v[64:65], v[64:65], v[0:1] op_sel_hi:[1,0]
	v_pk_mul_f32 v[60:61], v[60:61], v[0:1] op_sel_hi:[1,0]
	v_pk_mul_f32 v[62:63], v[62:63], v[0:1] op_sel_hi:[1,0]
	v_pk_mul_f32 v[56:57], v[56:57], v[0:1] op_sel_hi:[1,0]
	v_pk_mul_f32 v[54:55], v[54:55], v[0:1] op_sel_hi:[1,0]
	v_pk_mul_f32 v[52:53], v[52:53], v[0:1] op_sel_hi:[1,0]
	s_and_b64 vcc, exec, s[6:7]
	v_lshlrev_b32_e32 v66, 16, v70
	v_add_f32_e32 v64, v64, v66
	v_and_b32_e32 v66, 0xffff0000, v70
	v_add_f32_e32 v67, v65, v66
	v_lshlrev_b32_e32 v65, 16, v71
	v_add_f32_e32 v65, v76, v65
	v_lshlrev_b32_e32 v76, 16, v72
	v_and_b32_e32 v72, 0xffff0000, v72
	v_add_f32_e32 v61, v61, v72
	v_lshlrev_b32_e32 v72, 16, v73
	v_and_b32_e32 v66, 0xffff0000, v71
	v_add_f32_e32 v62, v62, v72
	v_and_b32_e32 v72, 0xffff0000, v73
	v_add_f32_e32 v66, v77, v66
	v_cvt_pk_bf16_f32 v70, v64, v67
	v_cvt_pk_bf16_f32 v71, v65, v66
	v_add_f32_e32 v60, v60, v76
	v_add_f32_e32 v63, v63, v72
	v_cvt_pk_bf16_f32 v72, v60, v61
	v_cvt_pk_bf16_f32 v73, v62, v63
	global_store_dwordx4 v[74:75], v[70:73], off
	s_nop 1
	v_mov_b64_e32 v[70:71], v[222:223]
	v_mov_b64_e32 v[72:73], v[224:225]
	v_pk_mul_f32 v[74:75], v[58:59], v[0:1] op_sel_hi:[1,0]
	v_lshlrev_b32_e32 v0, 16, v72
	v_lshlrev_b32_e32 v58, 16, v70
	v_add_f32_e32 v0, v52, v0
	v_and_b32_e32 v52, 0xffff0000, v72
	v_add_f32_e32 v56, v56, v58
	v_and_b32_e32 v58, 0xffff0000, v70
	v_add_f32_e32 v52, v53, v52
	v_lshlrev_b32_e32 v53, 16, v73
	v_add_f32_e32 v59, v57, v58
	v_lshlrev_b32_e32 v57, 16, v71
	v_and_b32_e32 v58, 0xffff0000, v71
	v_add_f32_e32 v53, v54, v53
	v_and_b32_e32 v54, 0xffff0000, v73
	v_add_f32_e32 v57, v74, v57
	v_add_f32_e32 v58, v75, v58
	v_add_f32_e32 v54, v55, v54
	v_cvt_pk_bf16_f32 v70, v56, v59
	v_cvt_pk_bf16_f32 v71, v57, v58
	v_cvt_pk_bf16_f32 v72, v0, v52
	v_cvt_pk_bf16_f32 v73, v53, v54
	global_store_dwordx4 v[68:69], v[70:73], off offset:256
	s_cbranch_vccnz .LBB0_205
	v_mul_f32_e32 v55, v67, v67
	v_mul_f32_e32 v61, v61, v61
	v_fmac_f32_e32 v55, v64, v64
	v_fmac_f32_e32 v61, v60, v60
	v_mul_f32_e32 v59, v59, v59
	v_fmac_f32_e32 v55, v65, v65
	v_fmac_f32_e32 v61, v62, v62
	v_fmac_f32_e32 v59, v56, v56
	v_mul_f32_e32 v52, v52, v52
	v_fmac_f32_e32 v55, v66, v66
	v_fmac_f32_e32 v61, v63, v63
	v_fmac_f32_e32 v59, v57, v57
	v_fmac_f32_e32 v52, v0, v0
	v_add_f32_e32 v55, v55, v61
	v_fmac_f32_e32 v59, v58, v58
	v_fmac_f32_e32 v52, v53, v53
	v_add_f32_e32 v55, v55, v59
	v_fmac_f32_e32 v52, v54, v54
	v_and_b32_e32 v53, 64, v177
	v_add_f32_e32 v0, v52, v55
	v_xor_b32_e32 v52, 16, v177
	v_add_u32_e32 v53, 64, v53
	v_cmp_lt_i32_e32 vcc, v52, v53
	s_nop 1
	v_cndmask_b32_e32 v52, v177, v52, vcc
	v_lshlrev_b32_e32 v52, 2, v52
	ds_bpermute_b32 v52, v52, v0
	s_waitcnt lgkmcnt(0)
	v_add_f32_e32 v0, v0, v52
	v_xor_b32_e32 v52, 32, v177
	v_cmp_lt_i32_e32 vcc, v52, v53
	s_nop 1
	v_cndmask_b32_e32 v52, v177, v52, vcc
	v_lshlrev_b32_e32 v52, 2, v52
	ds_bpermute_b32 v52, v52, v0
	s_and_saveexec_b64 s[2:3], s[8:9]
	s_cbranch_execz .LBB0_204
	s_waitcnt lgkmcnt(0)
	v_add_f32_e32 v0, v0, v52
	v_mul_f32_e32 v0, 0x4b800000, v0
	v_trunc_f32_e32 v0, v0
	v_mul_f32_e32 v52, 0x2f800000, v0
	v_floor_f32_e32 v53, v52
	v_fmac_f32_e32 v0, 0xcf800000, v53
	v_cvt_u32_f32_e32 v52, v0
	v_cvt_u32_f32_e32 v53, v53
	v_readlane_b32 s0, v255, 17
	v_readlane_b32 s1, v255, 18
	s_nop 1
	v_lshl_add_u64 v[54:55], v[2:3], 3, s[0:1]
	global_atomic_add_x2 v[54:55], v[52:53], off offset:1024

.LBB0_207:
	s_waitcnt lgkmcnt(0)
	v_lshlrev_b64 v[52:53], 11, v[2:3]
	v_lshl_add_u64 v[52:53], s[94:95], 0, v[52:53]
	v_lshl_add_u64 v[54:55], v[156:157], 1, v[52:53]
	v_add_co_u32_e32 v58, vcc, 0x48000, v54
	s_mov_b64 s[0:1], 0x48000
	s_nop 0
	v_addc_co_u32_e32 v59, vcc, 0, v55, vcc
	v_lshl_add_u64 v[52:53], v[54:55], 0, s[0:1]
	s_nop 1
	v_mov_b64_e32 v[54:55], v[226:227]
	v_mov_b64_e32 v[56:57], v[228:229]
	v_pk_mul_f32 v[60:61], v[50:51], v[0:1] op_sel_hi:[1,0]
	v_pk_mul_f32 v[48:49], v[48:49], v[0:1] op_sel_hi:[1,0]
	v_pk_mul_f32 v[44:45], v[44:45], v[0:1] op_sel_hi:[1,0]
	v_pk_mul_f32 v[46:47], v[46:47], v[0:1] op_sel_hi:[1,0]
	v_pk_mul_f32 v[40:41], v[40:41], v[0:1] op_sel_hi:[1,0]
	v_pk_mul_f32 v[38:39], v[38:39], v[0:1] op_sel_hi:[1,0]
	v_pk_mul_f32 v[36:37], v[36:37], v[0:1] op_sel_hi:[1,0]
	s_and_b64 vcc, exec, s[6:7]
	v_lshlrev_b32_e32 v50, 16, v54
	v_add_f32_e32 v48, v48, v50
	v_and_b32_e32 v50, 0xffff0000, v54
	v_add_f32_e32 v51, v49, v50
	v_lshlrev_b32_e32 v49, 16, v55
	v_add_f32_e32 v49, v60, v49
	v_lshlrev_b32_e32 v60, 16, v56
	v_and_b32_e32 v56, 0xffff0000, v56
	v_add_f32_e32 v45, v45, v56
	v_lshlrev_b32_e32 v56, 16, v57
	v_and_b32_e32 v50, 0xffff0000, v55
	v_add_f32_e32 v46, v46, v56
	v_and_b32_e32 v56, 0xffff0000, v57
	v_add_f32_e32 v50, v61, v50
	v_cvt_pk_bf16_f32 v54, v48, v51
	v_cvt_pk_bf16_f32 v55, v49, v50
	v_add_f32_e32 v44, v44, v60
	v_add_f32_e32 v47, v47, v56
	v_cvt_pk_bf16_f32 v56, v44, v45
	v_cvt_pk_bf16_f32 v57, v46, v47
	global_store_dwordx4 v[58:59], v[54:57], off
	s_nop 1
	v_mov_b64_e32 v[54:55], v[230:231]
	v_mov_b64_e32 v[56:57], v[232:233]
	v_pk_mul_f32 v[58:59], v[42:43], v[0:1] op_sel_hi:[1,0]
	v_lshlrev_b32_e32 v0, 16, v56
	v_lshlrev_b32_e32 v42, 16, v54
	v_add_f32_e32 v0, v36, v0
	v_and_b32_e32 v36, 0xffff0000, v56
	v_add_f32_e32 v40, v40, v42
	v_and_b32_e32 v42, 0xffff0000, v54
	v_add_f32_e32 v36, v37, v36
	v_lshlrev_b32_e32 v37, 16, v57
	v_add_f32_e32 v43, v41, v42
	v_lshlrev_b32_e32 v41, 16, v55
	v_and_b32_e32 v42, 0xffff0000, v55
	v_add_f32_e32 v37, v38, v37
	v_and_b32_e32 v38, 0xffff0000, v57
	v_add_f32_e32 v41, v58, v41
	v_add_f32_e32 v42, v59, v42
	v_add_f32_e32 v38, v39, v38
	v_cvt_pk_bf16_f32 v54, v40, v43
	v_cvt_pk_bf16_f32 v55, v41, v42
	v_cvt_pk_bf16_f32 v56, v0, v36
	v_cvt_pk_bf16_f32 v57, v37, v38
	global_store_dwordx4 v[52:53], v[54:57], off offset:256
	s_cbranch_vccnz .LBB0_211
	v_mul_f32_e32 v39, v51, v51
	v_mul_f32_e32 v45, v45, v45
	v_fmac_f32_e32 v39, v48, v48
	v_fmac_f32_e32 v45, v44, v44
	v_mul_f32_e32 v43, v43, v43
	v_fmac_f32_e32 v39, v49, v49
	v_fmac_f32_e32 v45, v46, v46
	v_fmac_f32_e32 v43, v40, v40
	v_mul_f32_e32 v36, v36, v36
	v_fmac_f32_e32 v39, v50, v50
	v_fmac_f32_e32 v45, v47, v47
	v_fmac_f32_e32 v43, v41, v41
	v_fmac_f32_e32 v36, v0, v0
	v_add_f32_e32 v39, v39, v45
	v_fmac_f32_e32 v43, v42, v42
	v_fmac_f32_e32 v36, v37, v37
	v_add_f32_e32 v39, v39, v43
	v_fmac_f32_e32 v36, v38, v38
	v_and_b32_e32 v37, 64, v177
	v_add_f32_e32 v0, v36, v39
	v_xor_b32_e32 v36, 16, v177
	v_add_u32_e32 v37, 64, v37
	v_cmp_lt_i32_e32 vcc, v36, v37
	s_nop 1
	v_cndmask_b32_e32 v36, v177, v36, vcc
	v_lshlrev_b32_e32 v36, 2, v36
	ds_bpermute_b32 v36, v36, v0
	s_waitcnt lgkmcnt(0)
	v_add_f32_e32 v0, v0, v36
	v_xor_b32_e32 v36, 32, v177
	v_cmp_lt_i32_e32 vcc, v36, v37
	s_nop 1
	v_cndmask_b32_e32 v36, v177, v36, vcc
	v_lshlrev_b32_e32 v36, 2, v36
	ds_bpermute_b32 v36, v36, v0
	s_and_saveexec_b64 s[2:3], s[8:9]
	s_cbranch_execz .LBB0_210
	s_waitcnt lgkmcnt(0)
	v_add_f32_e32 v0, v0, v36
	v_mul_f32_e32 v0, 0x4b800000, v0
	v_trunc_f32_e32 v0, v0
	v_mul_f32_e32 v36, 0x2f800000, v0
	v_floor_f32_e32 v37, v36
	v_fmac_f32_e32 v0, 0xcf800000, v37
	v_cvt_u32_f32_e32 v36, v0
	v_cvt_u32_f32_e32 v37, v37
	v_readlane_b32 s0, v255, 17
	v_readlane_b32 s1, v255, 18
	s_nop 1
	v_lshl_add_u64 v[38:39], v[2:3], 3, s[0:1]
	global_atomic_add_x2 v[38:39], v[36:37], off offset:1152

.LBB0_213:
	s_waitcnt lgkmcnt(0)
	v_lshlrev_b64 v[36:37], 11, v[2:3]
	v_lshl_add_u64 v[36:37], s[94:95], 0, v[36:37]
	v_lshl_add_u64 v[38:39], v[156:157], 1, v[36:37]
	v_add_co_u32_e32 v42, vcc, 0x50000, v38
	s_mov_b64 s[0:1], 0x50000
	s_nop 0
	v_addc_co_u32_e32 v43, vcc, 0, v39, vcc
	v_lshl_add_u64 v[36:37], v[38:39], 0, s[0:1]
	s_nop 1
	v_mov_b64_e32 v[38:39], v[234:235]
	v_mov_b64_e32 v[40:41], v[236:237]
	v_pk_mul_f32 v[44:45], v[34:35], v[0:1] op_sel_hi:[1,0]
	v_pk_mul_f32 v[32:33], v[32:33], v[0:1] op_sel_hi:[1,0]
	v_pk_mul_f32 v[28:29], v[28:29], v[0:1] op_sel_hi:[1,0]
	v_pk_mul_f32 v[30:31], v[30:31], v[0:1] op_sel_hi:[1,0]
	v_pk_mul_f32 v[24:25], v[24:25], v[0:1] op_sel_hi:[1,0]
	v_pk_mul_f32 v[22:23], v[22:23], v[0:1] op_sel_hi:[1,0]
	v_pk_mul_f32 v[20:21], v[20:21], v[0:1] op_sel_hi:[1,0]
	s_and_b64 vcc, exec, s[6:7]
	v_lshlrev_b32_e32 v34, 16, v38
	v_add_f32_e32 v32, v32, v34
	v_and_b32_e32 v34, 0xffff0000, v38
	v_add_f32_e32 v35, v33, v34
	v_lshlrev_b32_e32 v33, 16, v39
	v_add_f32_e32 v33, v44, v33
	v_lshlrev_b32_e32 v44, 16, v40
	v_and_b32_e32 v40, 0xffff0000, v40
	v_add_f32_e32 v29, v29, v40
	v_lshlrev_b32_e32 v40, 16, v41
	v_and_b32_e32 v34, 0xffff0000, v39
	v_add_f32_e32 v30, v30, v40
	v_and_b32_e32 v40, 0xffff0000, v41
	v_add_f32_e32 v34, v45, v34
	v_cvt_pk_bf16_f32 v38, v32, v35
	v_cvt_pk_bf16_f32 v39, v33, v34
	v_add_f32_e32 v28, v28, v44
	v_add_f32_e32 v31, v31, v40
	v_cvt_pk_bf16_f32 v40, v28, v29
	v_cvt_pk_bf16_f32 v41, v30, v31
	global_store_dwordx4 v[42:43], v[38:41], off
	s_nop 1
	v_mov_b64_e32 v[38:39], v[238:239]
	v_mov_b64_e32 v[40:41], v[240:241]
	v_pk_mul_f32 v[42:43], v[26:27], v[0:1] op_sel_hi:[1,0]
	v_lshlrev_b32_e32 v0, 16, v40
	v_lshlrev_b32_e32 v26, 16, v38
	v_add_f32_e32 v0, v20, v0
	v_and_b32_e32 v20, 0xffff0000, v40
	v_add_f32_e32 v24, v24, v26
	v_and_b32_e32 v26, 0xffff0000, v38
	v_add_f32_e32 v20, v21, v20
	v_lshlrev_b32_e32 v21, 16, v41
	v_add_f32_e32 v27, v25, v26
	v_lshlrev_b32_e32 v25, 16, v39
	v_and_b32_e32 v26, 0xffff0000, v39
	v_add_f32_e32 v21, v22, v21
	v_and_b32_e32 v22, 0xffff0000, v41
	v_add_f32_e32 v25, v42, v25
	v_add_f32_e32 v26, v43, v26
	v_add_f32_e32 v22, v23, v22
	v_cvt_pk_bf16_f32 v38, v24, v27
	v_cvt_pk_bf16_f32 v39, v25, v26
	v_cvt_pk_bf16_f32 v40, v0, v20
	v_cvt_pk_bf16_f32 v41, v21, v22
	global_store_dwordx4 v[36:37], v[38:41], off offset:256
	s_cbranch_vccnz .LBB0_217
	v_mul_f32_e32 v23, v35, v35
	v_mul_f32_e32 v29, v29, v29
	v_fmac_f32_e32 v23, v32, v32
	v_fmac_f32_e32 v29, v28, v28
	v_mul_f32_e32 v27, v27, v27
	v_fmac_f32_e32 v23, v33, v33
	v_fmac_f32_e32 v29, v30, v30
	v_fmac_f32_e32 v27, v24, v24
	v_mul_f32_e32 v20, v20, v20
	v_fmac_f32_e32 v23, v34, v34
	v_fmac_f32_e32 v29, v31, v31
	v_fmac_f32_e32 v27, v25, v25
	v_fmac_f32_e32 v20, v0, v0
	v_add_f32_e32 v23, v23, v29
	v_fmac_f32_e32 v27, v26, v26
	v_fmac_f32_e32 v20, v21, v21
	v_add_f32_e32 v23, v23, v27
	v_fmac_f32_e32 v20, v22, v22
	v_and_b32_e32 v21, 64, v177
	v_add_f32_e32 v0, v20, v23
	v_xor_b32_e32 v20, 16, v177
	v_add_u32_e32 v21, 64, v21
	v_cmp_lt_i32_e32 vcc, v20, v21
	s_nop 1
	v_cndmask_b32_e32 v20, v177, v20, vcc
	v_lshlrev_b32_e32 v20, 2, v20
	ds_bpermute_b32 v20, v20, v0
	s_waitcnt lgkmcnt(0)
	v_add_f32_e32 v0, v0, v20
	v_xor_b32_e32 v20, 32, v177
	v_cmp_lt_i32_e32 vcc, v20, v21
	s_nop 1
	v_cndmask_b32_e32 v20, v177, v20, vcc
	v_lshlrev_b32_e32 v20, 2, v20
	ds_bpermute_b32 v20, v20, v0
	s_and_saveexec_b64 s[2:3], s[8:9]
	s_cbranch_execz .LBB0_216
	s_waitcnt lgkmcnt(0)
	v_add_f32_e32 v0, v0, v20
	v_mul_f32_e32 v0, 0x4b800000, v0
	v_trunc_f32_e32 v0, v0
	v_mul_f32_e32 v20, 0x2f800000, v0
	v_floor_f32_e32 v21, v20
	v_fmac_f32_e32 v0, 0xcf800000, v21
	v_cvt_u32_f32_e32 v20, v0
	v_cvt_u32_f32_e32 v21, v21
	v_readlane_b32 s0, v255, 17
	v_readlane_b32 s1, v255, 18
	s_nop 1
	v_lshl_add_u64 v[22:23], v[2:3], 3, s[0:1]
	global_atomic_add_x2 v[22:23], v[20:21], off offset:1280

.LBB0_219:
	s_waitcnt lgkmcnt(0)
	v_lshlrev_b64 v[20:21], 11, v[2:3]
	v_lshl_add_u64 v[20:21], s[94:95], 0, v[20:21]
	v_lshl_add_u64 v[22:23], v[156:157], 1, v[20:21]
	v_add_co_u32_e32 v26, vcc, 0x58000, v22
	s_mov_b64 s[0:1], 0x58000
	s_nop 0
	v_addc_co_u32_e32 v27, vcc, 0, v23, vcc
	v_lshl_add_u64 v[20:21], v[22:23], 0, s[0:1]
	s_nop 1
	v_mov_b64_e32 v[22:23], v[242:243]
	v_mov_b64_e32 v[24:25], v[244:245]
	v_pk_mul_f32 v[28:29], v[18:19], v[0:1] op_sel_hi:[1,0]
	v_pk_mul_f32 v[16:17], v[16:17], v[0:1] op_sel_hi:[1,0]
	v_pk_mul_f32 v[12:13], v[12:13], v[0:1] op_sel_hi:[1,0]
	v_pk_mul_f32 v[14:15], v[14:15], v[0:1] op_sel_hi:[1,0]
	v_pk_mul_f32 v[8:9], v[8:9], v[0:1] op_sel_hi:[1,0]
	v_pk_mul_f32 v[6:7], v[6:7], v[0:1] op_sel_hi:[1,0]
	v_pk_mul_f32 v[4:5], v[4:5], v[0:1] op_sel_hi:[1,0]
	s_and_b64 vcc, exec, s[6:7]
	v_lshlrev_b32_e32 v18, 16, v22
	v_add_f32_e32 v16, v16, v18
	v_and_b32_e32 v18, 0xffff0000, v22
	v_add_f32_e32 v19, v17, v18
	v_lshlrev_b32_e32 v17, 16, v23
	v_add_f32_e32 v17, v28, v17
	v_lshlrev_b32_e32 v28, 16, v24
	v_and_b32_e32 v24, 0xffff0000, v24
	v_add_f32_e32 v13, v13, v24
	v_lshlrev_b32_e32 v24, 16, v25
	v_and_b32_e32 v18, 0xffff0000, v23
	v_add_f32_e32 v14, v14, v24
	v_and_b32_e32 v24, 0xffff0000, v25
	v_add_f32_e32 v18, v29, v18
	v_cvt_pk_bf16_f32 v22, v16, v19
	v_cvt_pk_bf16_f32 v23, v17, v18
	v_add_f32_e32 v12, v12, v28
	v_add_f32_e32 v15, v15, v24
	v_cvt_pk_bf16_f32 v24, v12, v13
	v_cvt_pk_bf16_f32 v25, v14, v15
	global_store_dwordx4 v[26:27], v[22:25], off
	s_nop 1
	v_mov_b64_e32 v[22:23], v[246:247]
	v_mov_b64_e32 v[24:25], v[248:249]
	v_pk_mul_f32 v[26:27], v[10:11], v[0:1] op_sel_hi:[1,0]
	v_lshlrev_b32_e32 v0, 16, v24
	v_lshlrev_b32_e32 v10, 16, v22
	v_add_f32_e32 v0, v4, v0
	v_and_b32_e32 v4, 0xffff0000, v24
	v_add_f32_e32 v8, v8, v10
	v_and_b32_e32 v10, 0xffff0000, v22
	v_add_f32_e32 v4, v5, v4
	v_lshlrev_b32_e32 v5, 16, v25
	v_add_f32_e32 v11, v9, v10
	v_lshlrev_b32_e32 v9, 16, v23
	v_and_b32_e32 v10, 0xffff0000, v23
	v_add_f32_e32 v5, v6, v5
	v_and_b32_e32 v6, 0xffff0000, v25
	v_add_f32_e32 v9, v26, v9
	v_add_f32_e32 v10, v27, v10
	v_add_f32_e32 v6, v7, v6
	v_cvt_pk_bf16_f32 v22, v8, v11
	v_cvt_pk_bf16_f32 v23, v9, v10
	v_cvt_pk_bf16_f32 v24, v0, v4
	v_cvt_pk_bf16_f32 v25, v5, v6
	global_store_dwordx4 v[20:21], v[22:25], off offset:256
	s_cbranch_vccnz .LBB0_158
	v_mul_f32_e32 v7, v19, v19
	v_mul_f32_e32 v13, v13, v13
	v_fmac_f32_e32 v7, v16, v16
	v_fmac_f32_e32 v13, v12, v12
	v_mul_f32_e32 v11, v11, v11
	v_fmac_f32_e32 v7, v17, v17
	v_fmac_f32_e32 v13, v14, v14
	v_fmac_f32_e32 v11, v8, v8
	v_mul_f32_e32 v4, v4, v4
	v_fmac_f32_e32 v7, v18, v18
	v_fmac_f32_e32 v13, v15, v15
	v_fmac_f32_e32 v11, v9, v9
	v_fmac_f32_e32 v4, v0, v0
	v_add_f32_e32 v7, v7, v13
	v_fmac_f32_e32 v11, v10, v10
	v_fmac_f32_e32 v4, v5, v5
	v_add_f32_e32 v7, v7, v11
	v_fmac_f32_e32 v4, v6, v6
	v_and_b32_e32 v5, 64, v177
	v_add_f32_e32 v0, v4, v7
	v_xor_b32_e32 v4, 16, v177
	v_add_u32_e32 v5, 64, v5
	v_cmp_lt_i32_e32 vcc, v4, v5
	s_nop 1
	v_cndmask_b32_e32 v4, v177, v4, vcc
	v_lshlrev_b32_e32 v4, 2, v4
	ds_bpermute_b32 v4, v4, v0
	s_waitcnt lgkmcnt(0)
	v_add_f32_e32 v0, v0, v4
	v_xor_b32_e32 v4, 32, v177
	v_cmp_lt_i32_e32 vcc, v4, v5
	s_nop 1
	v_cndmask_b32_e32 v4, v177, v4, vcc
	v_lshlrev_b32_e32 v4, 2, v4
	ds_bpermute_b32 v4, v4, v0
	s_and_saveexec_b64 s[2:3], s[8:9]
	s_cbranch_execz .LBB0_157
	s_waitcnt lgkmcnt(0)
	v_add_f32_e32 v0, v0, v4
	v_mul_f32_e32 v0, 0x4b800000, v0
	v_trunc_f32_e32 v0, v0
	v_mul_f32_e32 v4, 0x2f800000, v0
	v_floor_f32_e32 v5, v4
	v_fmac_f32_e32 v0, 0xcf800000, v5
	v_cvt_u32_f32_e32 v4, v0
	v_cvt_u32_f32_e32 v5, v5
	v_readlane_b32 s0, v255, 17
	v_readlane_b32 s1, v255, 18
	s_nop 1
	v_lshl_add_u64 v[2:3], v[2:3], 3, s[0:1]
	global_atomic_add_x2 v[2:3], v[4:5], off offset:1408
	s_branch .LBB0_157

.LBB0_784:
	v_add_u32_e32 v140, s19, v159
	ds_read_b128 v[154:157], v140
	ds_read_b128 v[164:167], v140 offset:1024
	ds_read_b128 v[168:171], v140 offset:2048
	ds_read_b128 v[188:191], v140 offset:3072
	s_add_u32 s22, s20, 0xfffc0080
	s_addc_u32 s23, s21, -1
	s_cmp_eq_u32 s65, 12
	s_cselect_b32 s25, s9, s23
	s_cselect_b32 s24, s13, s22
	s_cselect_b32 s23, s11, s64
	s_cselect_b32 s22, s62, s63
	v_lshl_add_u64 v[140:141], s[20:21], 0, v[136:137]
	s_add_i32 m0, s30, 0xc000
	ds_read_b128 v[192:195], v162
	ds_read_b128 v[196:199], v162 offset:1024
	ds_read_b128 v[200:203], v162 offset:2048
	ds_read_b128 v[204:207], v162 offset:3072
	ds_read_b128 v[208:211], v162 offset:4096
	ds_read_b128 v[212:215], v162 offset:5120
	ds_read_b128 v[218:221], v162 offset:6144
	ds_read_b128 v[222:225], v162 offset:7168
	global_load_lds_dwordx4 v[140:141], off
	v_lshl_add_u64 v[140:141], s[20:21], 0, v[138:139]
	s_add_i32 m0, s30, 0xe000
	s_nop 0
	global_load_lds_dwordx4 v[140:141], off
	s_waitcnt lgkmcnt(8)
	s_barrier
	s_waitcnt lgkmcnt(0)
	s_setprio 1
	s_waitcnt lgkmcnt(0)
	v_mfma_f32_16x16x32_bf16 v[126:129], v[154:157], v[192:195], v[126:129]
	v_mfma_f32_16x16x32_bf16 v[122:125], v[168:171], v[192:195], v[122:125]
	v_mfma_f32_16x16x32_bf16 v[110:113], v[154:157], v[200:203], v[110:113]
	v_mfma_f32_16x16x32_bf16 v[106:109], v[168:171], v[200:203], v[106:109]
	v_mfma_f32_16x16x32_bf16 v[94:97], v[154:157], v[208:211], v[94:97]
	v_mfma_f32_16x16x32_bf16 v[90:93], v[168:171], v[208:211], v[90:93]
	v_mfma_f32_16x16x32_bf16 v[78:81], v[154:157], v[218:221], v[78:81]
	v_mfma_f32_16x16x32_bf16 v[74:77], v[168:171], v[218:221], v[74:77]
	v_mfma_f32_16x16x32_bf16 v[126:129], v[164:167], v[196:199], v[126:129]
	v_mfma_f32_16x16x32_bf16 v[122:125], v[188:191], v[196:199], v[122:125]
	v_mfma_f32_16x16x32_bf16 v[110:113], v[164:167], v[204:207], v[110:113]
	v_mfma_f32_16x16x32_bf16 v[106:109], v[188:191], v[204:207], v[106:109]
	v_mfma_f32_16x16x32_bf16 v[94:97], v[164:167], v[212:215], v[94:97]
	v_mfma_f32_16x16x32_bf16 v[90:93], v[188:191], v[212:215], v[90:93]
	v_mfma_f32_16x16x32_bf16 v[78:81], v[164:167], v[222:225], v[78:81]
	v_mfma_f32_16x16x32_bf16 v[74:77], v[188:191], v[222:225], v[74:77]
	s_setprio 0
	s_barrier
	v_add_u32_e32 v140, s33, v159
	s_mov_b32 m0, s28
	ds_read_b128 v[226:229], v140
	ds_read_b128 v[230:233], v140 offset:1024
	ds_read_b128 v[234:237], v140 offset:2048
	ds_read_b128 v[238:241], v140 offset:3072
	v_lshl_add_u64 v[140:141], s[22:23], 0, v[0:1]
	global_load_lds_dwordx4 v[140:141], off
	v_lshl_add_u64 v[242:243], s[22:23], 0, v[134:135]
	s_mov_b32 m0, s29
	s_nop 0
	global_load_lds_dwordx4 v[242:243], off
	s_barrier
	s_waitcnt lgkmcnt(0)
	s_setprio 1
	s_waitcnt lgkmcnt(0)
	v_mfma_f32_16x16x32_bf16 v[118:121], v[226:229], v[192:195], v[118:121]
	v_mfma_f32_16x16x32_bf16 v[114:117], v[234:237], v[192:195], v[114:117]
	v_mfma_f32_16x16x32_bf16 v[102:105], v[226:229], v[200:203], v[102:105]
	v_mfma_f32_16x16x32_bf16 v[98:101], v[234:237], v[200:203], v[98:101]
	v_mfma_f32_16x16x32_bf16 v[86:89], v[226:229], v[208:211], v[86:89]
	v_mfma_f32_16x16x32_bf16 v[82:85], v[234:237], v[208:211], v[82:85]
	v_mfma_f32_16x16x32_bf16 v[70:73], v[226:229], v[218:221], v[70:73]
	v_mfma_f32_16x16x32_bf16 v[66:69], v[234:237], v[218:221], v[66:69]
	v_mfma_f32_16x16x32_bf16 v[118:121], v[230:233], v[196:199], v[118:121]
	v_mfma_f32_16x16x32_bf16 v[114:117], v[238:241], v[196:199], v[114:117]
	v_mfma_f32_16x16x32_bf16 v[102:105], v[230:233], v[204:207], v[102:105]
	v_mfma_f32_16x16x32_bf16 v[98:101], v[238:241], v[204:207], v[98:101]
	v_mfma_f32_16x16x32_bf16 v[86:89], v[230:233], v[212:215], v[86:89]
	v_mfma_f32_16x16x32_bf16 v[82:85], v[238:241], v[212:215], v[82:85]
	v_mfma_f32_16x16x32_bf16 v[70:73], v[230:233], v[222:225], v[70:73]
	v_mfma_f32_16x16x32_bf16 v[66:69], v[238:241], v[222:225], v[66:69]
	s_setprio 0
	s_mov_b32 m0, s30
	v_lshl_add_u64 v[244:245], s[24:25], 0, v[130:131]
	s_barrier
	ds_read_b128 v[192:195], v162 offset:16384
	ds_read_b128 v[196:199], v162 offset:17408
	ds_read_b128 v[200:203], v162 offset:18432
	ds_read_b128 v[204:207], v162 offset:19456
	ds_read_b128 v[208:211], v162 offset:20480
	ds_read_b128 v[212:215], v162 offset:21504
	ds_read_b128 v[218:221], v162 offset:22528
	ds_read_b128 v[222:225], v162 offset:23552
	global_load_lds_dwordx4 v[244:245], off
	v_lshl_add_u64 v[246:247], s[24:25], 0, v[132:133]
	s_mov_b32 m0, s31
	s_nop 0
	global_load_lds_dwordx4 v[246:247], off
	s_barrier
	s_waitcnt lgkmcnt(0)
	s_setprio 1
	s_waitcnt lgkmcnt(0)
	v_mfma_f32_16x16x32_bf16 v[62:65], v[154:157], v[192:195], v[62:65]
	v_mfma_f32_16x16x32_bf16 v[58:61], v[168:171], v[192:195], v[58:61]
	v_mfma_f32_16x16x32_bf16 v[46:49], v[154:157], v[200:203], v[46:49]
	v_mfma_f32_16x16x32_bf16 v[42:45], v[168:171], v[200:203], v[42:45]
	v_mfma_f32_16x16x32_bf16 v[30:33], v[154:157], v[208:211], v[30:33]
	v_mfma_f32_16x16x32_bf16 v[26:29], v[168:171], v[208:211], v[26:29]
	v_mfma_f32_16x16x32_bf16 v[14:17], v[154:157], v[218:221], v[14:17]
	v_mfma_f32_16x16x32_bf16 v[10:13], v[168:171], v[218:221], v[10:13]
	v_mfma_f32_16x16x32_bf16 v[62:65], v[164:167], v[196:199], v[62:65]
	v_mfma_f32_16x16x32_bf16 v[58:61], v[188:191], v[196:199], v[58:61]
	v_mfma_f32_16x16x32_bf16 v[46:49], v[164:167], v[204:207], v[46:49]
	v_mfma_f32_16x16x32_bf16 v[42:45], v[188:191], v[204:207], v[42:45]
	v_mfma_f32_16x16x32_bf16 v[30:33], v[164:167], v[212:215], v[30:33]
	v_mfma_f32_16x16x32_bf16 v[26:29], v[188:191], v[212:215], v[26:29]
	v_mfma_f32_16x16x32_bf16 v[14:17], v[164:167], v[222:225], v[14:17]
	v_mfma_f32_16x16x32_bf16 v[10:13], v[188:191], v[222:225], v[10:13]
	s_setprio 0
	s_barrier
	s_add_u32 s70, s22, 0x40000
	s_addc_u32 s71, s23, 0
	s_mov_b32 m0, s34
	v_lshl_add_u64 v[154:155], s[70:71], 0, v[0:1]
	global_load_lds_dwordx4 v[154:155], off
	v_lshl_add_u64 v[154:155], s[70:71], 0, v[134:135]
	s_mov_b32 m0, s35
	s_nop 0
	global_load_lds_dwordx4 v[154:155], off
	s_waitcnt vmcnt(6)
	s_barrier
	s_setprio 1
	v_mfma_f32_16x16x32_bf16 v[54:57], v[226:229], v[192:195], v[54:57]
	v_mfma_f32_16x16x32_bf16 v[50:53], v[234:237], v[192:195], v[50:53]
	v_mfma_f32_16x16x32_bf16 v[38:41], v[226:229], v[200:203], v[38:41]
	v_mfma_f32_16x16x32_bf16 v[34:37], v[234:237], v[200:203], v[34:37]
	v_mfma_f32_16x16x32_bf16 v[22:25], v[226:229], v[208:211], v[22:25]
	v_mfma_f32_16x16x32_bf16 v[18:21], v[234:237], v[208:211], v[18:21]
	v_mfma_f32_16x16x32_bf16 v[6:9], v[226:229], v[218:221], v[6:9]
	v_mfma_f32_16x16x32_bf16 v[2:5], v[234:237], v[218:221], v[2:5]
	v_mfma_f32_16x16x32_bf16 v[54:57], v[230:233], v[196:199], v[54:57]
	v_mfma_f32_16x16x32_bf16 v[50:53], v[238:241], v[196:199], v[50:53]
	v_mfma_f32_16x16x32_bf16 v[38:41], v[230:233], v[204:207], v[38:41]
	v_mfma_f32_16x16x32_bf16 v[34:37], v[238:241], v[204:207], v[34:37]
	v_mfma_f32_16x16x32_bf16 v[22:25], v[230:233], v[212:215], v[22:25]
	v_mfma_f32_16x16x32_bf16 v[18:21], v[238:241], v[212:215], v[18:21]
	v_mfma_f32_16x16x32_bf16 v[6:9], v[230:233], v[222:225], v[6:9]
	v_mfma_f32_16x16x32_bf16 v[2:5], v[238:241], v[222:225], v[2:5]
	s_setprio 0
	v_add_u32_e32 v144, s38, v159
	s_barrier
	ds_read_b128 v[154:157], v144
	ds_read_b128 v[164:167], v144 offset:1024
	ds_read_b128 v[168:171], v144 offset:2048
	ds_read_b128 v[188:191], v144 offset:3072
	s_add_u32 s24, s24, 0x40000
	s_addc_u32 s25, s25, 0
	s_mov_b32 m0, s36
	v_lshl_add_u64 v[226:227], s[24:25], 0, v[130:131]
	ds_read_b128 v[192:195], v162 offset:32768
	ds_read_b128 v[196:199], v162 offset:33792
	ds_read_b128 v[200:203], v162 offset:34816
	ds_read_b128 v[204:207], v162 offset:35840
	ds_read_b128 v[208:211], v162 offset:36864
	ds_read_b128 v[212:215], v162 offset:37888
	ds_read_b128 v[218:221], v162 offset:38912
	ds_read_b128 v[222:225], v162 offset:39936
	global_load_lds_dwordx4 v[226:227], off
	v_lshl_add_u64 v[226:227], s[24:25], 0, v[132:133]
	s_mov_b32 m0, s37
	s_nop 0
	global_load_lds_dwordx4 v[226:227], off
	s_waitcnt lgkmcnt(8)
	s_barrier
	s_waitcnt lgkmcnt(0)
	s_setprio 1
	s_waitcnt lgkmcnt(0)
	v_mfma_f32_16x16x32_bf16 v[126:129], v[154:157], v[192:195], v[126:129]
	v_mfma_f32_16x16x32_bf16 v[122:125], v[168:171], v[192:195], v[122:125]
	v_mfma_f32_16x16x32_bf16 v[110:113], v[154:157], v[200:203], v[110:113]
	v_mfma_f32_16x16x32_bf16 v[106:109], v[168:171], v[200:203], v[106:109]
	v_mfma_f32_16x16x32_bf16 v[94:97], v[154:157], v[208:211], v[94:97]
	v_mfma_f32_16x16x32_bf16 v[90:93], v[168:171], v[208:211], v[90:93]
	v_mfma_f32_16x16x32_bf16 v[78:81], v[154:157], v[218:221], v[78:81]
	v_mfma_f32_16x16x32_bf16 v[74:77], v[168:171], v[218:221], v[74:77]
	v_mfma_f32_16x16x32_bf16 v[126:129], v[164:167], v[196:199], v[126:129]
	v_mfma_f32_16x16x32_bf16 v[122:125], v[188:191], v[196:199], v[122:125]
	v_mfma_f32_16x16x32_bf16 v[110:113], v[164:167], v[204:207], v[110:113]
	v_mfma_f32_16x16x32_bf16 v[106:109], v[188:191], v[204:207], v[106:109]
	v_mfma_f32_16x16x32_bf16 v[94:97], v[164:167], v[212:215], v[94:97]
	v_mfma_f32_16x16x32_bf16 v[90:93], v[188:191], v[212:215], v[90:93]
	v_mfma_f32_16x16x32_bf16 v[78:81], v[164:167], v[222:225], v[78:81]
	v_mfma_f32_16x16x32_bf16 v[74:77], v[188:191], v[222:225], v[74:77]
	s_setprio 0
	s_barrier
	s_mov_b32 m0, s39
	v_add_u32_e32 v144, s43, v159
	v_lshl_add_u64 v[140:141], v[140:141], 0, s[66:67]
	ds_read_b128 v[226:229], v144
	ds_read_b128 v[230:233], v144 offset:1024
	ds_read_b128 v[234:237], v144 offset:2048
	ds_read_b128 v[238:241], v144 offset:3072
	global_load_lds_dwordx4 v[140:141], off
	v_lshl_add_u64 v[140:141], v[242:243], 0, s[66:67]
	s_mov_b32 m0, s40
	s_nop 0
	global_load_lds_dwordx4 v[140:141], off
	s_barrier
	s_waitcnt lgkmcnt(0)
	s_setprio 1
	s_waitcnt lgkmcnt(0)
	v_mfma_f32_16x16x32_bf16 v[118:121], v[226:229], v[192:195], v[118:121]
	v_mfma_f32_16x16x32_bf16 v[114:117], v[234:237], v[192:195], v[114:117]
	v_mfma_f32_16x16x32_bf16 v[102:105], v[226:229], v[200:203], v[102:105]
	v_mfma_f32_16x16x32_bf16 v[98:101], v[234:237], v[200:203], v[98:101]
	v_mfma_f32_16x16x32_bf16 v[86:89], v[226:229], v[208:211], v[86:89]
	v_mfma_f32_16x16x32_bf16 v[82:85], v[234:237], v[208:211], v[82:85]
	v_mfma_f32_16x16x32_bf16 v[70:73], v[226:229], v[218:221], v[70:73]
	v_mfma_f32_16x16x32_bf16 v[66:69], v[234:237], v[218:221], v[66:69]
	v_mfma_f32_16x16x32_bf16 v[118:121], v[230:233], v[196:199], v[118:121]
	v_mfma_f32_16x16x32_bf16 v[114:117], v[238:241], v[196:199], v[114:117]
	v_mfma_f32_16x16x32_bf16 v[102:105], v[230:233], v[204:207], v[102:105]
	v_mfma_f32_16x16x32_bf16 v[98:101], v[238:241], v[204:207], v[98:101]
	v_mfma_f32_16x16x32_bf16 v[86:89], v[230:233], v[212:215], v[86:89]
	v_mfma_f32_16x16x32_bf16 v[82:85], v[238:241], v[212:215], v[82:85]
	v_mfma_f32_16x16x32_bf16 v[70:73], v[230:233], v[222:225], v[70:73]
	v_mfma_f32_16x16x32_bf16 v[66:69], v[238:241], v[222:225], v[66:69]
	s_setprio 0
	s_mov_b32 m0, s41
	v_lshl_add_u64 v[140:141], v[244:245], 0, s[66:67]
	s_barrier
	ds_read_b128 v[192:195], v162 offset:49152
	ds_read_b128 v[196:199], v162 offset:50176
	ds_read_b128 v[200:203], v162 offset:51200
	ds_read_b128 v[204:207], v162 offset:52224
	ds_read_b128 v[208:211], v162 offset:53248
	ds_read_b128 v[212:215], v162 offset:54272
	ds_read_b128 v[218:221], v162 offset:55296
	ds_read_b128 v[222:225], v162 offset:56320
	global_load_lds_dwordx4 v[140:141], off
	v_lshl_add_u64 v[140:141], v[246:247], 0, s[66:67]
	s_mov_b32 m0, s42
	s_nop 0
	global_load_lds_dwordx4 v[140:141], off
	s_barrier
	s_waitcnt lgkmcnt(0)
	s_setprio 1
	s_waitcnt lgkmcnt(0)
	v_mfma_f32_16x16x32_bf16 v[62:65], v[154:157], v[192:195], v[62:65]
	v_mfma_f32_16x16x32_bf16 v[58:61], v[168:171], v[192:195], v[58:61]
	v_mfma_f32_16x16x32_bf16 v[46:49], v[154:157], v[200:203], v[46:49]
	v_mfma_f32_16x16x32_bf16 v[42:45], v[168:171], v[200:203], v[42:45]
	v_mfma_f32_16x16x32_bf16 v[30:33], v[154:157], v[208:211], v[30:33]
	v_mfma_f32_16x16x32_bf16 v[26:29], v[168:171], v[208:211], v[26:29]
	v_mfma_f32_16x16x32_bf16 v[14:17], v[154:157], v[218:221], v[14:17]
	v_mfma_f32_16x16x32_bf16 v[10:13], v[168:171], v[218:221], v[10:13]
	v_mfma_f32_16x16x32_bf16 v[62:65], v[164:167], v[196:199], v[62:65]
	v_mfma_f32_16x16x32_bf16 v[58:61], v[188:191], v[196:199], v[58:61]
	v_mfma_f32_16x16x32_bf16 v[46:49], v[164:167], v[204:207], v[46:49]
	v_mfma_f32_16x16x32_bf16 v[42:45], v[188:191], v[204:207], v[42:45]
	v_mfma_f32_16x16x32_bf16 v[30:33], v[164:167], v[212:215], v[30:33]
	v_mfma_f32_16x16x32_bf16 v[26:29], v[188:191], v[212:215], v[26:29]
	v_mfma_f32_16x16x32_bf16 v[14:17], v[164:167], v[222:225], v[14:17]
	v_mfma_f32_16x16x32_bf16 v[10:13], v[188:191], v[222:225], v[10:13]
	s_setprio 0
	s_barrier
	s_add_u32 s22, s22, 0x40080
	s_addc_u32 s23, s23, 0
	s_mov_b32 m0, s44
	v_lshl_add_u64 v[140:141], s[22:23], 0, v[0:1]
	global_load_lds_dwordx4 v[140:141], off
	v_lshl_add_u64 v[140:141], s[22:23], 0, v[134:135]
	s_mov_b32 m0, s45
	s_nop 0
	global_load_lds_dwordx4 v[140:141], off
	s_waitcnt vmcnt(6)
	s_barrier
	s_setprio 1
	v_mfma_f32_16x16x32_bf16 v[54:57], v[226:229], v[192:195], v[54:57]
	v_mfma_f32_16x16x32_bf16 v[50:53], v[234:237], v[192:195], v[50:53]
	v_mfma_f32_16x16x32_bf16 v[38:41], v[226:229], v[200:203], v[38:41]
	v_mfma_f32_16x16x32_bf16 v[34:37], v[234:237], v[200:203], v[34:37]
	v_mfma_f32_16x16x32_bf16 v[22:25], v[226:229], v[208:211], v[22:25]
	v_mfma_f32_16x16x32_bf16 v[18:21], v[234:237], v[208:211], v[18:21]
	v_mfma_f32_16x16x32_bf16 v[6:9], v[226:229], v[218:221], v[6:9]
	v_mfma_f32_16x16x32_bf16 v[2:5], v[234:237], v[218:221], v[2:5]
	v_mfma_f32_16x16x32_bf16 v[54:57], v[230:233], v[196:199], v[54:57]
	v_mfma_f32_16x16x32_bf16 v[50:53], v[238:241], v[196:199], v[50:53]
	v_mfma_f32_16x16x32_bf16 v[38:41], v[230:233], v[204:207], v[38:41]
	v_mfma_f32_16x16x32_bf16 v[34:37], v[238:241], v[204:207], v[34:37]
	v_mfma_f32_16x16x32_bf16 v[22:25], v[230:233], v[212:215], v[22:25]
	v_mfma_f32_16x16x32_bf16 v[18:21], v[238:241], v[212:215], v[18:21]
	v_mfma_f32_16x16x32_bf16 v[6:9], v[230:233], v[222:225], v[6:9]
	v_mfma_f32_16x16x32_bf16 v[2:5], v[238:241], v[222:225], v[2:5]
	s_setprio 0
	s_add_i32 s65, s65, 2
	s_add_u32 s20, s20, 0x100
	s_addc_u32 s21, s21, 0
	s_add_u32 s63, s63, 0x100
	s_addc_u32 s64, s64, 0
	s_cmp_gt_u32 s65, 13
	s_barrier
	s_cbranch_scc0 .LBB0_784
	v_lshl_add_u32 v140, s8, 8, v153
	v_ashrrev_i32_e32 v141, 31, v140
	v_cndmask_b32_e64 v144, 0, 1, s[2:3]
	v_mov_b32_e32 v158, 1.0
	v_cmp_ne_u32_e64 s[8:9], 1, v144
	s_andn2_b64 vcc, exec, s[2:3]
	v_lshl_add_u64 v[156:157], v[140:141], 3, s[0:1]
	v_mov_b32_e32 v160, 1.0
	s_cbranch_vccnz .LBB0_787
	global_load_dwordx2 v[154:155], v[156:157], off
	global_load_dwordx2 v[192:193], v[156:157], off offset:128
	global_load_dwordx2 v[194:195], v[156:157], off offset:256
	global_load_dwordx2 v[196:197], v[156:157], off offset:384
	global_load_dwordx2 v[198:199], v[156:157], off offset:1024
	global_load_dwordx2 v[200:201], v[156:157], off offset:1152
	global_load_dwordx2 v[202:203], v[156:157], off offset:1280
	global_load_dwordx2 v[204:205], v[156:157], off offset:1408
	s_waitcnt vmcnt(0)
	v_ffbh_u32_e32 v141, v155
	v_min_u32_e32 v141, 32, v141
	v_lshlrev_b64 v[154:155], v141, v[154:155]
	v_min_u32_e32 v144, 1, v154
	v_or_b32_e32 v144, v155, v144
	v_cvt_f32_u32_e32 v144, v144
	v_sub_u32_e32 v141, 32, v141
	v_ldexp_f32 v141, v144, v141
	v_fmamk_f32 v141, v141, 0x2e800000, v143
	v_mul_f32_e32 v144, 0x4b800000, v141
	v_cmp_gt_f32_e32 vcc, s90, v141
	s_nop 1
	v_cndmask_b32_e32 v141, v141, v144, vcc
	v_rsq_f32_e32 v141, v141
	s_nop 0
	v_mul_f32_e32 v144, 0x45800000, v141
	v_cndmask_b32_e32 v160, v141, v144, vcc
.LBB0_787:
	v_lshl_or_b32 v154, s18, 8, v161
	v_mad_i64_i32 v[164:165], s[20:21], v140, s4, 0
	v_ashrrev_i32_e32 v155, 31, v154
	v_lshl_add_u64 v[164:165], v[164:165], 1, s[72:73]
	v_lshl_add_u64 v[164:165], v[154:155], 1, v[164:165]
	v_pk_mul_f32 v[128:129], v[128:129], v[160:161] op_sel_hi:[1,0]
	v_pk_mul_f32 v[126:127], v[126:127], v[160:161] op_sel_hi:[1,0]
	v_pk_mul_f32 v[166:167], v[124:125], v[160:161] op_sel_hi:[1,0]
	v_pk_mul_f32 v[124:125], v[122:123], v[160:161] op_sel_hi:[1,0]
	v_cvt_pk_bf16_f32 v122, v126, v127
	v_cvt_pk_bf16_f32 v123, v128, v129
	s_and_b64 vcc, exec, s[8:9]
	v_cvt_pk_bf16_f32 v124, v124, v125
	v_cvt_pk_bf16_f32 v125, v166, v167
	global_store_dwordx4 v[164:165], v[122:125], off
	v_pk_mul_f32 v[120:121], v[120:121], v[160:161] op_sel_hi:[1,0]
	v_pk_mul_f32 v[118:119], v[118:119], v[160:161] op_sel_hi:[1,0]
	v_pk_mul_f32 v[122:123], v[116:117], v[160:161] op_sel_hi:[1,0]
	v_pk_mul_f32 v[116:117], v[114:115], v[160:161] op_sel_hi:[1,0]
	v_cvt_pk_bf16_f32 v114, v118, v119
	v_cvt_pk_bf16_f32 v115, v120, v121
	s_nop 0
	v_cvt_pk_bf16_f32 v116, v116, v117
	v_cvt_pk_bf16_f32 v117, v122, v123
	global_store_dwordx4 v[164:165], v[114:117], off offset:256
	s_cbranch_vccnz .LBB0_789
	s_nop 1
	v_mov_b64_e32 v[114:115], v[192:193]
	v_ffbh_u32_e32 v116, v115
	v_min_u32_e32 v116, 32, v116
	v_lshlrev_b64 v[114:115], v116, v[114:115]
	v_min_u32_e32 v114, 1, v114
	v_or_b32_e32 v114, v115, v114
	v_cvt_f32_u32_e32 v114, v114
	v_sub_u32_e32 v115, 32, v116
	v_ldexp_f32 v114, v114, v115
	v_fmamk_f32 v114, v114, 0x2e800000, v143
	v_mul_f32_e32 v115, 0x4b800000, v114
	v_cmp_gt_f32_e32 vcc, s90, v114
	s_nop 1
	v_cndmask_b32_e32 v114, v114, v115, vcc
	v_rsq_f32_e32 v114, v114
	s_nop 0
	v_mul_f32_e32 v115, 0x45800000, v114
	v_cndmask_b32_e32 v158, v114, v115, vcc
.LBB0_789:
	s_nop 0
	v_or_b32_e32 v114, 16, v140
	v_mad_i64_i32 v[114:115], s[20:21], v114, s4, 0
	v_lshl_add_u64 v[114:115], v[114:115], 1, s[72:73]
	v_lshl_add_u64 v[114:115], v[154:155], 1, v[114:115]
	v_pk_mul_f32 v[112:113], v[112:113], v[158:159] op_sel_hi:[1,0]
	v_pk_mul_f32 v[110:111], v[110:111], v[158:159] op_sel_hi:[1,0]
	v_pk_mul_f32 v[116:117], v[108:109], v[158:159] op_sel_hi:[1,0]
	v_pk_mul_f32 v[108:109], v[106:107], v[158:159] op_sel_hi:[1,0]
	v_cvt_pk_bf16_f32 v106, v110, v111
	v_cvt_pk_bf16_f32 v107, v112, v113
	v_pk_mul_f32 v[104:105], v[104:105], v[158:159] op_sel_hi:[1,0]
	v_cvt_pk_bf16_f32 v108, v108, v109
	v_cvt_pk_bf16_f32 v109, v116, v117
	global_store_dwordx4 v[114:115], v[106:109], off
	v_pk_mul_f32 v[102:103], v[102:103], v[158:159] op_sel_hi:[1,0]
	s_and_b64 vcc, exec, s[8:9]
	v_pk_mul_f32 v[106:107], v[100:101], v[158:159] op_sel_hi:[1,0]
	v_pk_mul_f32 v[100:101], v[98:99], v[158:159] op_sel_hi:[1,0]
	v_cvt_pk_bf16_f32 v98, v102, v103
	v_cvt_pk_bf16_f32 v99, v104, v105
	s_nop 0
	v_cvt_pk_bf16_f32 v100, v100, v101
	v_cvt_pk_bf16_f32 v101, v106, v107
	global_store_dwordx4 v[114:115], v[98:101], off offset:256
	s_nop 1
	v_mov_b32_e32 v98, 1.0
	v_mov_b32_e32 v100, 1.0
	s_cbranch_vccnz .LBB0_791
	s_nop 1
	v_mov_b64_e32 v[100:101], v[194:195]
	v_ffbh_u32_e32 v99, v101
	v_min_u32_e32 v99, 32, v99
	v_lshlrev_b64 v[100:101], v99, v[100:101]
	v_min_u32_e32 v100, 1, v100
	v_or_b32_e32 v100, v101, v100
	v_cvt_f32_u32_e32 v100, v100
	v_sub_u32_e32 v99, 32, v99
	v_ldexp_f32 v99, v100, v99
	v_fmamk_f32 v99, v99, 0x2e800000, v143
	v_mul_f32_e32 v100, 0x4b800000, v99
	v_cmp_gt_f32_e32 vcc, s90, v99
	s_nop 1
	v_cndmask_b32_e32 v99, v99, v100, vcc
	v_rsq_f32_e32 v99, v99
	s_nop 0
	v_mul_f32_e32 v100, 0x45800000, v99
	v_cndmask_b32_e32 v100, v99, v100, vcc
.LBB0_791:
	v_or_b32_e32 v99, 32, v140
	v_mad_i64_i32 v[102:103], s[20:21], v99, s4, 0
	v_lshl_add_u64 v[102:103], v[102:103], 1, s[72:73]
	v_lshl_add_u64 v[102:103], v[154:155], 1, v[102:103]
	v_pk_mul_f32 v[96:97], v[96:97], v[100:101] op_sel_hi:[1,0]
	v_pk_mul_f32 v[94:95], v[94:95], v[100:101] op_sel_hi:[1,0]
	v_pk_mul_f32 v[104:105], v[92:93], v[100:101] op_sel_hi:[1,0]
	v_pk_mul_f32 v[92:93], v[90:91], v[100:101] op_sel_hi:[1,0]
	v_cvt_pk_bf16_f32 v90, v94, v95
	v_cvt_pk_bf16_f32 v91, v96, v97
	s_and_b64 vcc, exec, s[8:9]
	v_cvt_pk_bf16_f32 v92, v92, v93
	v_cvt_pk_bf16_f32 v93, v104, v105
	global_store_dwordx4 v[102:103], v[90:93], off
	v_pk_mul_f32 v[88:89], v[88:89], v[100:101] op_sel_hi:[1,0]
	v_pk_mul_f32 v[86:87], v[86:87], v[100:101] op_sel_hi:[1,0]
	v_pk_mul_f32 v[90:91], v[84:85], v[100:101] op_sel_hi:[1,0]
	v_pk_mul_f32 v[84:85], v[82:83], v[100:101] op_sel_hi:[1,0]
	v_cvt_pk_bf16_f32 v82, v86, v87
	v_cvt_pk_bf16_f32 v83, v88, v89
	s_nop 0
	v_cvt_pk_bf16_f32 v84, v84, v85
	v_cvt_pk_bf16_f32 v85, v90, v91
	global_store_dwordx4 v[102:103], v[82:85], off offset:256
	s_cbranch_vccnz .LBB0_793
	s_nop 1
	v_mov_b64_e32 v[82:83], v[196:197]
	v_ffbh_u32_e32 v84, v83
	v_min_u32_e32 v84, 32, v84
	v_lshlrev_b64 v[82:83], v84, v[82:83]
	v_min_u32_e32 v82, 1, v82
	v_or_b32_e32 v82, v83, v82
	v_cvt_f32_u32_e32 v82, v82
	v_sub_u32_e32 v83, 32, v84
	v_ldexp_f32 v82, v82, v83
	v_fmamk_f32 v82, v82, 0x2e800000, v143
	v_mul_f32_e32 v83, 0x4b800000, v82
	v_cmp_gt_f32_e32 vcc, s90, v82
	s_nop 1
	v_cndmask_b32_e32 v82, v82, v83, vcc
	v_rsq_f32_e32 v82, v82
	s_nop 0
	v_mul_f32_e32 v83, 0x45800000, v82
	v_cndmask_b32_e32 v98, v82, v83, vcc
.LBB0_793:
	s_nop 0
	v_or_b32_e32 v82, 48, v140
	v_mad_i64_i32 v[82:83], s[20:21], v82, s4, 0
	v_lshl_add_u64 v[82:83], v[82:83], 1, s[72:73]
	v_lshl_add_u64 v[82:83], v[154:155], 1, v[82:83]
	v_pk_mul_f32 v[80:81], v[80:81], v[98:99] op_sel_hi:[1,0]
	v_pk_mul_f32 v[78:79], v[78:79], v[98:99] op_sel_hi:[1,0]
	v_pk_mul_f32 v[84:85], v[76:77], v[98:99] op_sel_hi:[1,0]
	v_pk_mul_f32 v[76:77], v[74:75], v[98:99] op_sel_hi:[1,0]
	v_cvt_pk_bf16_f32 v74, v78, v79
	v_cvt_pk_bf16_f32 v75, v80, v81
	v_pk_mul_f32 v[72:73], v[72:73], v[98:99] op_sel_hi:[1,0]
	v_cvt_pk_bf16_f32 v76, v76, v77
	v_cvt_pk_bf16_f32 v77, v84, v85
	global_store_dwordx4 v[82:83], v[74:77], off
	v_pk_mul_f32 v[70:71], v[70:71], v[98:99] op_sel_hi:[1,0]
	s_and_b64 vcc, exec, s[8:9]
	v_pk_mul_f32 v[74:75], v[68:69], v[98:99] op_sel_hi:[1,0]
	v_pk_mul_f32 v[68:69], v[66:67], v[98:99] op_sel_hi:[1,0]
	v_cvt_pk_bf16_f32 v66, v70, v71
	v_cvt_pk_bf16_f32 v67, v72, v73
	s_nop 0
	v_cvt_pk_bf16_f32 v68, v68, v69
	v_cvt_pk_bf16_f32 v69, v74, v75
	global_store_dwordx4 v[82:83], v[66:69], off offset:256
	s_nop 1
	v_mov_b32_e32 v66, 1.0
	v_mov_b32_e32 v68, 1.0
	s_cbranch_vccnz .LBB0_795
	s_nop 1
	v_mov_b64_e32 v[68:69], v[198:199]
	v_ffbh_u32_e32 v67, v69
	v_min_u32_e32 v67, 32, v67
	v_lshlrev_b64 v[68:69], v67, v[68:69]
	v_min_u32_e32 v68, 1, v68
	v_or_b32_e32 v68, v69, v68
	v_cvt_f32_u32_e32 v68, v68
	v_sub_u32_e32 v67, 32, v67
	v_ldexp_f32 v67, v68, v67
	v_fmamk_f32 v67, v67, 0x2e800000, v143
	v_mul_f32_e32 v68, 0x4b800000, v67
	v_cmp_gt_f32_e32 vcc, s90, v67
	s_nop 1
	v_cndmask_b32_e32 v67, v67, v68, vcc
	v_rsq_f32_e32 v67, v67
	s_nop 0
	v_mul_f32_e32 v68, 0x45800000, v67
	v_cndmask_b32_e32 v68, v67, v68, vcc
.LBB0_795:
	v_add_u32_e32 v67, 0x80, v140
	v_mad_i64_i32 v[70:71], s[20:21], v67, s4, 0
	v_lshl_add_u64 v[70:71], v[70:71], 1, s[72:73]
	v_lshl_add_u64 v[70:71], v[154:155], 1, v[70:71]
	v_pk_mul_f32 v[64:65], v[64:65], v[68:69] op_sel_hi:[1,0]
	v_pk_mul_f32 v[62:63], v[62:63], v[68:69] op_sel_hi:[1,0]
	v_pk_mul_f32 v[72:73], v[60:61], v[68:69] op_sel_hi:[1,0]
	v_pk_mul_f32 v[60:61], v[58:59], v[68:69] op_sel_hi:[1,0]
	v_cvt_pk_bf16_f32 v58, v62, v63
	v_cvt_pk_bf16_f32 v59, v64, v65
	s_and_b64 vcc, exec, s[8:9]
	v_cvt_pk_bf16_f32 v60, v60, v61
	v_cvt_pk_bf16_f32 v61, v72, v73
	global_store_dwordx4 v[70:71], v[58:61], off
	v_pk_mul_f32 v[56:57], v[56:57], v[68:69] op_sel_hi:[1,0]
	v_pk_mul_f32 v[54:55], v[54:55], v[68:69] op_sel_hi:[1,0]
	v_pk_mul_f32 v[58:59], v[52:53], v[68:69] op_sel_hi:[1,0]
	v_pk_mul_f32 v[52:53], v[50:51], v[68:69] op_sel_hi:[1,0]
	v_cvt_pk_bf16_f32 v50, v54, v55
	v_cvt_pk_bf16_f32 v51, v56, v57
	s_nop 0
	v_cvt_pk_bf16_f32 v52, v52, v53
	v_cvt_pk_bf16_f32 v53, v58, v59
	global_store_dwordx4 v[70:71], v[50:53], off offset:256
	s_cbranch_vccnz .LBB0_797
	s_nop 1
	v_mov_b64_e32 v[50:51], v[200:201]
	v_ffbh_u32_e32 v52, v51
	v_min_u32_e32 v52, 32, v52
	v_lshlrev_b64 v[50:51], v52, v[50:51]
	v_min_u32_e32 v50, 1, v50
	v_or_b32_e32 v50, v51, v50
	v_cvt_f32_u32_e32 v50, v50
	v_sub_u32_e32 v51, 32, v52
	v_ldexp_f32 v50, v50, v51
	v_fmamk_f32 v50, v50, 0x2e800000, v143
	v_mul_f32_e32 v51, 0x4b800000, v50
	v_cmp_gt_f32_e32 vcc, s90, v50
	s_nop 1
	v_cndmask_b32_e32 v50, v50, v51, vcc
	v_rsq_f32_e32 v50, v50
	s_nop 0
	v_mul_f32_e32 v51, 0x45800000, v50
	v_cndmask_b32_e32 v66, v50, v51, vcc
.LBB0_797:
	s_nop 0
	v_add_u32_e32 v50, 0x90, v140
	v_mad_i64_i32 v[50:51], s[20:21], v50, s4, 0
	v_lshl_add_u64 v[50:51], v[50:51], 1, s[72:73]
	v_lshl_add_u64 v[50:51], v[154:155], 1, v[50:51]
	v_pk_mul_f32 v[48:49], v[48:49], v[66:67] op_sel_hi:[1,0]
	v_pk_mul_f32 v[46:47], v[46:47], v[66:67] op_sel_hi:[1,0]
	v_pk_mul_f32 v[52:53], v[44:45], v[66:67] op_sel_hi:[1,0]
	v_pk_mul_f32 v[44:45], v[42:43], v[66:67] op_sel_hi:[1,0]
	v_cvt_pk_bf16_f32 v42, v46, v47
	v_cvt_pk_bf16_f32 v43, v48, v49
	v_pk_mul_f32 v[40:41], v[40:41], v[66:67] op_sel_hi:[1,0]
	v_cvt_pk_bf16_f32 v44, v44, v45
	v_cvt_pk_bf16_f32 v45, v52, v53
	global_store_dwordx4 v[50:51], v[42:45], off
	v_pk_mul_f32 v[38:39], v[38:39], v[66:67] op_sel_hi:[1,0]
	s_and_b64 vcc, exec, s[8:9]
	v_pk_mul_f32 v[42:43], v[36:37], v[66:67] op_sel_hi:[1,0]
	v_pk_mul_f32 v[36:37], v[34:35], v[66:67] op_sel_hi:[1,0]
	v_cvt_pk_bf16_f32 v34, v38, v39
	v_cvt_pk_bf16_f32 v35, v40, v41
	s_nop 0
	v_cvt_pk_bf16_f32 v36, v36, v37
	v_cvt_pk_bf16_f32 v37, v42, v43
	global_store_dwordx4 v[50:51], v[34:37], off offset:256
	s_nop 1
	v_mov_b32_e32 v34, 1.0
	v_mov_b32_e32 v36, 1.0
	s_cbranch_vccnz .LBB0_799
	s_nop 1
	v_mov_b64_e32 v[36:37], v[202:203]
	v_ffbh_u32_e32 v35, v37
	v_min_u32_e32 v35, 32, v35
	v_lshlrev_b64 v[36:37], v35, v[36:37]
	v_min_u32_e32 v36, 1, v36
	v_or_b32_e32 v36, v37, v36
	v_cvt_f32_u32_e32 v36, v36
	v_sub_u32_e32 v35, 32, v35
	v_ldexp_f32 v35, v36, v35
	v_fmamk_f32 v35, v35, 0x2e800000, v143
	v_mul_f32_e32 v36, 0x4b800000, v35
	v_cmp_gt_f32_e32 vcc, s90, v35
	s_nop 1
	v_cndmask_b32_e32 v35, v35, v36, vcc
	v_rsq_f32_e32 v35, v35
	s_nop 0
	v_mul_f32_e32 v36, 0x45800000, v35
	v_cndmask_b32_e32 v36, v35, v36, vcc
.LBB0_799:
	v_add_u32_e32 v35, 0xa0, v140
	v_mad_i64_i32 v[38:39], s[20:21], v35, s4, 0
	v_lshl_add_u64 v[38:39], v[38:39], 1, s[72:73]
	v_lshl_add_u64 v[38:39], v[154:155], 1, v[38:39]
	v_pk_mul_f32 v[32:33], v[32:33], v[36:37] op_sel_hi:[1,0]
	v_pk_mul_f32 v[30:31], v[30:31], v[36:37] op_sel_hi:[1,0]
	v_pk_mul_f32 v[40:41], v[28:29], v[36:37] op_sel_hi:[1,0]
	v_pk_mul_f32 v[28:29], v[26:27], v[36:37] op_sel_hi:[1,0]
	v_cvt_pk_bf16_f32 v26, v30, v31
	v_cvt_pk_bf16_f32 v27, v32, v33
	s_and_b64 vcc, exec, s[8:9]
	v_cvt_pk_bf16_f32 v28, v28, v29
	v_cvt_pk_bf16_f32 v29, v40, v41
	global_store_dwordx4 v[38:39], v[26:29], off
	v_pk_mul_f32 v[24:25], v[24:25], v[36:37] op_sel_hi:[1,0]
	v_pk_mul_f32 v[22:23], v[22:23], v[36:37] op_sel_hi:[1,0]
	v_pk_mul_f32 v[26:27], v[20:21], v[36:37] op_sel_hi:[1,0]
	v_pk_mul_f32 v[20:21], v[18:19], v[36:37] op_sel_hi:[1,0]
	v_cvt_pk_bf16_f32 v18, v22, v23
	v_cvt_pk_bf16_f32 v19, v24, v25
	s_nop 0
	v_cvt_pk_bf16_f32 v20, v20, v21
	v_cvt_pk_bf16_f32 v21, v26, v27
	global_store_dwordx4 v[38:39], v[18:21], off offset:256
	s_cbranch_vccnz .LBB0_776
	s_nop 1
	v_mov_b64_e32 v[18:19], v[204:205]
	v_ffbh_u32_e32 v20, v19
	v_min_u32_e32 v20, 32, v20
	v_lshlrev_b64 v[18:19], v20, v[18:19]
	v_min_u32_e32 v18, 1, v18
	v_or_b32_e32 v18, v19, v18
	v_cvt_f32_u32_e32 v18, v18
	v_sub_u32_e32 v19, 32, v20
	v_ldexp_f32 v18, v18, v19
	v_fmamk_f32 v18, v18, 0x2e800000, v143
	v_mul_f32_e32 v19, 0x4b800000, v18
	v_cmp_gt_f32_e32 vcc, s90, v18
	s_nop 1
	v_cndmask_b32_e32 v18, v18, v19, vcc
	v_rsq_f32_e32 v18, v18
	s_nop 0
	v_mul_f32_e32 v19, 0x45800000, v18
	v_cndmask_b32_e32 v34, v18, v19, vcc
	s_branch .LBB0_776
